# chainzz2 + E2 with k=8 early MFMAs before BAR1 (fp8 k=4)
# baseline (speedup 1.0000x reference)
; #define PG8_STAGE(bufoff, gbase, voff) do { _Pragma("unroll") for (int _i = 0; _i < 2; ++_i) \
;         __builtin_amdgcn_global_load_lds((const unsigned*)((const char*)(gbase) + (voff)[_i]), (LAS unsigned*)(lds + (bufoff) + ldsw + _i * 8192), 16, 0, 0); } while (0)
; #define PG8_LDA(dst, b, h) do { _Pragma("unroll") for (int m = 0; m < 4; ++m) _Pragma("unroll") for (int k = 0; k < 2; ++k) dst[m][k] = *(const LAS bf16x8*)(lds + PG8_SA(b, h) + aoffk[k] + m * 2048); } while (0)
; #define PG8_BAR __builtin_amdgcn_s_barrier()
; template <class Epi, class Sched, class GemmT>
; __device__ __forceinline__ void gemm_phase(LAS unsigned char* lds, const GemmT& g, const Sched& S, const Epi& E, const int wid) {
;     ...
;             for (int t = 0; t < nt; t += 2) {
;                 const bool last = (t == nt - 2);
;                 const char* a1 = cA + (size_t)(t + 1) * kstep;
;                 const char* a2 = last ? ns.A : cA + (size_t)(t + 2) * kstep; const char* b2 = last ? ns.B : cB + (size_t)(t + 2) * kstep;
;                 const char* a3 = a2 + kstep; const char* b3 = b2 + kstep;
;                 unsigned vA2[2], vB2[2];
; #pragma unroll
;                 for (int i = 0; i < 2; ++i) { vA2[i] = last ? nvA[i] : voffA[i]; vB2[i] = last ? nvB[i] : voffB[i]; }
;                 const size_t hA2 = last ? nhA : hstepA, hB2 = last ? nhB : hstepB;
;                 PG8_LDB(B0, 0, 0); PG8_LDB(B1, 0, 1); PG8_SCHED; PG8_LDA(At, 0, 0); PG8_STAGE(PG8_SA(1, 1), a1 + hstepA, voffA);
;                 PG8_WAIT_V(8); PG8_WAIT_L(0); PG8_BAR; PG8_MMA(0, 0, At, B0); PG8_MMA(0, 1, At, B1); PG8_BAR; PG8_SCHED;
;                 PG8_LDA(At, 0, 1); PG8_STAGE(PG8_SB(0, 0), b2, vB2); PG8_STAGE(PG8_SB(0, 1), b2 + hB2, vB2); PG8_STAGE(PG8_SA(0, 0), a2, vA2);
;                 PG8_WAIT_V(8); PG8_WAIT_L(0); PG8_BAR; PG8_MMA(1, 0, At, B0); PG8_MMA(1, 1, At, B1); PG8_BAR; PG8_SCHED;
;                 PG8_LDB(B0, 1, 0); PG8_LDB(B1, 1, 1); PG8_SCHED; PG8_LDA(At, 1, 0); PG8_STAGE(PG8_SA(0, 1), a2 + hA2, vA2);
;                 PG8_WAIT_V(8); PG8_WAIT_L(0); PG8_BAR; PG8_MMA(0, 0, At, B0); PG8_MMA(0, 1, At, B1); PG8_BAR; PG8_SCHED;
;                 PG8_LDA(At, 1, 1); PG8_STAGE(PG8_SB(1, 0), b3, vB2); PG8_STAGE(PG8_SB(1, 1), b3 + hB2, vB2); PG8_STAGE(PG8_SA(1, 0), a3, vA2);
;                 PG8_WAIT_V(8); PG8_WAIT_L(0); PG8_BAR; PG8_MMA(1, 0, At, B0); PG8_MMA(1, 1, At, B1); PG8_BAR; PG8_SCHED;
.LBB0_361:
	ds_read_b128 v[24:27], v186
	ds_read_b128 v[28:31], v187
	ds_read_b128 v[16:19], v188
	ds_read_b128 v[20:23], v189
	ds_read_b128 v[8:11], v190
	ds_read_b128 v[12:15], v191
	ds_read_b128 v[0:3], v192
	ds_read_b128 v[4:7], v193
	s_add_u32 s41, s56, 0xfff80080
	s_addc_u32 s48, s57, -1
	s_cmp_eq_u32 s40, 28
	s_cselect_b32 s83, s43, s48
	s_cselect_b32 s82, s42, s41
	s_cselect_b32 s59, s37, s39
	s_cselect_b32 s58, s36, s38
	v_lshl_add_u64 v[230:231], s[56:57], 0, v[160:161]
	s_add_i32 m0, s12, 0xc000
	ds_read_b128 v[174:177], v194
	ds_read_b128 v[204:207], v194 offset:2048
	ds_read_b128 v[178:181], v195
	ds_read_b128 v[208:211], v195 offset:2048
	ds_read_b128 v[212:215], v194 offset:4096
	ds_read_b128 v[220:223], v194 offset:6144
	ds_read_b128 v[216:219], v195 offset:4096
	ds_read_b128 v[224:227], v195 offset:6144
	global_load_lds_dwordx4 v[230:231], off
	v_lshl_add_u64 v[230:231], s[56:57], 0, v[164:165]
	s_add_i32 m0, s12, 0xe000
	s_nop 0
	global_load_lds_dwordx4 v[230:231], off
	s_waitcnt vmcnt(8)
	s_waitcnt lgkmcnt(0)
	s_waitcnt lgkmcnt(0)
	v_mfma_scale_f32_16x16x128_f8f6f4 v[156:159], v[24:31], v[174:181], v[156:159], v196, v196 op_sel_hi:[0,0,0]
	v_mfma_scale_f32_16x16x128_f8f6f4 v[152:155], v[16:23], v[174:181], v[152:155], v196, v196 op_sel_hi:[0,0,0]
	v_mfma_scale_f32_16x16x128_f8f6f4 v[136:139], v[16:23], v[204:211], v[136:139], v196, v196 op_sel_hi:[0,0,0]
	v_mfma_scale_f32_16x16x128_f8f6f4 v[140:143], v[24:31], v[204:211], v[140:143], v196, v196 op_sel_hi:[0,0,0]
	s_barrier
	s_setprio 3
	v_mfma_scale_f32_16x16x128_f8f6f4 v[124:127], v[24:31], v[212:219], v[124:127], v196, v196 op_sel_hi:[0,0,0]
	v_mfma_scale_f32_16x16x128_f8f6f4 v[120:123], v[16:23], v[212:219], v[120:123], v196, v196 op_sel_hi:[0,0,0]
	v_mfma_scale_f32_16x16x128_f8f6f4 v[104:107], v[16:23], v[220:227], v[104:107], v196, v196 op_sel_hi:[0,0,0]
	v_mfma_scale_f32_16x16x128_f8f6f4 v[108:111], v[24:31], v[220:227], v[108:111], v196, v196 op_sel_hi:[0,0,0]
	s_setprio 0
	s_setprio 3
	v_mfma_scale_f32_16x16x128_f8f6f4 v[148:151], v[8:15], v[174:181], v[148:151], v196, v196 op_sel_hi:[0,0,0]
	v_mfma_scale_f32_16x16x128_f8f6f4 v[144:147], v[0:7], v[174:181], v[144:147], v196, v196 op_sel_hi:[0,0,0]
	v_mfma_scale_f32_16x16x128_f8f6f4 v[128:131], v[0:7], v[204:211], v[128:131], v196, v196 op_sel_hi:[0,0,0]
	v_mfma_scale_f32_16x16x128_f8f6f4 v[132:135], v[8:15], v[204:211], v[132:135], v196, v196 op_sel_hi:[0,0,0]
	v_mfma_scale_f32_16x16x128_f8f6f4 v[116:119], v[8:15], v[212:219], v[116:119], v196, v196 op_sel_hi:[0,0,0]
	v_mfma_scale_f32_16x16x128_f8f6f4 v[112:115], v[0:7], v[212:219], v[112:115], v196, v196 op_sel_hi:[0,0,0]
	v_mfma_scale_f32_16x16x128_f8f6f4 v[96:99], v[0:7], v[220:227], v[96:99], v196, v196 op_sel_hi:[0,0,0]
	v_mfma_scale_f32_16x16x128_f8f6f4 v[100:103], v[8:15], v[220:227], v[100:103], v196, v196 op_sel_hi:[0,0,0]
	s_setprio 0
	s_barrier
	s_add_i32 s41, s64, s68
	v_lshl_add_u64 v[174:175], s[58:59], 0, v[162:163]
	s_mov_b32 m0, s41
	ds_read_b128 v[204:207], v194 offset:16384
	ds_read_b128 v[212:215], v194 offset:18432
	ds_read_b128 v[208:211], v195 offset:16384
	ds_read_b128 v[216:219], v195 offset:18432
	ds_read_b128 v[220:223], v194 offset:20480
	ds_read_b128 v[230:233], v194 offset:22528
	ds_read_b128 v[224:227], v195 offset:20480
	ds_read_b128 v[234:237], v195 offset:22528
	global_load_lds_dwordx4 v[174:175], off
	s_add_i32 m0, s41, 0x2000
	s_add_u32 s50, s58, 0x80000
	v_lshl_add_u64 v[176:177], s[58:59], 0, v[166:167]
	s_addc_u32 s51, s59, 0
	s_add_i32 s41, s65, s68
	global_load_lds_dwordx4 v[176:177], off
	v_lshl_add_u64 v[178:179], s[50:51], 0, v[162:163]
	s_mov_b32 m0, s41
	v_lshl_add_u64 v[180:181], s[82:83], 0, v[164:165]
	global_load_lds_dwordx4 v[178:179], off
	v_lshl_add_u64 v[178:179], s[50:51], 0, v[166:167]
	s_add_i32 m0, s41, 0x2000
	s_nop 0
	global_load_lds_dwordx4 v[178:179], off
	v_lshl_add_u64 v[178:179], s[82:83], 0, v[160:161]
	s_mov_b32 m0, s12
	s_nop 0
	global_load_lds_dwordx4 v[178:179], off
	s_mov_b32 m0, s13
	s_nop 0
	global_load_lds_dwordx4 v[180:181], off
	s_waitcnt vmcnt(8)
	s_waitcnt lgkmcnt(0)
	s_waitcnt lgkmcnt(0)
	v_mfma_scale_f32_16x16x128_f8f6f4 v[84:87], v[24:31], v[204:211], v[84:87], v196, v196 op_sel_hi:[0,0,0]
	v_mfma_scale_f32_16x16x128_f8f6f4 v[80:83], v[16:23], v[204:211], v[80:83], v196, v196 op_sel_hi:[0,0,0]
	v_mfma_scale_f32_16x16x128_f8f6f4 v[64:67], v[16:23], v[212:219], v[64:67], v196, v196 op_sel_hi:[0,0,0]
	v_mfma_scale_f32_16x16x128_f8f6f4 v[68:71], v[24:31], v[212:219], v[68:71], v196, v196 op_sel_hi:[0,0,0]
	s_barrier
	s_setprio 3
	v_mfma_scale_f32_16x16x128_f8f6f4 v[52:55], v[24:31], v[220:227], v[52:55], v196, v196 op_sel_hi:[0,0,0]
	v_mfma_scale_f32_16x16x128_f8f6f4 v[48:51], v[16:23], v[220:227], v[48:51], v196, v196 op_sel_hi:[0,0,0]
	v_mfma_scale_f32_16x16x128_f8f6f4 v[32:35], v[16:23], v[230:237], v[32:35], v196, v196 op_sel_hi:[0,0,0]
	v_mfma_scale_f32_16x16x128_f8f6f4 v[36:39], v[24:31], v[230:237], v[36:39], v196, v196 op_sel_hi:[0,0,0]
	s_setprio 0
	s_setprio 3
	v_mfma_scale_f32_16x16x128_f8f6f4 v[92:95], v[8:15], v[204:211], v[92:95], v196, v196 op_sel_hi:[0,0,0]
	v_mfma_scale_f32_16x16x128_f8f6f4 v[88:91], v[0:7], v[204:211], v[88:91], v196, v196 op_sel_hi:[0,0,0]
	v_mfma_scale_f32_16x16x128_f8f6f4 v[72:75], v[0:7], v[212:219], v[72:75], v196, v196 op_sel_hi:[0,0,0]
	v_mfma_scale_f32_16x16x128_f8f6f4 v[76:79], v[8:15], v[212:219], v[76:79], v196, v196 op_sel_hi:[0,0,0]
	v_mfma_scale_f32_16x16x128_f8f6f4 v[60:63], v[8:15], v[220:227], v[60:63], v196, v196 op_sel_hi:[0,0,0]
	v_mfma_scale_f32_16x16x128_f8f6f4 v[56:59], v[0:7], v[220:227], v[56:59], v196, v196 op_sel_hi:[0,0,0]
	v_mfma_scale_f32_16x16x128_f8f6f4 v[40:43], v[0:7], v[230:237], v[40:43], v196, v196 op_sel_hi:[0,0,0]
	v_mfma_scale_f32_16x16x128_f8f6f4 v[44:47], v[8:15], v[230:237], v[44:47], v196, v196 op_sel_hi:[0,0,0]
	s_setprio 0
	s_barrier
; #define PG8_STAGE(bufoff, gbase, voff) do { _Pragma("unroll") for (int _i = 0; _i < 2; ++_i) \
;         __builtin_amdgcn_global_load_lds((const unsigned*)((const char*)(gbase) + (voff)[_i]), (LAS unsigned*)(lds + (bufoff) + ldsw + _i * 8192), 16, 0, 0); } while (0)
; #define PG8_LDA(dst, b, h) do { _Pragma("unroll") for (int m = 0; m < 4; ++m) _Pragma("unroll") for (int k = 0; k < 2; ++k) dst[m][k] = *(const LAS bf16x8*)(lds + PG8_SA(b, h) + aoffk[k] + m * 2048); } while (0)
; #define PG8_LDB(dst, b, h) do { _Pragma("unroll") for (int n = 0; n < 2; ++n) _Pragma("unroll") for (int k = 0; k < 2; ++k) dst[n][k] = *(const LAS bf16x8*)(lds + PG8_SB(b, h) + boffk[k] + n * 2048); } while (0)
; #define PG8_WAIT_V(n) asm volatile("s_waitcnt vmcnt(" #n ")" ::: "memory")
; #define PG8_WAIT_L(n) asm volatile("s_waitcnt lgkmcnt(" #n ")" ::: "memory")
; #define PG8_BAR __builtin_amdgcn_s_barrier()
; #define PG8_SCHED __builtin_amdgcn_sched_barrier(0)
; template <class Epi, class Sched, class GemmT>
; __device__ __forceinline__ void gemm_phase(LAS unsigned char* lds, const GemmT& g, const Sched& S, const Epi& E, const int wid) {
;     ...
;                 PG8_LDB(B0, 1, 0); PG8_LDB(B1, 1, 1); PG8_SCHED; PG8_LDA(At, 1, 0); PG8_STAGE(PG8_SA(0, 1), a2 + hA2, vA2);
;                 PG8_WAIT_V(8); PG8_WAIT_L(0); PG8_BAR; PG8_MMA(0, 0, At, B0); PG8_MMA(0, 1, At, B1); PG8_BAR; PG8_SCHED;
;                 PG8_LDA(At, 1, 1); PG8_STAGE(PG8_SB(1, 0), b3, vB2); PG8_STAGE(PG8_SB(1, 1), b3 + hB2, vB2); PG8_STAGE(PG8_SA(1, 0), a3, vA2);
;                 PG8_WAIT_V(8); PG8_WAIT_L(0); PG8_BAR; PG8_MMA(1, 0, At, B0); PG8_MMA(1, 1, At, B1); PG8_BAR; PG8_SCHED;
;             }
;             if constexpr (NSEG > 1) { if (sgi + 1 < NSEG) E.mid(acc, cur, sgi, wr, wc, fr, fq); }
;             cs = ns; cA = ns.A; cB = ns.B; hstepA = nhA; hstepB = nhB;
; #pragma unroll
;             for (int i = 0; i < 2; ++i) { voffA[i] = nvA[i]; voffB[i] = nvB[i]; }
;         }
;         if (wr == 0) PG8_BAR;
	s_add_i32 s41, 0, 0x18000
	s_add_i32 s48, 0, 0x1c000
	v_add_u32_e32 v0, s41, v184
	v_add_u32_e32 v4, s41, v185
	v_add_u32_e32 v16, s48, v184
	v_add_u32_e32 v20, s48, v185
	ds_read_b128 v[0:3], v0
	ds_read_b128 v[4:7], v4
	ds_read_b128 v[8:11], v197
	ds_read_b128 v[12:15], v198
	ds_read_b128 v[16:19], v16
	ds_read_b128 v[20:23], v20
	ds_read_b128 v[24:27], v199
	ds_read_b128 v[28:31], v200
	s_add_u32 s50, s82, 0x80000
	s_addc_u32 s51, s83, 0
	s_mov_b32 m0, s15
	v_lshl_add_u64 v[238:239], s[50:51], 0, v[160:161]
	ds_read_b128 v[204:207], v194 offset:32768
	ds_read_b128 v[212:215], v194 offset:34816
	ds_read_b128 v[208:211], v195 offset:32768
	ds_read_b128 v[216:219], v195 offset:34816
	ds_read_b128 v[220:223], v194 offset:36864
	ds_read_b128 v[230:233], v194 offset:38912
	ds_read_b128 v[224:227], v195 offset:36864
	ds_read_b128 v[234:237], v195 offset:38912
	global_load_lds_dwordx4 v[238:239], off
	v_lshl_add_u64 v[238:239], s[50:51], 0, v[164:165]
	s_mov_b32 m0, s21
	s_nop 0
	global_load_lds_dwordx4 v[238:239], off
	s_waitcnt vmcnt(8)
	s_waitcnt lgkmcnt(0)
	s_waitcnt lgkmcnt(0)
	v_mfma_scale_f32_16x16x128_f8f6f4 v[156:159], v[0:7], v[204:211], v[156:159], v196, v196 op_sel_hi:[0,0,0]
	v_mfma_scale_f32_16x16x128_f8f6f4 v[152:155], v[8:15], v[204:211], v[152:155], v196, v196 op_sel_hi:[0,0,0]
	v_mfma_scale_f32_16x16x128_f8f6f4 v[136:139], v[8:15], v[212:219], v[136:139], v196, v196 op_sel_hi:[0,0,0]
	v_mfma_scale_f32_16x16x128_f8f6f4 v[140:143], v[0:7], v[212:219], v[140:143], v196, v196 op_sel_hi:[0,0,0]
	s_barrier
	s_setprio 3
	v_mfma_scale_f32_16x16x128_f8f6f4 v[124:127], v[0:7], v[220:227], v[124:127], v196, v196 op_sel_hi:[0,0,0]
	v_mfma_scale_f32_16x16x128_f8f6f4 v[120:123], v[8:15], v[220:227], v[120:123], v196, v196 op_sel_hi:[0,0,0]
	v_mfma_scale_f32_16x16x128_f8f6f4 v[104:107], v[8:15], v[230:237], v[104:107], v196, v196 op_sel_hi:[0,0,0]
	v_mfma_scale_f32_16x16x128_f8f6f4 v[108:111], v[0:7], v[230:237], v[108:111], v196, v196 op_sel_hi:[0,0,0]
	s_setprio 0
	s_setprio 3
	v_mfma_scale_f32_16x16x128_f8f6f4 v[148:151], v[16:23], v[204:211], v[148:151], v196, v196 op_sel_hi:[0,0,0]
	v_mfma_scale_f32_16x16x128_f8f6f4 v[144:147], v[24:31], v[204:211], v[144:147], v196, v196 op_sel_hi:[0,0,0]
	v_mfma_scale_f32_16x16x128_f8f6f4 v[128:131], v[24:31], v[212:219], v[128:131], v196, v196 op_sel_hi:[0,0,0]
	v_mfma_scale_f32_16x16x128_f8f6f4 v[132:135], v[16:23], v[212:219], v[132:135], v196, v196 op_sel_hi:[0,0,0]
	v_mfma_scale_f32_16x16x128_f8f6f4 v[116:119], v[16:23], v[220:227], v[116:119], v196, v196 op_sel_hi:[0,0,0]
	v_mfma_scale_f32_16x16x128_f8f6f4 v[112:115], v[24:31], v[220:227], v[112:115], v196, v196 op_sel_hi:[0,0,0]
	v_mfma_scale_f32_16x16x128_f8f6f4 v[96:99], v[24:31], v[230:237], v[96:99], v196, v196 op_sel_hi:[0,0,0]
	v_mfma_scale_f32_16x16x128_f8f6f4 v[100:103], v[16:23], v[230:237], v[100:103], v196, v196 op_sel_hi:[0,0,0]
	s_setprio 0
	s_barrier
	s_add_i32 s41, s41, s68
	v_lshl_add_u64 v[174:175], v[174:175], 0, s[10:11]
	s_mov_b32 m0, s41
	ds_read_b128 v[204:207], v194 offset:49152
	ds_read_b128 v[212:215], v194 offset:51200
	ds_read_b128 v[208:211], v195 offset:49152
	ds_read_b128 v[216:219], v195 offset:51200
	ds_read_b128 v[220:223], v194 offset:53248
	ds_read_b128 v[230:233], v194 offset:55296
	ds_read_b128 v[224:227], v195 offset:53248
	ds_read_b128 v[234:237], v195 offset:55296
	global_load_lds_dwordx4 v[174:175], off
	s_add_i32 m0, s41, 0x2000
	s_add_u32 s50, s58, 0x80080
	v_lshl_add_u64 v[174:175], v[176:177], 0, s[10:11]
	s_addc_u32 s51, s59, 0
	s_add_i32 s41, s48, s68
	global_load_lds_dwordx4 v[174:175], off
	v_lshl_add_u64 v[174:175], s[50:51], 0, v[162:163]
	s_mov_b32 m0, s41
	s_nop 0
	global_load_lds_dwordx4 v[174:175], off
	v_lshl_add_u64 v[174:175], s[50:51], 0, v[166:167]
	s_add_i32 m0, s41, 0x2000
	s_nop 0
	global_load_lds_dwordx4 v[174:175], off
	v_lshl_add_u64 v[174:175], v[178:179], 0, s[10:11]
	s_mov_b32 m0, s35
	s_nop 0
	global_load_lds_dwordx4 v[174:175], off
	v_lshl_add_u64 v[174:175], v[180:181], 0, s[10:11]
	s_mov_b32 m0, s53
	s_nop 0
	global_load_lds_dwordx4 v[174:175], off
	s_waitcnt vmcnt(8)
	s_waitcnt lgkmcnt(0)
	s_waitcnt lgkmcnt(0)
	v_mfma_scale_f32_16x16x128_f8f6f4 v[84:87], v[0:7], v[204:211], v[84:87], v196, v196 op_sel_hi:[0,0,0]
	v_mfma_scale_f32_16x16x128_f8f6f4 v[80:83], v[8:15], v[204:211], v[80:83], v196, v196 op_sel_hi:[0,0,0]
	v_mfma_scale_f32_16x16x128_f8f6f4 v[64:67], v[8:15], v[212:219], v[64:67], v196, v196 op_sel_hi:[0,0,0]
	v_mfma_scale_f32_16x16x128_f8f6f4 v[68:71], v[0:7], v[212:219], v[68:71], v196, v196 op_sel_hi:[0,0,0]
	s_barrier
	s_setprio 3
	v_mfma_scale_f32_16x16x128_f8f6f4 v[52:55], v[0:7], v[220:227], v[52:55], v196, v196 op_sel_hi:[0,0,0]
	v_mfma_scale_f32_16x16x128_f8f6f4 v[48:51], v[8:15], v[220:227], v[48:51], v196, v196 op_sel_hi:[0,0,0]
	v_mfma_scale_f32_16x16x128_f8f6f4 v[32:35], v[8:15], v[230:237], v[32:35], v196, v196 op_sel_hi:[0,0,0]
	v_mfma_scale_f32_16x16x128_f8f6f4 v[36:39], v[0:7], v[230:237], v[36:39], v196, v196 op_sel_hi:[0,0,0]
	s_setprio 0
	s_setprio 3
	v_mfma_scale_f32_16x16x128_f8f6f4 v[92:95], v[16:23], v[204:211], v[92:95], v196, v196 op_sel_hi:[0,0,0]
	v_mfma_scale_f32_16x16x128_f8f6f4 v[88:91], v[24:31], v[204:211], v[88:91], v196, v196 op_sel_hi:[0,0,0]
	v_mfma_scale_f32_16x16x128_f8f6f4 v[72:75], v[24:31], v[212:219], v[72:75], v196, v196 op_sel_hi:[0,0,0]
	v_mfma_scale_f32_16x16x128_f8f6f4 v[76:79], v[16:23], v[212:219], v[76:79], v196, v196 op_sel_hi:[0,0,0]
	v_mfma_scale_f32_16x16x128_f8f6f4 v[60:63], v[16:23], v[220:227], v[60:63], v196, v196 op_sel_hi:[0,0,0]
	v_mfma_scale_f32_16x16x128_f8f6f4 v[56:59], v[24:31], v[220:227], v[56:59], v196, v196 op_sel_hi:[0,0,0]
	v_mfma_scale_f32_16x16x128_f8f6f4 v[40:43], v[24:31], v[230:237], v[40:43], v196, v196 op_sel_hi:[0,0,0]
	v_mfma_scale_f32_16x16x128_f8f6f4 v[44:47], v[16:23], v[230:237], v[44:47], v196, v196 op_sel_hi:[0,0,0]
	s_setprio 0
	s_barrier
	s_add_i32 s40, s40, 2
	s_add_u32 s56, s56, 0x100
	s_addc_u32 s57, s57, 0
	s_add_u32 s38, s38, 0x100
	s_addc_u32 s39, s39, 0
	s_cmp_gt_u32 s40, 29
	s_cbranch_scc0 .LBB0_361
	s_and_b64 vcc, exec, s[16:17]
	s_cbranch_vccz .LBB0_364
	s_barrier

; #define PG8_STAGE(bufoff, gbase, voff) do { _Pragma("unroll") for (int _i = 0; _i < 2; ++_i) \
;         __builtin_amdgcn_global_load_lds((const unsigned*)((const char*)(gbase) + (voff)[_i]), (LAS unsigned*)(lds + (bufoff) + ldsw + _i * 8192), 16, 0, 0); } while (0)
; #define PG8_LDA(dst, b, h) do { _Pragma("unroll") for (int m = 0; m < 4; ++m) _Pragma("unroll") for (int k = 0; k < 2; ++k) dst[m][k] = *(const LAS bf16x8*)(lds + PG8_SA(b, h) + aoffk[k] + m * 2048); } while (0)
; #define PG8_BAR __builtin_amdgcn_s_barrier()
; template <class Epi, class Sched, class GemmT>
; __device__ __forceinline__ void gemm_phase(LAS unsigned char* lds, const GemmT& g, const Sched& S, const Epi& E, const int wid) {
;     ...
;             for (int t = 0; t < nt; t += 2) {
;                 const bool last = (t == nt - 2);
;                 const char* a1 = cA + (size_t)(t + 1) * kstep;
;                 const char* a2 = last ? ns.A : cA + (size_t)(t + 2) * kstep; const char* b2 = last ? ns.B : cB + (size_t)(t + 2) * kstep;
;                 const char* a3 = a2 + kstep; const char* b3 = b2 + kstep;
;                 unsigned vA2[2], vB2[2];
; #pragma unroll
;                 for (int i = 0; i < 2; ++i) { vA2[i] = last ? nvA[i] : voffA[i]; vB2[i] = last ? nvB[i] : voffB[i]; }
;                 const size_t hA2 = last ? nhA : hstepA, hB2 = last ? nhB : hstepB;
;                 PG8_LDB(B0, 0, 0); PG8_LDB(B1, 0, 1); PG8_SCHED; PG8_LDA(At, 0, 0); PG8_STAGE(PG8_SA(1, 1), a1 + hstepA, voffA);
;                 PG8_WAIT_V(8); PG8_WAIT_L(0); PG8_BAR; PG8_MMA(0, 0, At, B0); PG8_MMA(0, 1, At, B1); PG8_BAR; PG8_SCHED;
;                 PG8_LDA(At, 0, 1); PG8_STAGE(PG8_SB(0, 0), b2, vB2); PG8_STAGE(PG8_SB(0, 1), b2 + hB2, vB2); PG8_STAGE(PG8_SA(0, 0), a2, vA2);
;                 PG8_WAIT_V(8); PG8_WAIT_L(0); PG8_BAR; PG8_MMA(1, 0, At, B0); PG8_MMA(1, 1, At, B1); PG8_BAR; PG8_SCHED;
;                 PG8_LDB(B0, 1, 0); PG8_LDB(B1, 1, 1); PG8_SCHED; PG8_LDA(At, 1, 0); PG8_STAGE(PG8_SA(0, 1), a2 + hA2, vA2);
;                 PG8_WAIT_V(8); PG8_WAIT_L(0); PG8_BAR; PG8_MMA(0, 0, At, B0); PG8_MMA(0, 1, At, B1); PG8_BAR; PG8_SCHED;
;                 PG8_LDA(At, 1, 1); PG8_STAGE(PG8_SB(1, 0), b3, vB2); PG8_STAGE(PG8_SB(1, 1), b3 + hB2, vB2); PG8_STAGE(PG8_SA(1, 0), a3, vA2);
;                 PG8_WAIT_V(8); PG8_WAIT_L(0); PG8_BAR; PG8_MMA(1, 0, At, B0); PG8_MMA(1, 1, At, B1); PG8_BAR; PG8_SCHED;
.LBB0_417:
	ds_read_b128 v[140:143], v192
	ds_read_b128 v[144:147], v193
	ds_read_b128 v[148:151], v194
	ds_read_b128 v[152:155], v195
	ds_read_b128 v[156:159], v196
	ds_read_b128 v[160:163], v197
	ds_read_b128 v[164:167], v198
	ds_read_b128 v[168:171], v199
	s_add_u32 s39, s84, 0xfff00080
	s_addc_u32 s40, s85, -1
	s_cmp_eq_u32 s38, 60
	s_cselect_b32 s87, s57, s40
	s_cselect_b32 s86, s56, s39
	s_cselect_b32 s71, s16, s37
	s_cselect_b32 s70, s5, s36
	v_lshl_add_u64 v[176:177], s[84:85], 0, v[128:129]
	s_add_i32 m0, s9, 0xc000
	ds_read_b128 v[172:175], v200
	ds_read_b128 v[208:211], v200 offset:2048
	ds_read_b128 v[212:215], v201
	ds_read_b128 v[216:219], v201 offset:2048
	ds_read_b128 v[220:223], v200 offset:4096
	ds_read_b128 v[224:227], v200 offset:6144
	ds_read_b128 v[230:233], v201 offset:4096
	ds_read_b128 v[234:237], v201 offset:6144
	global_load_lds_dwordx4 v[176:177], off
	v_lshl_add_u64 v[176:177], s[84:85], 0, v[132:133]
	s_add_i32 m0, s9, 0xe000
	s_nop 0
	global_load_lds_dwordx4 v[176:177], off
	s_waitcnt vmcnt(8)
	s_waitcnt lgkmcnt(0)
	s_waitcnt lgkmcnt(0)
	v_mfma_f32_16x16x32_bf16 v[124:127], v[140:143], v[172:175], v[124:127]
	v_mfma_f32_16x16x32_bf16 v[124:127], v[144:147], v[212:215], v[124:127]
	v_mfma_f32_16x16x32_bf16 v[120:123], v[152:155], v[212:215], v[120:123]
	v_mfma_f32_16x16x32_bf16 v[120:123], v[148:151], v[172:175], v[120:123]
	v_mfma_f32_16x16x32_bf16 v[112:115], v[148:151], v[208:211], v[112:115]
	v_mfma_f32_16x16x32_bf16 v[112:115], v[152:155], v[216:219], v[112:115]
	v_mfma_f32_16x16x32_bf16 v[116:119], v[144:147], v[216:219], v[116:119]
	v_mfma_f32_16x16x32_bf16 v[116:119], v[140:143], v[208:211], v[116:119]
	s_barrier
	s_setprio 3
	v_mfma_f32_16x16x32_bf16 v[100:103], v[140:143], v[220:223], v[100:103]
	v_mfma_f32_16x16x32_bf16 v[100:103], v[144:147], v[230:233], v[100:103]
	v_mfma_f32_16x16x32_bf16 v[96:99], v[152:155], v[230:233], v[96:99]
	v_mfma_f32_16x16x32_bf16 v[96:99], v[148:151], v[220:223], v[96:99]
	v_mfma_f32_16x16x32_bf16 v[76:79], v[148:151], v[224:227], v[76:79]
	v_mfma_f32_16x16x32_bf16 v[76:79], v[152:155], v[234:237], v[76:79]
	v_mfma_f32_16x16x32_bf16 v[84:87], v[144:147], v[234:237], v[84:87]
	v_mfma_f32_16x16x32_bf16 v[84:87], v[140:143], v[224:227], v[84:87]
	s_setprio 0
	s_setprio 3
	v_mfma_f32_16x16x32_bf16 v[108:111], v[156:159], v[172:175], v[108:111]
	v_mfma_f32_16x16x32_bf16 v[108:111], v[160:163], v[212:215], v[108:111]
	v_mfma_f32_16x16x32_bf16 v[104:107], v[168:171], v[212:215], v[104:107]
	v_mfma_f32_16x16x32_bf16 v[104:107], v[164:167], v[172:175], v[104:107]
	v_mfma_f32_16x16x32_bf16 v[88:91], v[164:167], v[208:211], v[88:91]
	v_mfma_f32_16x16x32_bf16 v[88:91], v[168:171], v[216:219], v[88:91]
	v_mfma_f32_16x16x32_bf16 v[92:95], v[160:163], v[216:219], v[92:95]
	v_mfma_f32_16x16x32_bf16 v[92:95], v[156:159], v[208:211], v[92:95]
	v_mfma_f32_16x16x32_bf16 v[68:71], v[156:159], v[220:223], v[68:71]
	v_mfma_f32_16x16x32_bf16 v[68:71], v[160:163], v[230:233], v[68:71]
	v_mfma_f32_16x16x32_bf16 v[64:67], v[168:171], v[230:233], v[64:67]
	v_mfma_f32_16x16x32_bf16 v[64:67], v[164:167], v[220:223], v[64:67]
	v_mfma_f32_16x16x32_bf16 v[40:43], v[164:167], v[224:227], v[40:43]
	v_mfma_f32_16x16x32_bf16 v[40:43], v[168:171], v[234:237], v[40:43]
	v_mfma_f32_16x16x32_bf16 v[48:51], v[160:163], v[234:237], v[48:51]
	v_mfma_f32_16x16x32_bf16 v[48:51], v[156:159], v[224:227], v[48:51]
	s_setprio 0
	s_barrier
	s_add_i32 s39, s35, s68
	v_lshl_add_u64 v[176:177], s[70:71], 0, v[130:131]
	s_mov_b32 m0, s39
	ds_read_b128 v[172:175], v200 offset:16384
	ds_read_b128 v[208:211], v200 offset:18432
	ds_read_b128 v[212:215], v201 offset:16384
	ds_read_b128 v[216:219], v201 offset:18432
	ds_read_b128 v[220:223], v200 offset:20480
	ds_read_b128 v[224:227], v200 offset:22528
	ds_read_b128 v[230:233], v201 offset:20480
	ds_read_b128 v[234:237], v201 offset:22528
	global_load_lds_dwordx4 v[176:177], off
	s_add_i32 m0, s39, 0x2000
	s_add_u32 s40, s70, 0x100000
	v_lshl_add_u64 v[180:181], s[70:71], 0, v[134:135]
	s_addc_u32 s41, s71, 0
	s_add_i32 s39, s69, s68
	global_load_lds_dwordx4 v[180:181], off
	v_lshl_add_u64 v[184:185], s[40:41], 0, v[130:131]
	s_mov_b32 m0, s39
	v_lshl_add_u64 v[188:189], s[86:87], 0, v[132:133]
	global_load_lds_dwordx4 v[184:185], off
	v_lshl_add_u64 v[184:185], s[40:41], 0, v[134:135]
	s_add_i32 m0, s39, 0x2000
	s_nop 0
	global_load_lds_dwordx4 v[184:185], off
	v_lshl_add_u64 v[184:185], s[86:87], 0, v[128:129]
	s_mov_b32 m0, s9
	s_nop 0
	global_load_lds_dwordx4 v[184:185], off
	s_mov_b32 m0, s29
	s_nop 0
	global_load_lds_dwordx4 v[188:189], off
	s_waitcnt vmcnt(8)
	s_waitcnt lgkmcnt(0)
	s_waitcnt lgkmcnt(0)
	v_mfma_f32_16x16x32_bf16 v[28:31], v[140:143], v[172:175], v[28:31]
	v_mfma_f32_16x16x32_bf16 v[28:31], v[144:147], v[212:215], v[28:31]
	v_mfma_f32_16x16x32_bf16 v[24:27], v[152:155], v[212:215], v[24:27]
	v_mfma_f32_16x16x32_bf16 v[24:27], v[148:151], v[172:175], v[24:27]
	v_mfma_f32_16x16x32_bf16 v[16:19], v[148:151], v[208:211], v[16:19]
	v_mfma_f32_16x16x32_bf16 v[16:19], v[152:155], v[216:219], v[16:19]
	v_mfma_f32_16x16x32_bf16 v[20:23], v[144:147], v[216:219], v[20:23]
	v_mfma_f32_16x16x32_bf16 v[20:23], v[140:143], v[208:211], v[20:23]
	s_barrier
; #define PG8_STAGE(bufoff, gbase, voff) do { _Pragma("unroll") for (int _i = 0; _i < 2; ++_i) \
;         __builtin_amdgcn_global_load_lds((const unsigned*)((const char*)(gbase) + (voff)[_i]), (LAS unsigned*)(lds + (bufoff) + ldsw + _i * 8192), 16, 0, 0); } while (0)
; #define PG8_LDA(dst, b, h) do { _Pragma("unroll") for (int m = 0; m < 4; ++m) _Pragma("unroll") for (int k = 0; k < 2; ++k) dst[m][k] = *(const LAS bf16x8*)(lds + PG8_SA(b, h) + aoffk[k] + m * 2048); } while (0)
; #define PG8_LDB(dst, b, h) do { _Pragma("unroll") for (int n = 0; n < 2; ++n) _Pragma("unroll") for (int k = 0; k < 2; ++k) dst[n][k] = *(const LAS bf16x8*)(lds + PG8_SB(b, h) + boffk[k] + n * 2048); } while (0)
; #define PG8_WAIT_V(n) asm volatile("s_waitcnt vmcnt(" #n ")" ::: "memory")
; #define PG8_WAIT_L(n) asm volatile("s_waitcnt lgkmcnt(" #n ")" ::: "memory")
; #define PG8_BAR __builtin_amdgcn_s_barrier()
; #define PG8_SCHED __builtin_amdgcn_sched_barrier(0)
; template <class Epi, class Sched, class GemmT>
; __device__ __forceinline__ void gemm_phase(LAS unsigned char* lds, const GemmT& g, const Sched& S, const Epi& E, const int wid) {
;     ...
;                 PG8_WAIT_V(8); PG8_WAIT_L(0); PG8_BAR; PG8_MMA(1, 0, At, B0); PG8_MMA(1, 1, At, B1); PG8_BAR; PG8_SCHED;
;                 PG8_LDB(B0, 1, 0); PG8_LDB(B1, 1, 1); PG8_SCHED; PG8_LDA(At, 1, 0); PG8_STAGE(PG8_SA(0, 1), a2 + hA2, vA2);
;                 PG8_WAIT_V(8); PG8_WAIT_L(0); PG8_BAR; PG8_MMA(0, 0, At, B0); PG8_MMA(0, 1, At, B1); PG8_BAR; PG8_SCHED;
;                 PG8_LDA(At, 1, 1); PG8_STAGE(PG8_SB(1, 0), b3, vB2); PG8_STAGE(PG8_SB(1, 1), b3 + hB2, vB2); PG8_STAGE(PG8_SA(1, 0), a3, vA2);
	s_setprio 3
	v_mfma_f32_16x16x32_bf16 v[12:15], v[140:143], v[220:223], v[12:15]
	v_mfma_f32_16x16x32_bf16 v[12:15], v[144:147], v[230:233], v[12:15]
	v_mfma_f32_16x16x32_bf16 v[8:11], v[152:155], v[230:233], v[8:11]
	v_mfma_f32_16x16x32_bf16 v[8:11], v[148:151], v[220:223], v[8:11]
	v_mfma_f32_16x16x32_bf16 v[0:3], v[148:151], v[224:227], v[0:3]
	v_mfma_f32_16x16x32_bf16 v[0:3], v[152:155], v[234:237], v[0:3]
	v_mfma_f32_16x16x32_bf16 v[4:7], v[144:147], v[234:237], v[4:7]
	v_mfma_f32_16x16x32_bf16 v[4:7], v[140:143], v[224:227], v[4:7]
	s_setprio 0
	s_setprio 3
	v_mfma_f32_16x16x32_bf16 v[80:83], v[156:159], v[172:175], v[80:83]
	v_mfma_f32_16x16x32_bf16 v[80:83], v[160:163], v[212:215], v[80:83]
	v_mfma_f32_16x16x32_bf16 v[72:75], v[168:171], v[212:215], v[72:75]
	v_mfma_f32_16x16x32_bf16 v[72:75], v[164:167], v[172:175], v[72:75]
	v_mfma_f32_16x16x32_bf16 v[56:59], v[164:167], v[208:211], v[56:59]
	v_mfma_f32_16x16x32_bf16 v[56:59], v[168:171], v[216:219], v[56:59]
	v_mfma_f32_16x16x32_bf16 v[60:63], v[160:163], v[216:219], v[60:63]
	v_mfma_f32_16x16x32_bf16 v[60:63], v[156:159], v[208:211], v[60:63]
	v_mfma_f32_16x16x32_bf16 v[52:55], v[156:159], v[220:223], v[52:55]
	v_mfma_f32_16x16x32_bf16 v[52:55], v[160:163], v[230:233], v[52:55]
	v_mfma_f32_16x16x32_bf16 v[44:47], v[168:171], v[230:233], v[44:47]
	v_mfma_f32_16x16x32_bf16 v[44:47], v[164:167], v[220:223], v[44:47]
	v_mfma_f32_16x16x32_bf16 v[32:35], v[164:167], v[224:227], v[32:35]
	v_mfma_f32_16x16x32_bf16 v[32:35], v[168:171], v[234:237], v[32:35]
	v_mfma_f32_16x16x32_bf16 v[36:39], v[160:163], v[234:237], v[36:39]
	v_mfma_f32_16x16x32_bf16 v[36:39], v[156:159], v[224:227], v[36:39]
	s_setprio 0
	s_barrier
	s_add_i32 s39, 0, 0x18000
	s_add_i32 s48, 0, 0x1c000
	v_add_u32_e32 v140, s39, v187
	v_add_u32_e32 v144, s39, v190
	v_add_u32_e32 v156, s48, v187
	v_add_u32_e32 v160, s48, v190
	ds_read_b128 v[140:143], v140
	ds_read_b128 v[144:147], v144
	ds_read_b128 v[148:151], v202
	ds_read_b128 v[152:155], v203
	ds_read_b128 v[156:159], v156
	ds_read_b128 v[160:163], v160
	ds_read_b128 v[164:167], v204
	ds_read_b128 v[168:171], v205
	s_add_u32 s40, s86, 0x100000
	s_addc_u32 s41, s87, 0
	s_mov_b32 m0, s93
	v_lshl_add_u64 v[238:239], s[40:41], 0, v[128:129]
	ds_read_b128 v[172:175], v200 offset:32768
	ds_read_b128 v[208:211], v200 offset:34816
	ds_read_b128 v[212:215], v201 offset:32768
	ds_read_b128 v[216:219], v201 offset:34816
	ds_read_b128 v[220:223], v200 offset:36864
	ds_read_b128 v[224:227], v200 offset:38912
	ds_read_b128 v[230:233], v201 offset:36864
	ds_read_b128 v[234:237], v201 offset:38912
	global_load_lds_dwordx4 v[238:239], off
	v_lshl_add_u64 v[238:239], s[40:41], 0, v[132:133]
	s_mov_b32 m0, s6
	s_nop 0
	global_load_lds_dwordx4 v[238:239], off
	s_waitcnt vmcnt(8)
	s_waitcnt lgkmcnt(0)
	s_waitcnt lgkmcnt(0)
	v_mfma_f32_16x16x32_bf16 v[124:127], v[140:143], v[172:175], v[124:127]
	v_mfma_f32_16x16x32_bf16 v[124:127], v[144:147], v[212:215], v[124:127]
	v_mfma_f32_16x16x32_bf16 v[120:123], v[152:155], v[212:215], v[120:123]
	v_mfma_f32_16x16x32_bf16 v[120:123], v[148:151], v[172:175], v[120:123]
	v_mfma_f32_16x16x32_bf16 v[112:115], v[148:151], v[208:211], v[112:115]
	v_mfma_f32_16x16x32_bf16 v[112:115], v[152:155], v[216:219], v[112:115]
	v_mfma_f32_16x16x32_bf16 v[116:119], v[144:147], v[216:219], v[116:119]
	v_mfma_f32_16x16x32_bf16 v[116:119], v[140:143], v[208:211], v[116:119]
	s_barrier
	s_setprio 3
	v_mfma_f32_16x16x32_bf16 v[100:103], v[140:143], v[220:223], v[100:103]
	v_mfma_f32_16x16x32_bf16 v[100:103], v[144:147], v[230:233], v[100:103]
	v_mfma_f32_16x16x32_bf16 v[96:99], v[152:155], v[230:233], v[96:99]
	v_mfma_f32_16x16x32_bf16 v[96:99], v[148:151], v[220:223], v[96:99]
	v_mfma_f32_16x16x32_bf16 v[76:79], v[148:151], v[224:227], v[76:79]
	v_mfma_f32_16x16x32_bf16 v[76:79], v[152:155], v[234:237], v[76:79]
	v_mfma_f32_16x16x32_bf16 v[84:87], v[144:147], v[234:237], v[84:87]
	v_mfma_f32_16x16x32_bf16 v[84:87], v[140:143], v[224:227], v[84:87]
	s_setprio 0
	s_setprio 3
	v_mfma_f32_16x16x32_bf16 v[108:111], v[156:159], v[172:175], v[108:111]
	v_mfma_f32_16x16x32_bf16 v[108:111], v[160:163], v[212:215], v[108:111]
	v_mfma_f32_16x16x32_bf16 v[104:107], v[168:171], v[212:215], v[104:107]
	v_mfma_f32_16x16x32_bf16 v[104:107], v[164:167], v[172:175], v[104:107]
	v_mfma_f32_16x16x32_bf16 v[88:91], v[164:167], v[208:211], v[88:91]
	v_mfma_f32_16x16x32_bf16 v[88:91], v[168:171], v[216:219], v[88:91]
	v_mfma_f32_16x16x32_bf16 v[92:95], v[160:163], v[216:219], v[92:95]
	v_mfma_f32_16x16x32_bf16 v[92:95], v[156:159], v[208:211], v[92:95]
	v_mfma_f32_16x16x32_bf16 v[68:71], v[156:159], v[220:223], v[68:71]
	v_mfma_f32_16x16x32_bf16 v[68:71], v[160:163], v[230:233], v[68:71]
	v_mfma_f32_16x16x32_bf16 v[64:67], v[168:171], v[230:233], v[64:67]
	v_mfma_f32_16x16x32_bf16 v[64:67], v[164:167], v[220:223], v[64:67]
	v_mfma_f32_16x16x32_bf16 v[40:43], v[164:167], v[224:227], v[40:43]
	v_mfma_f32_16x16x32_bf16 v[40:43], v[168:171], v[234:237], v[40:43]
	v_mfma_f32_16x16x32_bf16 v[48:51], v[160:163], v[234:237], v[48:51]
	v_mfma_f32_16x16x32_bf16 v[48:51], v[156:159], v[224:227], v[48:51]
	s_setprio 0
	s_barrier
; #define PG8_STAGE(bufoff, gbase, voff) do { _Pragma("unroll") for (int _i = 0; _i < 2; ++_i) \
;         __builtin_amdgcn_global_load_lds((const unsigned*)((const char*)(gbase) + (voff)[_i]), (LAS unsigned*)(lds + (bufoff) + ldsw + _i * 8192), 16, 0, 0); } while (0)
; #define PG8_LDA(dst, b, h) do { _Pragma("unroll") for (int m = 0; m < 4; ++m) _Pragma("unroll") for (int k = 0; k < 2; ++k) dst[m][k] = *(const LAS bf16x8*)(lds + PG8_SA(b, h) + aoffk[k] + m * 2048); } while (0)
; #define PG8_WAIT_V(n) asm volatile("s_waitcnt vmcnt(" #n ")" ::: "memory")
; #define PG8_WAIT_L(n) asm volatile("s_waitcnt lgkmcnt(" #n ")" ::: "memory")
; #define PG8_BAR __builtin_amdgcn_s_barrier()
; #define PG8_SCHED __builtin_amdgcn_sched_barrier(0)
; template <class Epi, class Sched, class GemmT>
; __device__ __forceinline__ void gemm_phase(LAS unsigned char* lds, const GemmT& g, const Sched& S, const Epi& E, const int wid) {
;     ...
;                 PG8_LDA(At, 1, 1); PG8_STAGE(PG8_SB(1, 0), b3, vB2); PG8_STAGE(PG8_SB(1, 1), b3 + hB2, vB2); PG8_STAGE(PG8_SA(1, 0), a3, vA2);
;                 PG8_WAIT_V(8); PG8_WAIT_L(0); PG8_BAR; PG8_MMA(1, 0, At, B0); PG8_MMA(1, 1, At, B1); PG8_BAR; PG8_SCHED;
;             }
;             if constexpr (NSEG > 1) { if (sgi + 1 < NSEG) E.mid(acc, cur, sgi, wr, wc, fr, fq); }
;             cs = ns; cA = ns.A; cB = ns.B; hstepA = nhA; hstepB = nhB;
; #pragma unroll
;             for (int i = 0; i < 2; ++i) { voffA[i] = nvA[i]; voffB[i] = nvB[i]; }
;         }
;         if (wr == 0) PG8_BAR;
	s_add_i32 s39, s39, s68
	v_lshl_add_u64 v[176:177], v[176:177], 0, s[66:67]
	s_mov_b32 m0, s39
	ds_read_b128 v[172:175], v200 offset:49152
	ds_read_b128 v[208:211], v200 offset:51200
	ds_read_b128 v[212:215], v201 offset:49152
	ds_read_b128 v[216:219], v201 offset:51200
	ds_read_b128 v[220:223], v200 offset:53248
	ds_read_b128 v[224:227], v200 offset:55296
	ds_read_b128 v[230:233], v201 offset:53248
	ds_read_b128 v[234:237], v201 offset:55296
	global_load_lds_dwordx4 v[176:177], off
	s_add_i32 m0, s39, 0x2000
	s_add_u32 s40, s70, 0x100080
	v_lshl_add_u64 v[176:177], v[180:181], 0, s[66:67]
	s_addc_u32 s41, s71, 0
	s_add_i32 s39, s48, s68
	global_load_lds_dwordx4 v[176:177], off
	v_lshl_add_u64 v[176:177], s[40:41], 0, v[130:131]
	s_mov_b32 m0, s39
	s_nop 0
	global_load_lds_dwordx4 v[176:177], off
	v_lshl_add_u64 v[176:177], s[40:41], 0, v[134:135]
	s_add_i32 m0, s39, 0x2000
	s_nop 0
	global_load_lds_dwordx4 v[176:177], off
	v_lshl_add_u64 v[176:177], v[184:185], 0, s[66:67]
	s_mov_b32 m0, s7
	s_nop 0
	global_load_lds_dwordx4 v[176:177], off
	v_lshl_add_u64 v[176:177], v[188:189], 0, s[66:67]
	s_mov_b32 m0, s12
	s_nop 0
	global_load_lds_dwordx4 v[176:177], off
	s_waitcnt vmcnt(8)
	s_waitcnt lgkmcnt(0)
	s_waitcnt lgkmcnt(0)
	v_mfma_f32_16x16x32_bf16 v[28:31], v[140:143], v[172:175], v[28:31]
	v_mfma_f32_16x16x32_bf16 v[28:31], v[144:147], v[212:215], v[28:31]
	v_mfma_f32_16x16x32_bf16 v[24:27], v[152:155], v[212:215], v[24:27]
	v_mfma_f32_16x16x32_bf16 v[24:27], v[148:151], v[172:175], v[24:27]
	v_mfma_f32_16x16x32_bf16 v[16:19], v[148:151], v[208:211], v[16:19]
	v_mfma_f32_16x16x32_bf16 v[16:19], v[152:155], v[216:219], v[16:19]
	v_mfma_f32_16x16x32_bf16 v[20:23], v[144:147], v[216:219], v[20:23]
	v_mfma_f32_16x16x32_bf16 v[20:23], v[140:143], v[208:211], v[20:23]
	s_barrier
	s_setprio 3
	v_mfma_f32_16x16x32_bf16 v[12:15], v[140:143], v[220:223], v[12:15]
	v_mfma_f32_16x16x32_bf16 v[12:15], v[144:147], v[230:233], v[12:15]
	v_mfma_f32_16x16x32_bf16 v[8:11], v[152:155], v[230:233], v[8:11]
	v_mfma_f32_16x16x32_bf16 v[8:11], v[148:151], v[220:223], v[8:11]
	v_mfma_f32_16x16x32_bf16 v[0:3], v[148:151], v[224:227], v[0:3]
	v_mfma_f32_16x16x32_bf16 v[0:3], v[152:155], v[234:237], v[0:3]
	v_mfma_f32_16x16x32_bf16 v[4:7], v[144:147], v[234:237], v[4:7]
	v_mfma_f32_16x16x32_bf16 v[4:7], v[140:143], v[224:227], v[4:7]
	s_setprio 0
	s_setprio 3
	v_mfma_f32_16x16x32_bf16 v[80:83], v[156:159], v[172:175], v[80:83]
	v_mfma_f32_16x16x32_bf16 v[80:83], v[160:163], v[212:215], v[80:83]
	v_mfma_f32_16x16x32_bf16 v[72:75], v[168:171], v[212:215], v[72:75]
	v_mfma_f32_16x16x32_bf16 v[72:75], v[164:167], v[172:175], v[72:75]
	v_mfma_f32_16x16x32_bf16 v[56:59], v[164:167], v[208:211], v[56:59]
	v_mfma_f32_16x16x32_bf16 v[56:59], v[168:171], v[216:219], v[56:59]
	v_mfma_f32_16x16x32_bf16 v[60:63], v[160:163], v[216:219], v[60:63]
	v_mfma_f32_16x16x32_bf16 v[60:63], v[156:159], v[208:211], v[60:63]
	v_mfma_f32_16x16x32_bf16 v[52:55], v[156:159], v[220:223], v[52:55]
	v_mfma_f32_16x16x32_bf16 v[52:55], v[160:163], v[230:233], v[52:55]
	v_mfma_f32_16x16x32_bf16 v[44:47], v[168:171], v[230:233], v[44:47]
	v_mfma_f32_16x16x32_bf16 v[44:47], v[164:167], v[220:223], v[44:47]
	v_mfma_f32_16x16x32_bf16 v[32:35], v[164:167], v[224:227], v[32:35]
	v_mfma_f32_16x16x32_bf16 v[32:35], v[168:171], v[234:237], v[32:35]
	v_mfma_f32_16x16x32_bf16 v[36:39], v[160:163], v[234:237], v[36:39]
	v_mfma_f32_16x16x32_bf16 v[36:39], v[156:159], v[224:227], v[36:39]
	s_setprio 0
	s_barrier
	s_add_i32 s38, s38, 2
	s_add_u32 s84, s84, 0x100
	s_addc_u32 s85, s85, 0
	s_add_u32 s36, s36, 0x100
	s_addc_u32 s37, s37, 0
	s_cmp_gt_u32 s38, 61
	s_cbranch_scc0 .LBB0_417
	s_and_b64 vcc, exec, s[20:21]
	s_cbranch_vccz .LBB0_420
	s_barrier

; #define PG8_STAGE(bufoff, gbase, voff) do { _Pragma("unroll") for (int _i = 0; _i < 2; ++_i) \
;         __builtin_amdgcn_global_load_lds((const unsigned*)((const char*)(gbase) + (voff)[_i]), (LAS unsigned*)(lds + (bufoff) + ldsw + _i * 8192), 16, 0, 0); } while (0)
; #define PG8_LDA(dst, b, h) do { _Pragma("unroll") for (int m = 0; m < 4; ++m) _Pragma("unroll") for (int k = 0; k < 2; ++k) dst[m][k] = *(const LAS bf16x8*)(lds + PG8_SA(b, h) + aoffk[k] + m * 2048); } while (0)
; #define PG8_BAR __builtin_amdgcn_s_barrier()
; template <class Epi, class Sched, class GemmT>
; __device__ __forceinline__ void gemm_phase(LAS unsigned char* lds, const GemmT& g, const Sched& S, const Epi& E, const int wid) {
;     ...
;             for (int t = 0; t < nt; t += 2) {
;                 const bool last = (t == nt - 2);
;                 const char* a1 = cA + (size_t)(t + 1) * kstep;
;                 const char* a2 = last ? ns.A : cA + (size_t)(t + 2) * kstep; const char* b2 = last ? ns.B : cB + (size_t)(t + 2) * kstep;
;                 const char* a3 = a2 + kstep; const char* b3 = b2 + kstep;
;                 unsigned vA2[2], vB2[2];
; #pragma unroll
;                 for (int i = 0; i < 2; ++i) { vA2[i] = last ? nvA[i] : voffA[i]; vB2[i] = last ? nvB[i] : voffB[i]; }
;                 const size_t hA2 = last ? nhA : hstepA, hB2 = last ? nhB : hstepB;
;                 PG8_LDB(B0, 0, 0); PG8_LDB(B1, 0, 1); PG8_SCHED; PG8_LDA(At, 0, 0); PG8_STAGE(PG8_SA(1, 1), a1 + hstepA, voffA);
;                 PG8_WAIT_V(8); PG8_WAIT_L(0); PG8_BAR; PG8_MMA(0, 0, At, B0); PG8_MMA(0, 1, At, B1); PG8_BAR; PG8_SCHED;
;                 PG8_LDA(At, 0, 1); PG8_STAGE(PG8_SB(0, 0), b2, vB2); PG8_STAGE(PG8_SB(0, 1), b2 + hB2, vB2); PG8_STAGE(PG8_SA(0, 0), a2, vA2);
;                 PG8_WAIT_V(8); PG8_WAIT_L(0); PG8_BAR; PG8_MMA(1, 0, At, B0); PG8_MMA(1, 1, At, B1); PG8_BAR; PG8_SCHED;
;                 PG8_LDB(B0, 1, 0); PG8_LDB(B1, 1, 1); PG8_SCHED; PG8_LDA(At, 1, 0); PG8_STAGE(PG8_SA(0, 1), a2 + hA2, vA2);
;                 PG8_WAIT_V(8); PG8_WAIT_L(0); PG8_BAR; PG8_MMA(0, 0, At, B0); PG8_MMA(0, 1, At, B1); PG8_BAR; PG8_SCHED;
;                 PG8_LDA(At, 1, 1); PG8_STAGE(PG8_SB(1, 0), b3, vB2); PG8_STAGE(PG8_SB(1, 1), b3 + hB2, vB2); PG8_STAGE(PG8_SA(1, 0), a3, vA2);
;                 PG8_WAIT_V(8); PG8_WAIT_L(0); PG8_BAR; PG8_MMA(1, 0, At, B0); PG8_MMA(1, 1, At, B1); PG8_BAR; PG8_SCHED;
.LBB0_764:
	s_cmp_eq_u32 s43, s56
	s_cselect_b64 vcc, -1, 0
	s_add_i32 s90, s90, 2
	v_add_u32_e32 v131, s62, v208
	s_add_u32 s48, s50, s56
	v_add_u32_e32 v133, s62, v209
	ds_read_b128 v[144:147], v131
	ds_read_b128 v[148:151], v133
	v_add_u32_e32 v131, s63, v208
	s_addc_u32 s49, s51, s57
	v_add_u32_e32 v133, s63, v209
	ds_read_b128 v[152:155], v131
	ds_read_b128 v[156:159], v133
	v_add_u32_e32 v131, s64, v208
	s_add_u32 s58, s48, 0x100
	v_add_u32_e32 v133, s64, v209
	ds_read_b128 v[160:163], v131
	ds_read_b128 v[164:167], v133
	v_add_u32_e32 v131, s65, v208
	s_addc_u32 s59, s49, 0
	v_add_u32_e32 v133, s65, v209
	ds_read_b128 v[168:171], v131
	ds_read_b128 v[172:175], v133
	s_and_b64 s[48:49], vcc, exec
	s_cselect_b32 s59, s19, s59
	s_cselect_b32 s58, s18, s58
	s_add_u32 s60, s85, s56
	s_addc_u32 s61, s89, s57
	s_and_b64 s[48:49], vcc, exec
	v_cndmask_b32_e32 v138, v132, v190, vcc
	v_cndmask_b32_e32 v0, v143, v214, vcc
	v_cndmask_b32_e32 v140, v130, v194, vcc
	v_cndmask_b32_e32 v188, v142, v192, vcc
	s_cselect_b32 s61, s13, s61
	s_cselect_b32 s60, s12, s60
	s_cselect_b32 s91, 0, s45
	s_cselect_b32 s92, s6, s44
	v_lshl_add_u64 v[202:203], v[134:135], 0, s[56:57]
	s_add_i32 m0, s14, 0xc000
	ds_read_b128 v[176:179], v212
	ds_read_b128 v[180:183], v212 offset:2048
	ds_read_b128 v[184:187], v213
	ds_read_b128 v[216:219], v213 offset:2048
	ds_read_b128 v[220:223], v212 offset:4096
	ds_read_b128 v[224:227], v212 offset:6144
	ds_read_b128 v[230:233], v213 offset:4096
	ds_read_b128 v[234:237], v213 offset:6144
	global_load_lds_dwordx4 v[202:203], off
	v_lshl_add_u64 v[202:203], v[136:137], 0, s[56:57]
	s_add_i32 m0, s14, 0xe000
	s_nop 0
	global_load_lds_dwordx4 v[202:203], off
	s_waitcnt vmcnt(8)
	s_waitcnt lgkmcnt(0)
	s_waitcnt lgkmcnt(0)
	v_mfma_f32_16x16x32_bf16 v[126:129], v[144:147], v[176:179], v[126:129]
	v_mfma_f32_16x16x32_bf16 v[126:129], v[148:151], v[184:187], v[126:129]
	v_mfma_f32_16x16x32_bf16 v[122:125], v[156:159], v[184:187], v[122:125]
	v_mfma_f32_16x16x32_bf16 v[122:125], v[152:155], v[176:179], v[122:125]
	v_mfma_f32_16x16x32_bf16 v[106:109], v[152:155], v[180:183], v[106:109]
	v_mfma_f32_16x16x32_bf16 v[106:109], v[156:159], v[216:219], v[106:109]
	v_mfma_f32_16x16x32_bf16 v[110:113], v[148:151], v[216:219], v[110:113]
	v_mfma_f32_16x16x32_bf16 v[110:113], v[144:147], v[180:183], v[110:113]
	s_barrier
	s_setprio 3
	v_mfma_f32_16x16x32_bf16 v[94:97], v[144:147], v[220:223], v[94:97]
	v_mfma_f32_16x16x32_bf16 v[94:97], v[148:151], v[230:233], v[94:97]
	v_mfma_f32_16x16x32_bf16 v[90:93], v[156:159], v[230:233], v[90:93]
	v_mfma_f32_16x16x32_bf16 v[90:93], v[152:155], v[220:223], v[90:93]
	v_mfma_f32_16x16x32_bf16 v[74:77], v[152:155], v[224:227], v[74:77]
	v_mfma_f32_16x16x32_bf16 v[74:77], v[156:159], v[234:237], v[74:77]
	v_mfma_f32_16x16x32_bf16 v[78:81], v[148:151], v[234:237], v[78:81]
	v_mfma_f32_16x16x32_bf16 v[78:81], v[144:147], v[224:227], v[78:81]
	s_setprio 0
	s_setprio 3
	v_mfma_f32_16x16x32_bf16 v[118:121], v[160:163], v[176:179], v[118:121]
	v_mfma_f32_16x16x32_bf16 v[118:121], v[164:167], v[184:187], v[118:121]
	v_mfma_f32_16x16x32_bf16 v[114:117], v[172:175], v[184:187], v[114:117]
	v_mfma_f32_16x16x32_bf16 v[114:117], v[168:171], v[176:179], v[114:117]
	v_mfma_f32_16x16x32_bf16 v[98:101], v[168:171], v[180:183], v[98:101]
	v_mfma_f32_16x16x32_bf16 v[98:101], v[172:175], v[216:219], v[98:101]
	v_mfma_f32_16x16x32_bf16 v[102:105], v[164:167], v[216:219], v[102:105]
	v_mfma_f32_16x16x32_bf16 v[102:105], v[160:163], v[180:183], v[102:105]
	v_mfma_f32_16x16x32_bf16 v[86:89], v[160:163], v[220:223], v[86:89]
	v_mfma_f32_16x16x32_bf16 v[86:89], v[164:167], v[230:233], v[86:89]
	v_mfma_f32_16x16x32_bf16 v[82:85], v[172:175], v[230:233], v[82:85]
	v_mfma_f32_16x16x32_bf16 v[82:85], v[168:171], v[220:223], v[82:85]
	v_mfma_f32_16x16x32_bf16 v[66:69], v[168:171], v[224:227], v[66:69]
	v_mfma_f32_16x16x32_bf16 v[66:69], v[172:175], v[234:237], v[66:69]
	v_mfma_f32_16x16x32_bf16 v[70:73], v[164:167], v[234:237], v[70:73]
	v_mfma_f32_16x16x32_bf16 v[70:73], v[160:163], v[224:227], v[70:73]
	s_setprio 0
	s_barrier
	s_add_i32 s48, s62, s68
	s_mov_b32 m0, s48
	ds_read_b128 v[176:179], v212 offset:16384
	ds_read_b128 v[180:183], v213 offset:16384
	ds_read_b128 v[184:187], v212 offset:18432
	ds_read_b128 v[216:219], v213 offset:18432
	ds_read_b128 v[220:223], v212 offset:20480
	ds_read_b128 v[224:227], v213 offset:20480
	ds_read_b128 v[230:233], v212 offset:22528
	ds_read_b128 v[234:237], v213 offset:22528
	global_load_lds_dwordx4 v0, s[60:61]
	s_add_i32 m0, s48, 0x2000
	v_mov_b32_e32 v189, v1
	s_add_u32 s48, s60, s92
	v_lshl_add_u64 v[202:203], s[60:61], 0, v[0:1]
	v_lshl_add_u64 v[238:239], s[60:61], 0, v[188:189]
	global_load_lds_dwordx4 v188, s[60:61]
	s_addc_u32 s49, s61, s91
	s_add_i32 s60, s64, s68
	s_mov_b32 m0, s60
	v_mov_b32_e32 v139, v1
	global_load_lds_dwordx4 v0, s[48:49]
	s_add_i32 m0, s60, 0x2000
	v_mov_b32_e32 v141, v1
	global_load_lds_dwordx4 v188, s[48:49]
	s_mov_b32 m0, s14
	v_lshl_add_u64 v[240:241], s[48:49], 0, v[0:1]
	global_load_lds_dwordx4 v138, s[58:59]
	s_mov_b32 m0, s15
	v_lshl_add_u64 v[242:243], s[48:49], 0, v[188:189]
	global_load_lds_dwordx4 v140, s[58:59]
	s_waitcnt vmcnt(8)
	s_waitcnt lgkmcnt(0)
	v_lshl_add_u64 v[188:189], s[58:59], 0, v[138:139]
	v_lshl_add_u64 v[244:245], s[58:59], 0, v[140:141]
	s_waitcnt lgkmcnt(0)
	v_mfma_f32_16x16x32_bf16 v[62:65], v[144:147], v[176:179], v[62:65]
	v_mfma_f32_16x16x32_bf16 v[62:65], v[148:151], v[180:183], v[62:65]
	v_mfma_f32_16x16x32_bf16 v[58:61], v[156:159], v[180:183], v[58:61]
	v_mfma_f32_16x16x32_bf16 v[58:61], v[152:155], v[176:179], v[58:61]
	v_mfma_f32_16x16x32_bf16 v[42:45], v[152:155], v[184:187], v[42:45]
	v_mfma_f32_16x16x32_bf16 v[42:45], v[156:159], v[216:219], v[42:45]
	v_mfma_f32_16x16x32_bf16 v[46:49], v[148:151], v[216:219], v[46:49]
	v_mfma_f32_16x16x32_bf16 v[46:49], v[144:147], v[184:187], v[46:49]
	s_barrier
; #define PG8_STAGE(bufoff, gbase, voff) do { _Pragma("unroll") for (int _i = 0; _i < 2; ++_i) \
;         __builtin_amdgcn_global_load_lds((const unsigned*)((const char*)(gbase) + (voff)[_i]), (LAS unsigned*)(lds + (bufoff) + ldsw + _i * 8192), 16, 0, 0); } while (0)
; #define PG8_LDA(dst, b, h) do { _Pragma("unroll") for (int m = 0; m < 4; ++m) _Pragma("unroll") for (int k = 0; k < 2; ++k) dst[m][k] = *(const LAS bf16x8*)(lds + PG8_SA(b, h) + aoffk[k] + m * 2048); } while (0)
; #define PG8_LDB(dst, b, h) do { _Pragma("unroll") for (int n = 0; n < 2; ++n) _Pragma("unroll") for (int k = 0; k < 2; ++k) dst[n][k] = *(const LAS bf16x8*)(lds + PG8_SB(b, h) + boffk[k] + n * 2048); } while (0)
; #define PG8_WAIT_V(n) asm volatile("s_waitcnt vmcnt(" #n ")" ::: "memory")
; #define PG8_WAIT_L(n) asm volatile("s_waitcnt lgkmcnt(" #n ")" ::: "memory")
; #define PG8_BAR __builtin_amdgcn_s_barrier()
; #define PG8_SCHED __builtin_amdgcn_sched_barrier(0)
; template <class Epi, class Sched, class GemmT>
; __device__ __forceinline__ void gemm_phase(LAS unsigned char* lds, const GemmT& g, const Sched& S, const Epi& E, const int wid) {
;     ...
;                 PG8_WAIT_V(8); PG8_WAIT_L(0); PG8_BAR; PG8_MMA(1, 0, At, B0); PG8_MMA(1, 1, At, B1); PG8_BAR; PG8_SCHED;
;                 PG8_LDB(B0, 1, 0); PG8_LDB(B1, 1, 1); PG8_SCHED; PG8_LDA(At, 1, 0); PG8_STAGE(PG8_SA(0, 1), a2 + hA2, vA2);
;                 PG8_WAIT_V(8); PG8_WAIT_L(0); PG8_BAR; PG8_MMA(0, 0, At, B0); PG8_MMA(0, 1, At, B1); PG8_BAR; PG8_SCHED;
;                 PG8_LDA(At, 1, 1); PG8_STAGE(PG8_SB(1, 0), b3, vB2); PG8_STAGE(PG8_SB(1, 1), b3 + hB2, vB2); PG8_STAGE(PG8_SA(1, 0), a3, vA2);
	s_setprio 3
	v_mfma_f32_16x16x32_bf16 v[30:33], v[144:147], v[220:223], v[30:33]
	v_mfma_f32_16x16x32_bf16 v[30:33], v[148:151], v[224:227], v[30:33]
	v_mfma_f32_16x16x32_bf16 v[22:25], v[156:159], v[224:227], v[22:25]
	v_mfma_f32_16x16x32_bf16 v[22:25], v[152:155], v[220:223], v[22:25]
	v_mfma_f32_16x16x32_bf16 v[6:9], v[152:155], v[230:233], v[6:9]
	v_mfma_f32_16x16x32_bf16 v[6:9], v[156:159], v[234:237], v[6:9]
	v_mfma_f32_16x16x32_bf16 v[14:17], v[148:151], v[234:237], v[14:17]
	v_mfma_f32_16x16x32_bf16 v[14:17], v[144:147], v[230:233], v[14:17]
	s_setprio 0
	s_setprio 3
	v_mfma_f32_16x16x32_bf16 v[54:57], v[160:163], v[176:179], v[54:57]
	v_mfma_f32_16x16x32_bf16 v[54:57], v[164:167], v[180:183], v[54:57]
	v_mfma_f32_16x16x32_bf16 v[50:53], v[172:175], v[180:183], v[50:53]
	v_mfma_f32_16x16x32_bf16 v[50:53], v[168:171], v[176:179], v[50:53]
	v_mfma_f32_16x16x32_bf16 v[34:37], v[168:171], v[184:187], v[34:37]
	v_mfma_f32_16x16x32_bf16 v[34:37], v[172:175], v[216:219], v[34:37]
	v_mfma_f32_16x16x32_bf16 v[38:41], v[164:167], v[216:219], v[38:41]
	v_mfma_f32_16x16x32_bf16 v[38:41], v[160:163], v[184:187], v[38:41]
	v_mfma_f32_16x16x32_bf16 v[26:29], v[160:163], v[220:223], v[26:29]
	v_mfma_f32_16x16x32_bf16 v[26:29], v[164:167], v[224:227], v[26:29]
	v_mfma_f32_16x16x32_bf16 v[18:21], v[172:175], v[224:227], v[18:21]
	v_mfma_f32_16x16x32_bf16 v[18:21], v[168:171], v[220:223], v[18:21]
	v_mfma_f32_16x16x32_bf16 v[2:5], v[168:171], v[230:233], v[2:5]
	v_mfma_f32_16x16x32_bf16 v[2:5], v[172:175], v[234:237], v[2:5]
	v_mfma_f32_16x16x32_bf16 v[10:13], v[164:167], v[234:237], v[10:13]
	v_mfma_f32_16x16x32_bf16 v[10:13], v[160:163], v[230:233], v[10:13]
	s_setprio 0
	s_barrier
	s_add_i32 s60, 0, 0x18000
	v_add_u32_e32 v0, s60, v208
	v_add_u32_e32 v131, s60, v209
	ds_read_b128 v[144:147], v0
	ds_read_b128 v[148:151], v131
	v_add_u32_e32 v0, s66, v208
	s_add_i32 s61, 0, 0x1c000
	v_add_u32_e32 v131, s66, v209
	ds_read_b128 v[152:155], v0
	ds_read_b128 v[156:159], v131
	v_add_u32_e32 v0, s61, v208
	v_add_u32_e32 v131, s61, v209
	ds_read_b128 v[160:163], v0
	ds_read_b128 v[164:167], v131
	v_add_u32_e32 v0, s67, v208
	v_add_u32_e32 v131, s67, v209
	ds_read_b128 v[168:171], v0
	ds_read_b128 v[172:175], v131
	s_add_u32 s48, s58, s92
	s_addc_u32 s49, s59, s91
	s_mov_b32 m0, s34
	ds_read_b128 v[176:179], v212 offset:32768
	ds_read_b128 v[180:183], v212 offset:34816
	ds_read_b128 v[184:187], v213 offset:32768
	ds_read_b128 v[216:219], v213 offset:34816
	ds_read_b128 v[220:223], v212 offset:36864
	ds_read_b128 v[224:227], v212 offset:38912
	ds_read_b128 v[230:233], v213 offset:36864
	ds_read_b128 v[234:237], v213 offset:38912
	global_load_lds_dwordx4 v138, s[48:49]
	s_mov_b32 m0, s35
	s_nop 0
	global_load_lds_dwordx4 v140, s[48:49]
	s_waitcnt vmcnt(8)
	s_waitcnt lgkmcnt(0)
	s_waitcnt lgkmcnt(0)
	v_mfma_f32_16x16x32_bf16 v[126:129], v[144:147], v[176:179], v[126:129]
	v_mfma_f32_16x16x32_bf16 v[126:129], v[148:151], v[184:187], v[126:129]
	v_mfma_f32_16x16x32_bf16 v[122:125], v[156:159], v[184:187], v[122:125]
	v_mfma_f32_16x16x32_bf16 v[122:125], v[152:155], v[176:179], v[122:125]
	v_mfma_f32_16x16x32_bf16 v[106:109], v[152:155], v[180:183], v[106:109]
	v_mfma_f32_16x16x32_bf16 v[106:109], v[156:159], v[216:219], v[106:109]
	v_mfma_f32_16x16x32_bf16 v[110:113], v[148:151], v[216:219], v[110:113]
	v_mfma_f32_16x16x32_bf16 v[110:113], v[144:147], v[180:183], v[110:113]
	s_barrier
	s_setprio 3
	v_mfma_f32_16x16x32_bf16 v[94:97], v[144:147], v[220:223], v[94:97]
	v_mfma_f32_16x16x32_bf16 v[94:97], v[148:151], v[230:233], v[94:97]
	v_mfma_f32_16x16x32_bf16 v[90:93], v[156:159], v[230:233], v[90:93]
	v_mfma_f32_16x16x32_bf16 v[90:93], v[152:155], v[220:223], v[90:93]
	v_mfma_f32_16x16x32_bf16 v[74:77], v[152:155], v[224:227], v[74:77]
	v_mfma_f32_16x16x32_bf16 v[74:77], v[156:159], v[234:237], v[74:77]
	v_mfma_f32_16x16x32_bf16 v[78:81], v[148:151], v[234:237], v[78:81]
	v_mfma_f32_16x16x32_bf16 v[78:81], v[144:147], v[224:227], v[78:81]
	s_setprio 0
	s_setprio 3
	v_mfma_f32_16x16x32_bf16 v[118:121], v[160:163], v[176:179], v[118:121]
	v_mfma_f32_16x16x32_bf16 v[118:121], v[164:167], v[184:187], v[118:121]
	v_mfma_f32_16x16x32_bf16 v[114:117], v[172:175], v[184:187], v[114:117]
	v_mfma_f32_16x16x32_bf16 v[114:117], v[168:171], v[176:179], v[114:117]
	v_mfma_f32_16x16x32_bf16 v[98:101], v[168:171], v[180:183], v[98:101]
	v_mfma_f32_16x16x32_bf16 v[98:101], v[172:175], v[216:219], v[98:101]
	v_mfma_f32_16x16x32_bf16 v[102:105], v[164:167], v[216:219], v[102:105]
	v_mfma_f32_16x16x32_bf16 v[102:105], v[160:163], v[180:183], v[102:105]
	v_mfma_f32_16x16x32_bf16 v[86:89], v[160:163], v[220:223], v[86:89]
	v_mfma_f32_16x16x32_bf16 v[86:89], v[164:167], v[230:233], v[86:89]
	v_mfma_f32_16x16x32_bf16 v[82:85], v[172:175], v[230:233], v[82:85]
	v_mfma_f32_16x16x32_bf16 v[82:85], v[168:171], v[220:223], v[82:85]
	v_mfma_f32_16x16x32_bf16 v[66:69], v[168:171], v[224:227], v[66:69]
	v_mfma_f32_16x16x32_bf16 v[66:69], v[172:175], v[234:237], v[66:69]
	v_mfma_f32_16x16x32_bf16 v[70:73], v[164:167], v[234:237], v[70:73]
	v_mfma_f32_16x16x32_bf16 v[70:73], v[160:163], v[224:227], v[70:73]
	s_setprio 0
	s_barrier
; #define PG8_STAGE(bufoff, gbase, voff) do { _Pragma("unroll") for (int _i = 0; _i < 2; ++_i) \
;         __builtin_amdgcn_global_load_lds((const unsigned*)((const char*)(gbase) + (voff)[_i]), (LAS unsigned*)(lds + (bufoff) + ldsw + _i * 8192), 16, 0, 0); } while (0)
; #define PG8_LDA(dst, b, h) do { _Pragma("unroll") for (int m = 0; m < 4; ++m) _Pragma("unroll") for (int k = 0; k < 2; ++k) dst[m][k] = *(const LAS bf16x8*)(lds + PG8_SA(b, h) + aoffk[k] + m * 2048); } while (0)
; #define PG8_WAIT_V(n) asm volatile("s_waitcnt vmcnt(" #n ")" ::: "memory")
; #define PG8_WAIT_L(n) asm volatile("s_waitcnt lgkmcnt(" #n ")" ::: "memory")
; #define PG8_BAR __builtin_amdgcn_s_barrier()
; #define PG8_SCHED __builtin_amdgcn_sched_barrier(0)
;     __device__ __forceinline__ void mid(Acc& acc, const Unit& u, int s, int wr, int wc, int fr, int fq) const {
;         int lo = (wr * 4 + wc) * 8192 + (fq * 16 + fr) * 16; asm volatile("" : "+v"(lo));
;         const unsigned char* gp = gate + ((size_t)(u.pm * 48 + s * 16 + u.pn) << 16) + lo;
;         u32x4 G[8][2];
; #pragma unroll
;         for (int i = 0; i < 8; ++i) { G[i][0] = __builtin_nontemporal_load((const u32x4*)(gp + i * 1024)); G[i][1] = __builtin_nontemporal_load((const u32x4*)(gp + (1 << 20) + i * 1024)); }
; template <class Epi, class Sched, class GemmT>
; __device__ __forceinline__ void gemm_phase(LAS unsigned char* lds, const GemmT& g, const Sched& S, const Epi& E, const int wid) {
;     ...
;                 PG8_LDA(At, 1, 1); PG8_STAGE(PG8_SB(1, 0), b3, vB2); PG8_STAGE(PG8_SB(1, 1), b3 + hB2, vB2); PG8_STAGE(PG8_SA(1, 0), a3, vA2);
;                 PG8_WAIT_V(8); PG8_WAIT_L(0); PG8_BAR; PG8_MMA(1, 0, At, B0); PG8_MMA(1, 1, At, B1); PG8_BAR; PG8_SCHED;
;             }
;             if constexpr (NSEG > 1) { if (sgi + 1 < NSEG) E.mid(acc, cur, sgi, wr, wc, fr, fq); }
;             cs = ns; cA = ns.A; cB = ns.B; hstepA = nhA; hstepB = nhB;
	s_add_i32 s48, s60, s68
	v_lshl_add_u64 v[202:203], v[202:203], 0, s[20:21]
	s_mov_b32 m0, s48
	ds_read_b128 v[138:141], v212 offset:49152
	ds_read_b128 v[176:179], v212 offset:51200
	ds_read_b128 v[180:183], v213 offset:49152
	ds_read_b128 v[184:187], v213 offset:51200
	ds_read_b128 v[216:219], v212 offset:53248
	ds_read_b128 v[220:223], v212 offset:55296
	ds_read_b128 v[224:227], v213 offset:53248
	ds_read_b128 v[230:233], v213 offset:55296
	global_load_lds_dwordx4 v[202:203], off
	v_lshl_add_u64 v[202:203], v[238:239], 0, s[20:21]
	s_add_i32 m0, s48, 0x2000
	s_add_i32 s48, s61, s68
	global_load_lds_dwordx4 v[202:203], off
	v_lshl_add_u64 v[202:203], v[240:241], 0, s[20:21]
	s_mov_b32 m0, s48
	v_lshl_add_u64 v[188:189], v[188:189], 0, s[20:21]
	global_load_lds_dwordx4 v[202:203], off
	v_lshl_add_u64 v[202:203], v[242:243], 0, s[20:21]
	s_add_i32 m0, s48, 0x2000
	s_nop 0
	global_load_lds_dwordx4 v[202:203], off
	s_mov_b32 m0, s54
	s_nop 0
	global_load_lds_dwordx4 v[188:189], off
	v_lshl_add_u64 v[188:189], v[244:245], 0, s[20:21]
	s_mov_b32 m0, s55
	s_nop 0
	global_load_lds_dwordx4 v[188:189], off
	s_waitcnt vmcnt(8)
	s_waitcnt lgkmcnt(0)
	s_waitcnt lgkmcnt(0)
	v_mfma_f32_16x16x32_bf16 v[62:65], v[144:147], v[138:141], v[62:65]
	v_mfma_f32_16x16x32_bf16 v[62:65], v[148:151], v[180:183], v[62:65]
	v_mfma_f32_16x16x32_bf16 v[58:61], v[156:159], v[180:183], v[58:61]
	v_mfma_f32_16x16x32_bf16 v[58:61], v[152:155], v[138:141], v[58:61]
	v_mfma_f32_16x16x32_bf16 v[42:45], v[152:155], v[176:179], v[42:45]
	v_mfma_f32_16x16x32_bf16 v[42:45], v[156:159], v[184:187], v[42:45]
	v_mfma_f32_16x16x32_bf16 v[46:49], v[148:151], v[184:187], v[46:49]
	v_mfma_f32_16x16x32_bf16 v[46:49], v[144:147], v[176:179], v[46:49]
	s_barrier
	s_setprio 3
	v_mfma_f32_16x16x32_bf16 v[30:33], v[144:147], v[216:219], v[30:33]
	v_mfma_f32_16x16x32_bf16 v[30:33], v[148:151], v[224:227], v[30:33]
	v_mfma_f32_16x16x32_bf16 v[22:25], v[156:159], v[224:227], v[22:25]
	v_mfma_f32_16x16x32_bf16 v[22:25], v[152:155], v[216:219], v[22:25]
	v_mfma_f32_16x16x32_bf16 v[6:9], v[152:155], v[220:223], v[6:9]
	v_mfma_f32_16x16x32_bf16 v[6:9], v[156:159], v[230:233], v[6:9]
	v_mfma_f32_16x16x32_bf16 v[14:17], v[148:151], v[230:233], v[14:17]
	v_mfma_f32_16x16x32_bf16 v[14:17], v[144:147], v[220:223], v[14:17]
	s_setprio 0
	s_setprio 3
	v_mfma_f32_16x16x32_bf16 v[54:57], v[160:163], v[138:141], v[54:57]
	v_mfma_f32_16x16x32_bf16 v[54:57], v[164:167], v[180:183], v[54:57]
	v_mfma_f32_16x16x32_bf16 v[50:53], v[172:175], v[180:183], v[50:53]
	v_mfma_f32_16x16x32_bf16 v[50:53], v[168:171], v[138:141], v[50:53]
	v_mfma_f32_16x16x32_bf16 v[34:37], v[168:171], v[176:179], v[34:37]
	v_mfma_f32_16x16x32_bf16 v[34:37], v[172:175], v[184:187], v[34:37]
	v_mfma_f32_16x16x32_bf16 v[38:41], v[164:167], v[184:187], v[38:41]
	v_mfma_f32_16x16x32_bf16 v[38:41], v[160:163], v[176:179], v[38:41]
	v_mfma_f32_16x16x32_bf16 v[26:29], v[160:163], v[216:219], v[26:29]
	v_mfma_f32_16x16x32_bf16 v[26:29], v[164:167], v[224:227], v[26:29]
	v_mfma_f32_16x16x32_bf16 v[18:21], v[172:175], v[224:227], v[18:21]
	v_mfma_f32_16x16x32_bf16 v[18:21], v[168:171], v[216:219], v[18:21]
	v_mfma_f32_16x16x32_bf16 v[2:5], v[168:171], v[220:223], v[2:5]
	v_mfma_f32_16x16x32_bf16 v[2:5], v[172:175], v[230:233], v[2:5]
	v_mfma_f32_16x16x32_bf16 v[10:13], v[164:167], v[230:233], v[10:13]
	v_mfma_f32_16x16x32_bf16 v[10:13], v[160:163], v[220:223], v[10:13]
	s_setprio 0
	s_barrier
	s_add_u32 s56, s56, 0x100
	s_addc_u32 s57, s57, 0
	s_cmp_ge_u32 s90, s42
	s_cbranch_scc0 .LBB0_764
	s_and_b64 vcc, exec, s[52:53]
	s_cbranch_vccz .LBB0_767
	s_lshl_b32 s42, s83, 4
	s_add_i32 s42, s82, s42
	s_ashr_i32 s43, s42, 31
	s_lshl_b64 s[42:43], s[42:43], 16
	v_mov_b32_e32 v130, v210
	s_add_u32 s42, s22, s42
	s_addc_u32 s43, s23, s43
	v_ashrrev_i32_e32 v131, 31, v130
	v_lshl_add_u64 v[130:131], s[42:43], 0, v[130:131]
	v_add_co_u32_e32 v132, vcc, s69, v130
	s_mov_b32 s42, 0x101000
	s_nop 0
	v_addc_co_u32_e32 v133, vcc, 0, v131, vcc
	global_load_dwordx4 v[186:189], v[130:131], off nt
	v_add_co_u32_e32 v134, vcc, s42, v130
	s_movk_i32 s42, 0x1000
	s_nop 0
	v_addc_co_u32_e32 v135, vcc, 0, v131, vcc
	global_load_dwordx4 v[216:219], v[134:135], off offset:-4096 nt
	global_load_dwordx4 v[178:181], v[130:131], off offset:1024 nt
	global_load_dwordx4 v[182:185], v[132:133], off offset:1024 nt
	global_load_dwordx4 v[170:173], v[130:131], off offset:2048 nt
	global_load_dwordx4 v[174:177], v[132:133], off offset:2048 nt
	global_load_dwordx4 v[162:165], v[130:131], off offset:3072 nt
	global_load_dwordx4 v[166:169], v[132:133], off offset:3072 nt
	v_add_co_u32_e32 v130, vcc, s42, v130
	s_waitcnt vmcnt(0)
;     __device__ __forceinline__ void mid(Acc& acc, const Unit& u, int s, int wr, int wc, int fr, int fq) const {
;     ...
;         for (int i = 0; i < 8; ++i) { G[i][0] = __builtin_nontemporal_load((const u32x4*)(gp + i * 1024)); G[i][1] = __builtin_nontemporal_load((const u32x4*)(gp + (1 << 20) + i * 1024)); }
; #pragma unroll
;         for (int i = 0; i < 8; ++i) { const int ai = i >> 2, m = i & 3;
; #pragma unroll
;             for (int bj = 0; bj < 2; ++bj) {
;                 const u32x4 ga = G[i][0], gb = G[i][1];
;                 const u32x2 wa = bj == 0 ? (u32x2){ga.x, ga.y} : (u32x2){ga.z, ga.w}, wb = bj == 0 ? (u32x2){gb.x, gb.y} : (u32x2){gb.z, gb.w};
;                 float fa[8], fb[8]; gate_unpack8(wa, fa); gate_unpack8(wb, fb);
; #pragma unroll
;                 for (int e = 0; e < 8; ++e) fa[e] = fa[e] * __builtin_amdgcn_rcpf(fb[e]);
;                 f32x4& v0 = acc[ai][bj][m][0]; f32x4& v1 = acc[ai][bj][m][1];
;                 v0[0] *= fa[0]; v0[1] *= fa[1]; v0[2] *= fa[2]; v0[3] *= fa[3]; v1[0] *= fa[4]; v1[1] *= fa[5]; v1[2] *= fa[6]; v1[3] *= fa[7]; }
;             __builtin_amdgcn_sched_barrier(0); }
	v_cvt_f32_ubyte0_e32 v0, v216
	v_addc_co_u32_e32 v131, vcc, 0, v131, vcc
	global_load_dwordx4 v[154:157], v[130:131], off nt
	global_load_dwordx4 v[158:161], v[134:135], off nt
	global_load_dwordx4 v[146:149], v[130:131], off offset:1024 nt
	global_load_dwordx4 v[150:153], v[134:135], off offset:1024 nt
	global_load_dwordx4 v[138:141], v[130:131], off offset:2048 nt
	global_load_dwordx4 v[142:145], v[134:135], off offset:2048 nt
	s_nop 0
	global_load_dwordx4 v[130:133], v[130:131], off offset:3072 nt
	s_nop 0
	global_load_dwordx4 v[134:137], v[134:135], off offset:3072 nt
	v_cvt_f32_ubyte1_e32 v203, v216
	v_cvt_f32_ubyte2_e32 v215, v216
	v_cvt_f32_ubyte3_e32 v220, v216
	v_cvt_f32_ubyte0_e32 v221, v217
	v_cvt_f32_ubyte1_e32 v222, v217
	v_cvt_f32_ubyte2_e32 v223, v217
	v_cvt_f32_ubyte3_e32 v224, v217
	v_rcp_iflag_f32_e32 v202, v0
	v_rcp_iflag_f32_e32 v203, v203
	v_rcp_iflag_f32_e32 v216, v215
	v_rcp_iflag_f32_e32 v217, v220
	v_rcp_iflag_f32_e32 v220, v221
	v_rcp_iflag_f32_e32 v221, v222
	v_rcp_iflag_f32_e32 v222, v223
	v_rcp_iflag_f32_e32 v223, v224
	v_cvt_f32_ubyte3_e32 v225, v186
	v_cvt_f32_ubyte2_e32 v224, v186
	v_cvt_f32_ubyte1_e32 v227, v186
	v_cvt_f32_ubyte0_e32 v226, v186
	v_pk_mul_f32 v[202:203], v[202:203], v[226:227]
	v_pk_mul_f32 v[216:217], v[216:217], v[224:225]
	v_pk_mul_f32 v[126:127], v[126:127], v[202:203]
	v_pk_mul_f32 v[128:129], v[128:129], v[216:217]
	v_cvt_f32_ubyte3_e32 v203, v187
	v_cvt_f32_ubyte2_e32 v202, v187
	v_cvt_f32_ubyte1_e32 v217, v187
	v_cvt_f32_ubyte0_e32 v216, v187
	v_pk_mul_f32 v[186:187], v[220:221], v[216:217]
	v_pk_mul_f32 v[202:203], v[222:223], v[202:203]
	v_pk_mul_f32 v[122:123], v[122:123], v[186:187]
	v_pk_mul_f32 v[124:125], v[124:125], v[202:203]
	v_cvt_f32_ubyte0_e32 v0, v218
	v_cvt_f32_ubyte1_e32 v186, v218
	v_cvt_f32_ubyte2_e32 v187, v218
	v_cvt_f32_ubyte3_e32 v202, v218
	v_cvt_f32_ubyte0_e32 v203, v219
	v_cvt_f32_ubyte1_e32 v215, v219
	v_cvt_f32_ubyte2_e32 v220, v219
	v_cvt_f32_ubyte3_e32 v221, v219
	v_rcp_iflag_f32_e32 v216, v0
	v_rcp_iflag_f32_e32 v217, v186
	v_rcp_iflag_f32_e32 v218, v187
	v_rcp_iflag_f32_e32 v219, v202
	v_rcp_iflag_f32_e32 v202, v203
	v_rcp_iflag_f32_e32 v203, v215
	v_rcp_iflag_f32_e32 v186, v220
	v_rcp_iflag_f32_e32 v187, v221
	v_cvt_f32_ubyte3_e32 v221, v188
	v_cvt_f32_ubyte2_e32 v220, v188
	v_cvt_f32_ubyte1_e32 v223, v188
	v_cvt_f32_ubyte0_e32 v222, v188
	v_pk_mul_f32 v[216:217], v[216:217], v[222:223]
	v_pk_mul_f32 v[218:219], v[218:219], v[220:221]
	v_pk_mul_f32 v[118:119], v[118:119], v[216:217]
	v_pk_mul_f32 v[120:121], v[120:121], v[218:219]
	v_cvt_f32_ubyte3_e32 v217, v189
	v_cvt_f32_ubyte2_e32 v216, v189
	v_cvt_f32_ubyte1_e32 v219, v189
	v_cvt_f32_ubyte0_e32 v218, v189
	v_pk_mul_f32 v[188:189], v[202:203], v[218:219]
	v_pk_mul_f32 v[186:187], v[186:187], v[216:217]
	v_pk_mul_f32 v[114:115], v[114:115], v[188:189]
	v_pk_mul_f32 v[116:117], v[116:117], v[186:187]
	v_cvt_f32_ubyte0_e32 v0, v182
	v_cvt_f32_ubyte1_e32 v186, v182
	v_cvt_f32_ubyte2_e32 v187, v182
	v_cvt_f32_ubyte3_e32 v188, v182
	v_cvt_f32_ubyte0_e32 v189, v183
	v_cvt_f32_ubyte1_e32 v202, v183
	v_cvt_f32_ubyte2_e32 v203, v183
	v_cvt_f32_ubyte3_e32 v215, v183
	v_rcp_iflag_f32_e32 v182, v0
	v_rcp_iflag_f32_e32 v183, v186
	v_rcp_iflag_f32_e32 v186, v187
	v_rcp_iflag_f32_e32 v187, v188
	v_rcp_iflag_f32_e32 v188, v189
	v_rcp_iflag_f32_e32 v189, v202
	v_rcp_iflag_f32_e32 v202, v203
	v_rcp_iflag_f32_e32 v203, v215
	v_cvt_f32_ubyte3_e32 v217, v178
	v_cvt_f32_ubyte2_e32 v216, v178
	v_cvt_f32_ubyte1_e32 v219, v178
	v_cvt_f32_ubyte0_e32 v218, v178
	v_pk_mul_f32 v[182:183], v[182:183], v[218:219]
	v_pk_mul_f32 v[186:187], v[186:187], v[216:217]
	v_pk_mul_f32 v[110:111], v[110:111], v[182:183]
	v_pk_mul_f32 v[112:113], v[112:113], v[186:187]
	v_cvt_f32_ubyte3_e32 v183, v179
	v_cvt_f32_ubyte2_e32 v182, v179
	v_cvt_f32_ubyte1_e32 v187, v179
	v_cvt_f32_ubyte0_e32 v186, v179
	v_pk_mul_f32 v[178:179], v[188:189], v[186:187]
	v_pk_mul_f32 v[182:183], v[202:203], v[182:183]
	v_pk_mul_f32 v[106:107], v[106:107], v[178:179]
	v_pk_mul_f32 v[108:109], v[108:109], v[182:183]
	v_cvt_f32_ubyte0_e32 v0, v184
	v_cvt_f32_ubyte1_e32 v179, v184
	v_cvt_f32_ubyte2_e32 v182, v184
	v_cvt_f32_ubyte3_e32 v183, v184
	v_rcp_iflag_f32_e32 v178, v0
	v_rcp_iflag_f32_e32 v179, v179
	v_rcp_iflag_f32_e32 v182, v182
	v_rcp_iflag_f32_e32 v183, v183
	v_cvt_f32_ubyte0_e32 v184, v185
	v_cvt_f32_ubyte1_e32 v186, v185
	v_cvt_f32_ubyte2_e32 v187, v185
	v_cvt_f32_ubyte3_e32 v188, v185
	v_rcp_iflag_f32_e32 v184, v184
	v_rcp_iflag_f32_e32 v185, v186
	v_rcp_iflag_f32_e32 v186, v187
	v_rcp_iflag_f32_e32 v187, v188
	v_cvt_f32_ubyte3_e32 v189, v180
	v_cvt_f32_ubyte2_e32 v188, v180
	v_cvt_f32_ubyte1_e32 v203, v180
	v_cvt_f32_ubyte0_e32 v202, v180
	v_pk_mul_f32 v[178:179], v[178:179], v[202:203]
	v_pk_mul_f32 v[182:183], v[182:183], v[188:189]
	v_pk_mul_f32 v[102:103], v[102:103], v[178:179]
	v_pk_mul_f32 v[104:105], v[104:105], v[182:183]
	v_cvt_f32_ubyte3_e32 v179, v181
	v_cvt_f32_ubyte2_e32 v178, v181
	v_cvt_f32_ubyte1_e32 v183, v181
	v_cvt_f32_ubyte0_e32 v182, v181
	v_pk_mul_f32 v[180:181], v[184:185], v[182:183]
	v_pk_mul_f32 v[178:179], v[186:187], v[178:179]
	v_pk_mul_f32 v[98:99], v[98:99], v[180:181]
	v_pk_mul_f32 v[100:101], v[100:101], v[178:179]
	v_cvt_f32_ubyte0_e32 v0, v174
	v_cvt_f32_ubyte1_e32 v178, v174
	v_cvt_f32_ubyte2_e32 v179, v174
	v_cvt_f32_ubyte3_e32 v180, v174
	v_cvt_f32_ubyte0_e32 v181, v175
	v_cvt_f32_ubyte1_e32 v182, v175
	v_cvt_f32_ubyte2_e32 v183, v175
	v_cvt_f32_ubyte3_e32 v184, v175
	v_rcp_iflag_f32_e32 v174, v0
	v_rcp_iflag_f32_e32 v175, v178
	v_rcp_iflag_f32_e32 v178, v179
	v_rcp_iflag_f32_e32 v179, v180
	v_rcp_iflag_f32_e32 v180, v181
;     __device__ __forceinline__ void mid(Acc& acc, const Unit& u, int s, int wr, int wc, int fr, int fq) const {
;     ...
;         for (int i = 0; i < 8; ++i) { const int ai = i >> 2, m = i & 3;
; #pragma unroll
;             for (int bj = 0; bj < 2; ++bj) {
;                 const u32x4 ga = G[i][0], gb = G[i][1];
;                 const u32x2 wa = bj == 0 ? (u32x2){ga.x, ga.y} : (u32x2){ga.z, ga.w}, wb = bj == 0 ? (u32x2){gb.x, gb.y} : (u32x2){gb.z, gb.w};
;                 float fa[8], fb[8]; gate_unpack8(wa, fa); gate_unpack8(wb, fb);
; #pragma unroll
;                 for (int e = 0; e < 8; ++e) fa[e] = fa[e] * __builtin_amdgcn_rcpf(fb[e]);
;                 f32x4& v0 = acc[ai][bj][m][0]; f32x4& v1 = acc[ai][bj][m][1];
;                 v0[0] *= fa[0]; v0[1] *= fa[1]; v0[2] *= fa[2]; v0[3] *= fa[3]; v1[0] *= fa[4]; v1[1] *= fa[5]; v1[2] *= fa[6]; v1[3] *= fa[7]; }
;             __builtin_amdgcn_sched_barrier(0); }
	v_rcp_iflag_f32_e32 v181, v182
	v_rcp_iflag_f32_e32 v182, v183
	v_rcp_iflag_f32_e32 v183, v184
	v_cvt_f32_ubyte3_e32 v185, v170
	v_cvt_f32_ubyte2_e32 v184, v170
	v_cvt_f32_ubyte1_e32 v187, v170
	v_cvt_f32_ubyte0_e32 v186, v170
	v_pk_mul_f32 v[174:175], v[174:175], v[186:187]
	v_pk_mul_f32 v[178:179], v[178:179], v[184:185]
	v_pk_mul_f32 v[94:95], v[94:95], v[174:175]
	v_pk_mul_f32 v[96:97], v[96:97], v[178:179]
	v_cvt_f32_ubyte3_e32 v175, v171
	v_cvt_f32_ubyte2_e32 v174, v171
	v_cvt_f32_ubyte1_e32 v179, v171
	v_cvt_f32_ubyte0_e32 v178, v171
	v_pk_mul_f32 v[170:171], v[180:181], v[178:179]
	v_pk_mul_f32 v[174:175], v[182:183], v[174:175]
	v_pk_mul_f32 v[90:91], v[90:91], v[170:171]
	v_pk_mul_f32 v[92:93], v[92:93], v[174:175]
	v_cvt_f32_ubyte0_e32 v0, v176
	v_cvt_f32_ubyte1_e32 v171, v176
	v_cvt_f32_ubyte2_e32 v174, v176
	v_cvt_f32_ubyte3_e32 v175, v176
	v_rcp_iflag_f32_e32 v170, v0
	v_rcp_iflag_f32_e32 v171, v171
	v_rcp_iflag_f32_e32 v174, v174
	v_rcp_iflag_f32_e32 v175, v175
	v_cvt_f32_ubyte0_e32 v176, v177
	v_cvt_f32_ubyte1_e32 v178, v177
	v_cvt_f32_ubyte2_e32 v179, v177
	v_cvt_f32_ubyte3_e32 v180, v177
	v_rcp_iflag_f32_e32 v176, v176
	v_rcp_iflag_f32_e32 v177, v178
	v_rcp_iflag_f32_e32 v178, v179
	v_rcp_iflag_f32_e32 v179, v180
	v_cvt_f32_ubyte3_e32 v181, v172
	v_cvt_f32_ubyte2_e32 v180, v172
	v_cvt_f32_ubyte1_e32 v183, v172
	v_cvt_f32_ubyte0_e32 v182, v172
	v_pk_mul_f32 v[170:171], v[170:171], v[182:183]
	v_pk_mul_f32 v[174:175], v[174:175], v[180:181]
	v_pk_mul_f32 v[86:87], v[86:87], v[170:171]
	v_pk_mul_f32 v[88:89], v[88:89], v[174:175]
	v_cvt_f32_ubyte3_e32 v171, v173
	v_cvt_f32_ubyte2_e32 v170, v173
	v_cvt_f32_ubyte1_e32 v175, v173
	v_cvt_f32_ubyte0_e32 v174, v173
	v_pk_mul_f32 v[172:173], v[176:177], v[174:175]
	v_pk_mul_f32 v[170:171], v[178:179], v[170:171]
	v_pk_mul_f32 v[82:83], v[82:83], v[172:173]
	v_pk_mul_f32 v[84:85], v[84:85], v[170:171]
	v_cvt_f32_ubyte0_e32 v0, v166
	v_cvt_f32_ubyte1_e32 v170, v166
	v_cvt_f32_ubyte2_e32 v171, v166
	v_cvt_f32_ubyte3_e32 v172, v166
	v_cvt_f32_ubyte0_e32 v173, v167
	v_cvt_f32_ubyte1_e32 v174, v167
	v_cvt_f32_ubyte2_e32 v175, v167
	v_cvt_f32_ubyte3_e32 v176, v167
	v_rcp_iflag_f32_e32 v166, v0
	v_rcp_iflag_f32_e32 v167, v170
	v_rcp_iflag_f32_e32 v170, v171
	v_rcp_iflag_f32_e32 v171, v172
	v_rcp_iflag_f32_e32 v172, v173
	v_rcp_iflag_f32_e32 v173, v174
	v_rcp_iflag_f32_e32 v174, v175
	v_rcp_iflag_f32_e32 v175, v176
	v_cvt_f32_ubyte3_e32 v177, v162
	v_cvt_f32_ubyte2_e32 v176, v162
	v_cvt_f32_ubyte1_e32 v179, v162
	v_cvt_f32_ubyte0_e32 v178, v162
	v_pk_mul_f32 v[166:167], v[166:167], v[178:179]
	v_pk_mul_f32 v[170:171], v[170:171], v[176:177]
	v_pk_mul_f32 v[78:79], v[78:79], v[166:167]
	v_pk_mul_f32 v[80:81], v[80:81], v[170:171]
	v_cvt_f32_ubyte3_e32 v167, v163
	v_cvt_f32_ubyte2_e32 v166, v163
	v_cvt_f32_ubyte1_e32 v171, v163
	v_cvt_f32_ubyte0_e32 v170, v163
	v_pk_mul_f32 v[162:163], v[172:173], v[170:171]
	v_pk_mul_f32 v[166:167], v[174:175], v[166:167]
	v_pk_mul_f32 v[74:75], v[74:75], v[162:163]
	v_pk_mul_f32 v[76:77], v[76:77], v[166:167]
	v_cvt_f32_ubyte0_e32 v0, v168
	v_cvt_f32_ubyte1_e32 v163, v168
	v_cvt_f32_ubyte2_e32 v166, v168
	v_cvt_f32_ubyte3_e32 v167, v168
	v_rcp_iflag_f32_e32 v162, v0
	v_rcp_iflag_f32_e32 v163, v163
	v_rcp_iflag_f32_e32 v166, v166
	v_rcp_iflag_f32_e32 v167, v167
	v_cvt_f32_ubyte0_e32 v168, v169
	v_cvt_f32_ubyte1_e32 v170, v169
	v_cvt_f32_ubyte2_e32 v171, v169
	v_cvt_f32_ubyte3_e32 v172, v169
	v_rcp_iflag_f32_e32 v168, v168
	v_rcp_iflag_f32_e32 v169, v170
	v_rcp_iflag_f32_e32 v170, v171
	v_rcp_iflag_f32_e32 v171, v172
	v_cvt_f32_ubyte3_e32 v173, v164
	v_cvt_f32_ubyte2_e32 v172, v164
	v_cvt_f32_ubyte1_e32 v175, v164
	v_cvt_f32_ubyte0_e32 v174, v164
	v_pk_mul_f32 v[162:163], v[162:163], v[174:175]
	v_pk_mul_f32 v[166:167], v[166:167], v[172:173]
	v_pk_mul_f32 v[70:71], v[70:71], v[162:163]
	v_pk_mul_f32 v[72:73], v[72:73], v[166:167]
	v_cvt_f32_ubyte3_e32 v163, v165
	v_cvt_f32_ubyte2_e32 v162, v165
	v_cvt_f32_ubyte1_e32 v167, v165
	v_cvt_f32_ubyte0_e32 v166, v165
	v_pk_mul_f32 v[164:165], v[168:169], v[166:167]
	v_pk_mul_f32 v[162:163], v[170:171], v[162:163]
	v_pk_mul_f32 v[66:67], v[66:67], v[164:165]
	v_pk_mul_f32 v[68:69], v[68:69], v[162:163]
	s_waitcnt vmcnt(6)
	v_cvt_f32_ubyte0_e32 v0, v158
	v_cvt_f32_ubyte1_e32 v162, v158
	v_cvt_f32_ubyte2_e32 v163, v158
	v_cvt_f32_ubyte3_e32 v164, v158
	v_cvt_f32_ubyte0_e32 v165, v159
	v_cvt_f32_ubyte1_e32 v166, v159
	v_cvt_f32_ubyte2_e32 v167, v159
	v_cvt_f32_ubyte3_e32 v168, v159
	v_rcp_iflag_f32_e32 v158, v0
	v_rcp_iflag_f32_e32 v159, v162
	v_rcp_iflag_f32_e32 v162, v163
	v_rcp_iflag_f32_e32 v163, v164
	v_rcp_iflag_f32_e32 v164, v165
	v_rcp_iflag_f32_e32 v165, v166
	v_rcp_iflag_f32_e32 v166, v167
	v_rcp_iflag_f32_e32 v167, v168
	v_cvt_f32_ubyte3_e32 v169, v154
	v_cvt_f32_ubyte2_e32 v168, v154
	v_cvt_f32_ubyte1_e32 v171, v154
	v_cvt_f32_ubyte0_e32 v170, v154
	v_pk_mul_f32 v[158:159], v[158:159], v[170:171]
	v_pk_mul_f32 v[162:163], v[162:163], v[168:169]
	v_pk_mul_f32 v[62:63], v[62:63], v[158:159]
	v_pk_mul_f32 v[64:65], v[64:65], v[162:163]
	v_cvt_f32_ubyte3_e32 v159, v155
	v_cvt_f32_ubyte2_e32 v158, v155
	v_cvt_f32_ubyte1_e32 v163, v155
	v_cvt_f32_ubyte0_e32 v162, v155
	v_pk_mul_f32 v[154:155], v[164:165], v[162:163]
	v_pk_mul_f32 v[158:159], v[166:167], v[158:159]
	v_pk_mul_f32 v[58:59], v[58:59], v[154:155]
	v_pk_mul_f32 v[60:61], v[60:61], v[158:159]
	v_cvt_f32_ubyte0_e32 v0, v160
	v_cvt_f32_ubyte1_e32 v155, v160
	v_cvt_f32_ubyte2_e32 v158, v160
	v_cvt_f32_ubyte3_e32 v159, v160
	v_rcp_iflag_f32_e32 v154, v0
	v_rcp_iflag_f32_e32 v155, v155
	v_rcp_iflag_f32_e32 v158, v158
	v_rcp_iflag_f32_e32 v159, v159
	v_cvt_f32_ubyte0_e32 v160, v161
	v_cvt_f32_ubyte1_e32 v162, v161
	v_cvt_f32_ubyte2_e32 v163, v161
	v_cvt_f32_ubyte3_e32 v164, v161
	v_rcp_iflag_f32_e32 v160, v160
	v_rcp_iflag_f32_e32 v161, v162
	v_rcp_iflag_f32_e32 v162, v163
	v_rcp_iflag_f32_e32 v163, v164
	v_cvt_f32_ubyte3_e32 v165, v156
	v_cvt_f32_ubyte2_e32 v164, v156
	v_cvt_f32_ubyte1_e32 v167, v156
	v_cvt_f32_ubyte0_e32 v166, v156
	v_pk_mul_f32 v[154:155], v[154:155], v[166:167]
	v_pk_mul_f32 v[158:159], v[158:159], v[164:165]
	v_pk_mul_f32 v[54:55], v[54:55], v[154:155]
	v_pk_mul_f32 v[56:57], v[56:57], v[158:159]
	v_cvt_f32_ubyte3_e32 v155, v157
	v_cvt_f32_ubyte2_e32 v154, v157
	v_cvt_f32_ubyte1_e32 v159, v157
	v_cvt_f32_ubyte0_e32 v158, v157
	v_pk_mul_f32 v[156:157], v[160:161], v[158:159]
	v_pk_mul_f32 v[154:155], v[162:163], v[154:155]
	v_pk_mul_f32 v[50:51], v[50:51], v[156:157]
	v_pk_mul_f32 v[52:53], v[52:53], v[154:155]
	s_waitcnt vmcnt(4)
;     __device__ __forceinline__ void mid(Acc& acc, const Unit& u, int s, int wr, int wc, int fr, int fq) const {
;     ...
;         for (int i = 0; i < 8; ++i) { const int ai = i >> 2, m = i & 3;
; #pragma unroll
;             for (int bj = 0; bj < 2; ++bj) {
;                 const u32x4 ga = G[i][0], gb = G[i][1];
;                 const u32x2 wa = bj == 0 ? (u32x2){ga.x, ga.y} : (u32x2){ga.z, ga.w}, wb = bj == 0 ? (u32x2){gb.x, gb.y} : (u32x2){gb.z, gb.w};
;                 float fa[8], fb[8]; gate_unpack8(wa, fa); gate_unpack8(wb, fb);
; #pragma unroll
;                 for (int e = 0; e < 8; ++e) fa[e] = fa[e] * __builtin_amdgcn_rcpf(fb[e]);
;                 f32x4& v0 = acc[ai][bj][m][0]; f32x4& v1 = acc[ai][bj][m][1];
;                 v0[0] *= fa[0]; v0[1] *= fa[1]; v0[2] *= fa[2]; v0[3] *= fa[3]; v1[0] *= fa[4]; v1[1] *= fa[5]; v1[2] *= fa[6]; v1[3] *= fa[7]; }
;             __builtin_amdgcn_sched_barrier(0); }
	v_cvt_f32_ubyte0_e32 v0, v150
	v_cvt_f32_ubyte1_e32 v154, v150
	v_cvt_f32_ubyte2_e32 v155, v150
	v_cvt_f32_ubyte3_e32 v156, v150
	v_cvt_f32_ubyte0_e32 v157, v151
	v_cvt_f32_ubyte1_e32 v158, v151
	v_cvt_f32_ubyte2_e32 v159, v151
	v_cvt_f32_ubyte3_e32 v160, v151
	v_rcp_iflag_f32_e32 v150, v0
	v_rcp_iflag_f32_e32 v151, v154
	v_rcp_iflag_f32_e32 v154, v155
	v_rcp_iflag_f32_e32 v155, v156
	v_rcp_iflag_f32_e32 v156, v157
	v_rcp_iflag_f32_e32 v157, v158
	v_rcp_iflag_f32_e32 v158, v159
	v_rcp_iflag_f32_e32 v159, v160
	v_cvt_f32_ubyte3_e32 v161, v146
	v_cvt_f32_ubyte2_e32 v160, v146
	v_cvt_f32_ubyte1_e32 v163, v146
	v_cvt_f32_ubyte0_e32 v162, v146
	v_pk_mul_f32 v[150:151], v[150:151], v[162:163]
	v_pk_mul_f32 v[154:155], v[154:155], v[160:161]
	v_pk_mul_f32 v[46:47], v[46:47], v[150:151]
	v_pk_mul_f32 v[48:49], v[48:49], v[154:155]
	v_cvt_f32_ubyte3_e32 v151, v147
	v_cvt_f32_ubyte2_e32 v150, v147
	v_cvt_f32_ubyte1_e32 v155, v147
	v_cvt_f32_ubyte0_e32 v154, v147
	v_pk_mul_f32 v[146:147], v[156:157], v[154:155]
	v_pk_mul_f32 v[150:151], v[158:159], v[150:151]
	v_pk_mul_f32 v[42:43], v[42:43], v[146:147]
	v_pk_mul_f32 v[44:45], v[44:45], v[150:151]
	v_cvt_f32_ubyte0_e32 v0, v152
	v_cvt_f32_ubyte1_e32 v147, v152
	v_cvt_f32_ubyte2_e32 v150, v152
	v_cvt_f32_ubyte3_e32 v151, v152
	v_rcp_iflag_f32_e32 v146, v0
	v_rcp_iflag_f32_e32 v147, v147
	v_rcp_iflag_f32_e32 v150, v150
	v_rcp_iflag_f32_e32 v151, v151
	v_cvt_f32_ubyte0_e32 v152, v153
	v_cvt_f32_ubyte1_e32 v154, v153
	v_cvt_f32_ubyte2_e32 v155, v153
	v_cvt_f32_ubyte3_e32 v156, v153
	v_rcp_iflag_f32_e32 v152, v152
	v_rcp_iflag_f32_e32 v153, v154
	v_rcp_iflag_f32_e32 v154, v155
	v_rcp_iflag_f32_e32 v155, v156
	v_cvt_f32_ubyte3_e32 v157, v148
	v_cvt_f32_ubyte2_e32 v156, v148
	v_cvt_f32_ubyte1_e32 v159, v148
	v_cvt_f32_ubyte0_e32 v158, v148
	v_pk_mul_f32 v[146:147], v[146:147], v[158:159]
	v_pk_mul_f32 v[150:151], v[150:151], v[156:157]
	v_pk_mul_f32 v[38:39], v[38:39], v[146:147]
	v_pk_mul_f32 v[40:41], v[40:41], v[150:151]
	v_cvt_f32_ubyte3_e32 v147, v149
	v_cvt_f32_ubyte2_e32 v146, v149
	v_cvt_f32_ubyte1_e32 v151, v149
	v_cvt_f32_ubyte0_e32 v150, v149
	v_pk_mul_f32 v[148:149], v[152:153], v[150:151]
	v_pk_mul_f32 v[146:147], v[154:155], v[146:147]
	v_pk_mul_f32 v[34:35], v[34:35], v[148:149]
	v_pk_mul_f32 v[36:37], v[36:37], v[146:147]
	s_waitcnt vmcnt(2)
	v_cvt_f32_ubyte0_e32 v0, v142
	v_cvt_f32_ubyte1_e32 v146, v142
	v_cvt_f32_ubyte2_e32 v147, v142
	v_cvt_f32_ubyte3_e32 v148, v142
	v_cvt_f32_ubyte0_e32 v149, v143
	v_cvt_f32_ubyte1_e32 v150, v143
	v_cvt_f32_ubyte2_e32 v151, v143
	v_cvt_f32_ubyte3_e32 v152, v143
	v_rcp_iflag_f32_e32 v142, v0
	v_rcp_iflag_f32_e32 v143, v146
	v_rcp_iflag_f32_e32 v146, v147
	v_rcp_iflag_f32_e32 v147, v148
	v_rcp_iflag_f32_e32 v148, v149
	v_rcp_iflag_f32_e32 v149, v150
	v_rcp_iflag_f32_e32 v150, v151
	v_rcp_iflag_f32_e32 v151, v152
	v_cvt_f32_ubyte3_e32 v153, v138
	v_cvt_f32_ubyte2_e32 v152, v138
	v_cvt_f32_ubyte1_e32 v155, v138
	v_cvt_f32_ubyte0_e32 v154, v138
	v_pk_mul_f32 v[142:143], v[142:143], v[154:155]
	v_pk_mul_f32 v[146:147], v[146:147], v[152:153]
	v_pk_mul_f32 v[30:31], v[30:31], v[142:143]
	v_pk_mul_f32 v[32:33], v[32:33], v[146:147]
	v_cvt_f32_ubyte3_e32 v143, v139
	v_cvt_f32_ubyte2_e32 v142, v139
	v_cvt_f32_ubyte1_e32 v147, v139
	v_cvt_f32_ubyte0_e32 v146, v139
	v_pk_mul_f32 v[138:139], v[148:149], v[146:147]
	v_pk_mul_f32 v[142:143], v[150:151], v[142:143]
	v_pk_mul_f32 v[22:23], v[22:23], v[138:139]
	v_pk_mul_f32 v[24:25], v[24:25], v[142:143]
	v_cvt_f32_ubyte0_e32 v0, v144
	v_cvt_f32_ubyte1_e32 v139, v144
	v_cvt_f32_ubyte2_e32 v142, v144
	v_cvt_f32_ubyte3_e32 v143, v144
	v_rcp_iflag_f32_e32 v138, v0
	v_rcp_iflag_f32_e32 v139, v139
	v_rcp_iflag_f32_e32 v142, v142
	v_rcp_iflag_f32_e32 v143, v143
	v_cvt_f32_ubyte0_e32 v144, v145
	v_cvt_f32_ubyte1_e32 v146, v145
	v_cvt_f32_ubyte2_e32 v147, v145
	v_cvt_f32_ubyte3_e32 v148, v145
	v_rcp_iflag_f32_e32 v144, v144
	v_rcp_iflag_f32_e32 v145, v146
	v_rcp_iflag_f32_e32 v146, v147
	v_rcp_iflag_f32_e32 v147, v148
	v_cvt_f32_ubyte3_e32 v149, v140
	v_cvt_f32_ubyte2_e32 v148, v140
	v_cvt_f32_ubyte1_e32 v151, v140
	v_cvt_f32_ubyte0_e32 v150, v140
	v_pk_mul_f32 v[138:139], v[138:139], v[150:151]
	v_pk_mul_f32 v[142:143], v[142:143], v[148:149]
	v_pk_mul_f32 v[26:27], v[26:27], v[138:139]
	v_pk_mul_f32 v[28:29], v[28:29], v[142:143]
	v_cvt_f32_ubyte3_e32 v139, v141
	v_cvt_f32_ubyte2_e32 v138, v141
	v_cvt_f32_ubyte1_e32 v143, v141
	v_cvt_f32_ubyte0_e32 v142, v141
	v_pk_mul_f32 v[140:141], v[144:145], v[142:143]
	v_pk_mul_f32 v[138:139], v[146:147], v[138:139]
	v_pk_mul_f32 v[18:19], v[18:19], v[140:141]
	v_pk_mul_f32 v[20:21], v[20:21], v[138:139]
	s_waitcnt vmcnt(0)
	v_cvt_f32_ubyte0_e32 v0, v134
	v_cvt_f32_ubyte1_e32 v138, v134
	v_cvt_f32_ubyte2_e32 v139, v134
	v_cvt_f32_ubyte3_e32 v140, v134
	v_cvt_f32_ubyte0_e32 v141, v135
	v_cvt_f32_ubyte1_e32 v142, v135
	v_cvt_f32_ubyte2_e32 v143, v135
	v_cvt_f32_ubyte3_e32 v144, v135
	v_rcp_iflag_f32_e32 v134, v0
	v_rcp_iflag_f32_e32 v135, v138
	v_rcp_iflag_f32_e32 v138, v139
	v_rcp_iflag_f32_e32 v139, v140
	v_rcp_iflag_f32_e32 v140, v141
	v_rcp_iflag_f32_e32 v141, v142
	v_rcp_iflag_f32_e32 v142, v143
	v_rcp_iflag_f32_e32 v143, v144
	v_cvt_f32_ubyte3_e32 v145, v130
	v_cvt_f32_ubyte2_e32 v144, v130
	v_cvt_f32_ubyte1_e32 v147, v130
	v_cvt_f32_ubyte0_e32 v146, v130
	v_pk_mul_f32 v[134:135], v[134:135], v[146:147]
	v_pk_mul_f32 v[138:139], v[138:139], v[144:145]
	v_pk_mul_f32 v[14:15], v[14:15], v[134:135]
	v_pk_mul_f32 v[16:17], v[16:17], v[138:139]
	v_cvt_f32_ubyte3_e32 v135, v131
	v_cvt_f32_ubyte2_e32 v134, v131
	v_cvt_f32_ubyte1_e32 v139, v131
	v_cvt_f32_ubyte0_e32 v138, v131
	v_pk_mul_f32 v[130:131], v[140:141], v[138:139]
	v_pk_mul_f32 v[134:135], v[142:143], v[134:135]
	v_pk_mul_f32 v[6:7], v[6:7], v[130:131]
	v_pk_mul_f32 v[8:9], v[8:9], v[134:135]
	v_cvt_f32_ubyte0_e32 v0, v136
	v_cvt_f32_ubyte1_e32 v131, v136
	v_cvt_f32_ubyte2_e32 v134, v136
	v_cvt_f32_ubyte3_e32 v135, v136
	v_rcp_iflag_f32_e32 v130, v0
	v_rcp_iflag_f32_e32 v131, v131
	v_rcp_iflag_f32_e32 v134, v134
	v_rcp_iflag_f32_e32 v135, v135
	v_cvt_f32_ubyte0_e32 v136, v137
	v_cvt_f32_ubyte1_e32 v138, v137
	v_cvt_f32_ubyte2_e32 v139, v137
	v_cvt_f32_ubyte3_e32 v140, v137
	v_rcp_iflag_f32_e32 v136, v136
	v_rcp_iflag_f32_e32 v137, v138
	v_rcp_iflag_f32_e32 v138, v139
	v_rcp_iflag_f32_e32 v139, v140
	v_cvt_f32_ubyte3_e32 v141, v132
	v_cvt_f32_ubyte2_e32 v140, v132
	v_cvt_f32_ubyte1_e32 v143, v132
	v_cvt_f32_ubyte0_e32 v142, v132
	v_pk_mul_f32 v[130:131], v[130:131], v[142:143]
	v_pk_mul_f32 v[134:135], v[134:135], v[140:141]
	v_pk_mul_f32 v[10:11], v[10:11], v[130:131]
	v_pk_mul_f32 v[12:13], v[12:13], v[134:135]
	v_cvt_f32_ubyte3_e32 v131, v133
	v_cvt_f32_ubyte2_e32 v130, v133
	v_cvt_f32_ubyte1_e32 v135, v133
	v_cvt_f32_ubyte0_e32 v134, v133
	v_pk_mul_f32 v[132:133], v[136:137], v[134:135]
	v_pk_mul_f32 v[130:131], v[138:139], v[130:131]
	v_pk_mul_f32 v[2:3], v[2:3], v[132:133]
	v_pk_mul_f32 v[4:5], v[4:5], v[130:131]

; #define PG8_STAGE(bufoff, gbase, voff) do { _Pragma("unroll") for (int _i = 0; _i < 2; ++_i) \
;         __builtin_amdgcn_global_load_lds((const unsigned*)((const char*)(gbase) + (voff)[_i]), (LAS unsigned*)(lds + (bufoff) + ldsw + _i * 8192), 16, 0, 0); } while (0)
; #define PG8_LDA(dst, b, h) do { _Pragma("unroll") for (int m = 0; m < 4; ++m) _Pragma("unroll") for (int k = 0; k < 2; ++k) dst[m][k] = *(const LAS bf16x8*)(lds + PG8_SA(b, h) + aoffk[k] + m * 2048); } while (0)
; #define PG8_BAR __builtin_amdgcn_s_barrier()
; template <class Epi, class Sched, class GemmT>
; __device__ __forceinline__ void gemm_phase(LAS unsigned char* lds, const GemmT& g, const Sched& S, const Epi& E, const int wid) {
;     ...
;             for (int t = 0; t < nt; t += 2) {
;                 const bool last = (t == nt - 2);
;                 const char* a1 = cA + (size_t)(t + 1) * kstep;
;                 const char* a2 = last ? ns.A : cA + (size_t)(t + 2) * kstep; const char* b2 = last ? ns.B : cB + (size_t)(t + 2) * kstep;
;                 const char* a3 = a2 + kstep; const char* b3 = b2 + kstep;
;                 unsigned vA2[2], vB2[2];
; #pragma unroll
;                 for (int i = 0; i < 2; ++i) { vA2[i] = last ? nvA[i] : voffA[i]; vB2[i] = last ? nvB[i] : voffB[i]; }
;                 const size_t hA2 = last ? nhA : hstepA, hB2 = last ? nhB : hstepB;
;                 PG8_LDB(B0, 0, 0); PG8_LDB(B1, 0, 1); PG8_SCHED; PG8_LDA(At, 0, 0); PG8_STAGE(PG8_SA(1, 1), a1 + hstepA, voffA);
;                 PG8_WAIT_V(8); PG8_WAIT_L(0); PG8_BAR; PG8_MMA(0, 0, At, B0); PG8_MMA(0, 1, At, B1); PG8_BAR; PG8_SCHED;
;                 PG8_LDA(At, 0, 1); PG8_STAGE(PG8_SB(0, 0), b2, vB2); PG8_STAGE(PG8_SB(0, 1), b2 + hB2, vB2); PG8_STAGE(PG8_SA(0, 0), a2, vA2);
;                 PG8_WAIT_V(8); PG8_WAIT_L(0); PG8_BAR; PG8_MMA(1, 0, At, B0); PG8_MMA(1, 1, At, B1); PG8_BAR; PG8_SCHED;
;                 PG8_LDB(B0, 1, 0); PG8_LDB(B1, 1, 1); PG8_SCHED; PG8_LDA(At, 1, 0); PG8_STAGE(PG8_SA(0, 1), a2 + hA2, vA2);
;                 PG8_WAIT_V(8); PG8_WAIT_L(0); PG8_BAR; PG8_MMA(0, 0, At, B0); PG8_MMA(0, 1, At, B1); PG8_BAR; PG8_SCHED;
;                 PG8_LDA(At, 1, 1); PG8_STAGE(PG8_SB(1, 0), b3, vB2); PG8_STAGE(PG8_SB(1, 1), b3 + hB2, vB2); PG8_STAGE(PG8_SA(1, 0), a3, vA2);
;                 PG8_WAIT_V(8); PG8_WAIT_L(0); PG8_BAR; PG8_MMA(1, 0, At, B0); PG8_MMA(1, 1, At, B1); PG8_BAR; PG8_SCHED;
.LBB0_846:
	ds_read_b128 v[128:131], v194
	ds_read_b128 v[132:135], v195
	ds_read_b128 v[136:139], v196
	ds_read_b128 v[140:143], v197
	ds_read_b128 v[144:147], v198
	ds_read_b128 v[148:151], v199
	ds_read_b128 v[152:155], v200
	ds_read_b128 v[168:171], v201
	s_add_u32 s44, s42, 0xfff00080
	s_addc_u32 s45, s43, -1
	s_cmp_eq_u32 s62, 60
	s_cselect_b32 s51, s37, s45
	s_cselect_b32 s50, s36, s44
	s_cselect_b32 s45, s59, s61
	s_cselect_b32 s44, s41, s60
	v_lshl_add_u64 v[188:189], s[42:43], 0, v[156:157]
	s_add_i32 m0, s14, 0xc000
	ds_read_b128 v[172:175], v202
	ds_read_b128 v[176:179], v202 offset:2048
	ds_read_b128 v[180:183], v203
	ds_read_b128 v[184:187], v203 offset:2048
	ds_read_b128 v[208:211], v202 offset:4096
	ds_read_b128 v[212:215], v202 offset:6144
	ds_read_b128 v[216:219], v203 offset:4096
	ds_read_b128 v[220:223], v203 offset:6144
	global_load_lds_dwordx4 v[188:189], off
	v_lshl_add_u64 v[188:189], s[42:43], 0, v[160:161]
	s_add_i32 m0, s14, 0xe000
	s_nop 0
	global_load_lds_dwordx4 v[188:189], off
	s_waitcnt vmcnt(8)
	s_waitcnt lgkmcnt(0)
	s_waitcnt lgkmcnt(0)
	v_mfma_f32_16x16x32_bf16 v[124:127], v[128:131], v[172:175], v[124:127]
	v_mfma_f32_16x16x32_bf16 v[124:127], v[132:135], v[180:183], v[124:127]
	v_mfma_f32_16x16x32_bf16 v[120:123], v[140:143], v[180:183], v[120:123]
	v_mfma_f32_16x16x32_bf16 v[120:123], v[136:139], v[172:175], v[120:123]
	v_mfma_f32_16x16x32_bf16 v[104:107], v[136:139], v[176:179], v[104:107]
	v_mfma_f32_16x16x32_bf16 v[104:107], v[140:143], v[184:187], v[104:107]
	v_mfma_f32_16x16x32_bf16 v[108:111], v[132:135], v[184:187], v[108:111]
	v_mfma_f32_16x16x32_bf16 v[108:111], v[128:131], v[176:179], v[108:111]
	s_barrier
	s_setprio 3
	v_mfma_f32_16x16x32_bf16 v[92:95], v[128:131], v[208:211], v[92:95]
	v_mfma_f32_16x16x32_bf16 v[92:95], v[132:135], v[216:219], v[92:95]
	v_mfma_f32_16x16x32_bf16 v[88:91], v[140:143], v[216:219], v[88:91]
	v_mfma_f32_16x16x32_bf16 v[88:91], v[136:139], v[208:211], v[88:91]
	v_mfma_f32_16x16x32_bf16 v[72:75], v[136:139], v[212:215], v[72:75]
	v_mfma_f32_16x16x32_bf16 v[72:75], v[140:143], v[220:223], v[72:75]
	v_mfma_f32_16x16x32_bf16 v[76:79], v[132:135], v[220:223], v[76:79]
	v_mfma_f32_16x16x32_bf16 v[76:79], v[128:131], v[212:215], v[76:79]
	s_setprio 0
	s_setprio 3
	v_mfma_f32_16x16x32_bf16 v[116:119], v[144:147], v[172:175], v[116:119]
	v_mfma_f32_16x16x32_bf16 v[116:119], v[148:151], v[180:183], v[116:119]
	v_mfma_f32_16x16x32_bf16 v[112:115], v[168:171], v[180:183], v[112:115]
	v_mfma_f32_16x16x32_bf16 v[112:115], v[152:155], v[172:175], v[112:115]
	v_mfma_f32_16x16x32_bf16 v[96:99], v[152:155], v[176:179], v[96:99]
	v_mfma_f32_16x16x32_bf16 v[96:99], v[168:171], v[184:187], v[96:99]
	v_mfma_f32_16x16x32_bf16 v[100:103], v[148:151], v[184:187], v[100:103]
	v_mfma_f32_16x16x32_bf16 v[100:103], v[144:147], v[176:179], v[100:103]
	v_mfma_f32_16x16x32_bf16 v[84:87], v[144:147], v[208:211], v[84:87]
	v_mfma_f32_16x16x32_bf16 v[84:87], v[148:151], v[216:219], v[84:87]
	v_mfma_f32_16x16x32_bf16 v[80:83], v[168:171], v[216:219], v[80:83]
	v_mfma_f32_16x16x32_bf16 v[80:83], v[152:155], v[208:211], v[80:83]
	v_mfma_f32_16x16x32_bf16 v[64:67], v[152:155], v[212:215], v[64:67]
	v_mfma_f32_16x16x32_bf16 v[64:67], v[168:171], v[220:223], v[64:67]
	v_mfma_f32_16x16x32_bf16 v[68:71], v[148:151], v[220:223], v[68:71]
	v_mfma_f32_16x16x32_bf16 v[68:71], v[144:147], v[212:215], v[68:71]
	s_setprio 0
	s_barrier
	s_add_i32 s48, s54, s68
	v_lshl_add_u64 v[188:189], s[44:45], 0, v[158:159]
	s_mov_b32 m0, s48
	ds_read_b128 v[172:175], v202 offset:16384
	ds_read_b128 v[176:179], v202 offset:18432
	ds_read_b128 v[180:183], v203 offset:16384
	ds_read_b128 v[184:187], v203 offset:18432
	ds_read_b128 v[208:211], v202 offset:20480
	ds_read_b128 v[212:215], v202 offset:22528
	ds_read_b128 v[216:219], v203 offset:20480
	ds_read_b128 v[220:223], v203 offset:22528
	global_load_lds_dwordx4 v[188:189], off
	s_add_i32 m0, s48, 0x2000
	s_add_u32 s48, s44, 0x100000
	v_lshl_add_u64 v[224:225], s[44:45], 0, v[162:163]
	s_addc_u32 s49, s45, 0
	s_add_i32 s63, s55, s68
	global_load_lds_dwordx4 v[224:225], off
	v_lshl_add_u64 v[226:227], s[48:49], 0, v[158:159]
	s_mov_b32 m0, s63
	v_lshl_add_u64 v[230:231], s[50:51], 0, v[160:161]
	global_load_lds_dwordx4 v[226:227], off
	v_lshl_add_u64 v[226:227], s[48:49], 0, v[162:163]
	s_add_i32 m0, s63, 0x2000
	s_nop 0
	global_load_lds_dwordx4 v[226:227], off
	v_lshl_add_u64 v[226:227], s[50:51], 0, v[156:157]
	s_mov_b32 m0, s14
	s_nop 0
	global_load_lds_dwordx4 v[226:227], off
	s_mov_b32 m0, s15
	s_nop 0
	global_load_lds_dwordx4 v[230:231], off
	s_waitcnt vmcnt(8)
	s_waitcnt lgkmcnt(0)
	s_waitcnt lgkmcnt(0)
	v_mfma_f32_16x16x32_bf16 v[52:55], v[128:131], v[172:175], v[52:55]
	v_mfma_f32_16x16x32_bf16 v[52:55], v[132:135], v[180:183], v[52:55]
	v_mfma_f32_16x16x32_bf16 v[48:51], v[140:143], v[180:183], v[48:51]
	v_mfma_f32_16x16x32_bf16 v[48:51], v[136:139], v[172:175], v[48:51]
	v_mfma_f32_16x16x32_bf16 v[32:35], v[136:139], v[176:179], v[32:35]
	v_mfma_f32_16x16x32_bf16 v[32:35], v[140:143], v[184:187], v[32:35]
	v_mfma_f32_16x16x32_bf16 v[36:39], v[132:135], v[184:187], v[36:39]
	v_mfma_f32_16x16x32_bf16 v[36:39], v[128:131], v[176:179], v[36:39]
	s_barrier
; #define PG8_STAGE(bufoff, gbase, voff) do { _Pragma("unroll") for (int _i = 0; _i < 2; ++_i) \
;         __builtin_amdgcn_global_load_lds((const unsigned*)((const char*)(gbase) + (voff)[_i]), (LAS unsigned*)(lds + (bufoff) + ldsw + _i * 8192), 16, 0, 0); } while (0)
; #define PG8_LDA(dst, b, h) do { _Pragma("unroll") for (int m = 0; m < 4; ++m) _Pragma("unroll") for (int k = 0; k < 2; ++k) dst[m][k] = *(const LAS bf16x8*)(lds + PG8_SA(b, h) + aoffk[k] + m * 2048); } while (0)
; #define PG8_LDB(dst, b, h) do { _Pragma("unroll") for (int n = 0; n < 2; ++n) _Pragma("unroll") for (int k = 0; k < 2; ++k) dst[n][k] = *(const LAS bf16x8*)(lds + PG8_SB(b, h) + boffk[k] + n * 2048); } while (0)
; #define PG8_WAIT_V(n) asm volatile("s_waitcnt vmcnt(" #n ")" ::: "memory")
; #define PG8_WAIT_L(n) asm volatile("s_waitcnt lgkmcnt(" #n ")" ::: "memory")
; #define PG8_BAR __builtin_amdgcn_s_barrier()
; #define PG8_SCHED __builtin_amdgcn_sched_barrier(0)
; template <class Epi, class Sched, class GemmT>
; __device__ __forceinline__ void gemm_phase(LAS unsigned char* lds, const GemmT& g, const Sched& S, const Epi& E, const int wid) {
;     ...
;                 PG8_LDB(B0, 0, 0); PG8_LDB(B1, 0, 1); PG8_SCHED; PG8_LDA(At, 0, 0); PG8_STAGE(PG8_SA(1, 1), a1 + hstepA, voffA);
;                 PG8_WAIT_V(8); PG8_WAIT_L(0); PG8_BAR; PG8_MMA(0, 0, At, B0); PG8_MMA(0, 1, At, B1); PG8_BAR; PG8_SCHED;
;                 PG8_LDA(At, 0, 1); PG8_STAGE(PG8_SB(0, 0), b2, vB2); PG8_STAGE(PG8_SB(0, 1), b2 + hB2, vB2); PG8_STAGE(PG8_SA(0, 0), a2, vA2);
;                 PG8_WAIT_V(8); PG8_WAIT_L(0); PG8_BAR; PG8_MMA(1, 0, At, B0); PG8_MMA(1, 1, At, B1); PG8_BAR; PG8_SCHED;
;                 PG8_LDB(B0, 1, 0); PG8_LDB(B1, 1, 1); PG8_SCHED; PG8_LDA(At, 1, 0); PG8_STAGE(PG8_SA(0, 1), a2 + hA2, vA2);
;                 PG8_WAIT_V(8); PG8_WAIT_L(0); PG8_BAR; PG8_MMA(0, 0, At, B0); PG8_MMA(0, 1, At, B1); PG8_BAR; PG8_SCHED;
;                 PG8_LDA(At, 1, 1); PG8_STAGE(PG8_SB(1, 0), b3, vB2); PG8_STAGE(PG8_SB(1, 1), b3 + hB2, vB2); PG8_STAGE(PG8_SA(1, 0), a3, vA2);
	s_setprio 3
	v_mfma_f32_16x16x32_bf16 v[20:23], v[128:131], v[208:211], v[20:23]
	v_mfma_f32_16x16x32_bf16 v[20:23], v[132:135], v[216:219], v[20:23]
	v_mfma_f32_16x16x32_bf16 v[16:19], v[140:143], v[216:219], v[16:19]
	v_mfma_f32_16x16x32_bf16 v[16:19], v[136:139], v[208:211], v[16:19]
	v_mfma_f32_16x16x32_bf16 v[0:3], v[136:139], v[212:215], v[0:3]
	v_mfma_f32_16x16x32_bf16 v[0:3], v[140:143], v[220:223], v[0:3]
	v_mfma_f32_16x16x32_bf16 v[4:7], v[132:135], v[220:223], v[4:7]
	v_mfma_f32_16x16x32_bf16 v[4:7], v[128:131], v[212:215], v[4:7]
	s_setprio 0
	s_setprio 3
	v_mfma_f32_16x16x32_bf16 v[60:63], v[144:147], v[172:175], v[60:63]
	v_mfma_f32_16x16x32_bf16 v[60:63], v[148:151], v[180:183], v[60:63]
	v_mfma_f32_16x16x32_bf16 v[56:59], v[168:171], v[180:183], v[56:59]
	v_mfma_f32_16x16x32_bf16 v[56:59], v[152:155], v[172:175], v[56:59]
	v_mfma_f32_16x16x32_bf16 v[40:43], v[152:155], v[176:179], v[40:43]
	v_mfma_f32_16x16x32_bf16 v[40:43], v[168:171], v[184:187], v[40:43]
	v_mfma_f32_16x16x32_bf16 v[44:47], v[148:151], v[184:187], v[44:47]
	v_mfma_f32_16x16x32_bf16 v[44:47], v[144:147], v[176:179], v[44:47]
	v_mfma_f32_16x16x32_bf16 v[28:31], v[144:147], v[208:211], v[28:31]
	v_mfma_f32_16x16x32_bf16 v[28:31], v[148:151], v[216:219], v[28:31]
	v_mfma_f32_16x16x32_bf16 v[24:27], v[168:171], v[216:219], v[24:27]
	v_mfma_f32_16x16x32_bf16 v[24:27], v[152:155], v[208:211], v[24:27]
	v_mfma_f32_16x16x32_bf16 v[8:11], v[152:155], v[212:215], v[8:11]
	v_mfma_f32_16x16x32_bf16 v[8:11], v[168:171], v[220:223], v[8:11]
	v_mfma_f32_16x16x32_bf16 v[12:15], v[148:151], v[220:223], v[12:15]
	v_mfma_f32_16x16x32_bf16 v[12:15], v[144:147], v[212:215], v[12:15]
	s_setprio 0
	s_barrier
	s_add_i32 s63, 0, 0x18000
	s_add_i32 s64, 0, 0x1c000
	v_add_u32_e32 v128, s63, v191
	v_add_u32_e32 v132, s63, v192
	v_add_u32_e32 v144, s64, v191
	v_add_u32_e32 v148, s64, v192
	ds_read_b128 v[128:131], v128
	ds_read_b128 v[132:135], v132
	ds_read_b128 v[136:139], v204
	ds_read_b128 v[140:143], v205
	ds_read_b128 v[144:147], v144
	ds_read_b128 v[148:151], v148
	ds_read_b128 v[152:155], v206
	ds_read_b128 v[168:171], v207
	s_add_u32 s48, s50, 0x100000
	s_addc_u32 s49, s51, 0
	s_mov_b32 m0, s22
	v_lshl_add_u64 v[232:233], s[48:49], 0, v[156:157]
	ds_read_b128 v[172:175], v202 offset:32768
	ds_read_b128 v[176:179], v202 offset:34816
	ds_read_b128 v[180:183], v203 offset:32768
	ds_read_b128 v[184:187], v203 offset:34816
	ds_read_b128 v[208:211], v202 offset:36864
	ds_read_b128 v[212:215], v202 offset:38912
	ds_read_b128 v[216:219], v203 offset:36864
	ds_read_b128 v[220:223], v203 offset:38912
	global_load_lds_dwordx4 v[232:233], off
	v_lshl_add_u64 v[232:233], s[48:49], 0, v[160:161]
	s_mov_b32 m0, s23
	s_nop 0
	global_load_lds_dwordx4 v[232:233], off
	s_waitcnt vmcnt(8)
	s_waitcnt lgkmcnt(0)
	s_waitcnt lgkmcnt(0)
	v_mfma_f32_16x16x32_bf16 v[124:127], v[128:131], v[172:175], v[124:127]
	v_mfma_f32_16x16x32_bf16 v[124:127], v[132:135], v[180:183], v[124:127]
	v_mfma_f32_16x16x32_bf16 v[120:123], v[140:143], v[180:183], v[120:123]
	v_mfma_f32_16x16x32_bf16 v[120:123], v[136:139], v[172:175], v[120:123]
	v_mfma_f32_16x16x32_bf16 v[104:107], v[136:139], v[176:179], v[104:107]
	v_mfma_f32_16x16x32_bf16 v[104:107], v[140:143], v[184:187], v[104:107]
	v_mfma_f32_16x16x32_bf16 v[108:111], v[132:135], v[184:187], v[108:111]
	v_mfma_f32_16x16x32_bf16 v[108:111], v[128:131], v[176:179], v[108:111]
	s_barrier
	s_setprio 3
	v_mfma_f32_16x16x32_bf16 v[92:95], v[128:131], v[208:211], v[92:95]
	v_mfma_f32_16x16x32_bf16 v[92:95], v[132:135], v[216:219], v[92:95]
	v_mfma_f32_16x16x32_bf16 v[88:91], v[140:143], v[216:219], v[88:91]
	v_mfma_f32_16x16x32_bf16 v[88:91], v[136:139], v[208:211], v[88:91]
	v_mfma_f32_16x16x32_bf16 v[72:75], v[136:139], v[212:215], v[72:75]
	v_mfma_f32_16x16x32_bf16 v[72:75], v[140:143], v[220:223], v[72:75]
	v_mfma_f32_16x16x32_bf16 v[76:79], v[132:135], v[220:223], v[76:79]
	v_mfma_f32_16x16x32_bf16 v[76:79], v[128:131], v[212:215], v[76:79]
	s_setprio 0
	s_setprio 3
	v_mfma_f32_16x16x32_bf16 v[116:119], v[144:147], v[172:175], v[116:119]
	v_mfma_f32_16x16x32_bf16 v[116:119], v[148:151], v[180:183], v[116:119]
	v_mfma_f32_16x16x32_bf16 v[112:115], v[168:171], v[180:183], v[112:115]
	v_mfma_f32_16x16x32_bf16 v[112:115], v[152:155], v[172:175], v[112:115]
	v_mfma_f32_16x16x32_bf16 v[96:99], v[152:155], v[176:179], v[96:99]
	v_mfma_f32_16x16x32_bf16 v[96:99], v[168:171], v[184:187], v[96:99]
	v_mfma_f32_16x16x32_bf16 v[100:103], v[148:151], v[184:187], v[100:103]
	v_mfma_f32_16x16x32_bf16 v[100:103], v[144:147], v[176:179], v[100:103]
	v_mfma_f32_16x16x32_bf16 v[84:87], v[144:147], v[208:211], v[84:87]
	v_mfma_f32_16x16x32_bf16 v[84:87], v[148:151], v[216:219], v[84:87]
	v_mfma_f32_16x16x32_bf16 v[80:83], v[168:171], v[216:219], v[80:83]
	v_mfma_f32_16x16x32_bf16 v[80:83], v[152:155], v[208:211], v[80:83]
	v_mfma_f32_16x16x32_bf16 v[64:67], v[152:155], v[212:215], v[64:67]
	v_mfma_f32_16x16x32_bf16 v[64:67], v[168:171], v[220:223], v[64:67]
	v_mfma_f32_16x16x32_bf16 v[68:71], v[148:151], v[220:223], v[68:71]
	v_mfma_f32_16x16x32_bf16 v[68:71], v[144:147], v[212:215], v[68:71]
	s_setprio 0
	s_barrier
; #define PG8_STAGE(bufoff, gbase, voff) do { _Pragma("unroll") for (int _i = 0; _i < 2; ++_i) \
;         __builtin_amdgcn_global_load_lds((const unsigned*)((const char*)(gbase) + (voff)[_i]), (LAS unsigned*)(lds + (bufoff) + ldsw + _i * 8192), 16, 0, 0); } while (0)
; #define PG8_LDA(dst, b, h) do { _Pragma("unroll") for (int m = 0; m < 4; ++m) _Pragma("unroll") for (int k = 0; k < 2; ++k) dst[m][k] = *(const LAS bf16x8*)(lds + PG8_SA(b, h) + aoffk[k] + m * 2048); } while (0)
; #define PG8_LDB(dst, b, h) do { _Pragma("unroll") for (int n = 0; n < 2; ++n) _Pragma("unroll") for (int k = 0; k < 2; ++k) dst[n][k] = *(const LAS bf16x8*)(lds + PG8_SB(b, h) + boffk[k] + n * 2048); } while (0)
; #define PG8_WAIT_V(n) asm volatile("s_waitcnt vmcnt(" #n ")" ::: "memory")
; #define PG8_WAIT_L(n) asm volatile("s_waitcnt lgkmcnt(" #n ")" ::: "memory")
; #define PG8_BAR __builtin_amdgcn_s_barrier()
; #define PG8_SCHED __builtin_amdgcn_sched_barrier(0)
; template <class Epi, class Sched, class GemmT>
; __device__ __forceinline__ void gemm_phase(LAS unsigned char* lds, const GemmT& g, const Sched& S, const Epi& E, const int wid) {
;     ...
;                 PG8_LDB(B0, 1, 0); PG8_LDB(B1, 1, 1); PG8_SCHED; PG8_LDA(At, 1, 0); PG8_STAGE(PG8_SA(0, 1), a2 + hA2, vA2);
;                 PG8_WAIT_V(8); PG8_WAIT_L(0); PG8_BAR; PG8_MMA(0, 0, At, B0); PG8_MMA(0, 1, At, B1); PG8_BAR; PG8_SCHED;
;                 PG8_LDA(At, 1, 1); PG8_STAGE(PG8_SB(1, 0), b3, vB2); PG8_STAGE(PG8_SB(1, 1), b3 + hB2, vB2); PG8_STAGE(PG8_SA(1, 0), a3, vA2);
;                 PG8_WAIT_V(8); PG8_WAIT_L(0); PG8_BAR; PG8_MMA(1, 0, At, B0); PG8_MMA(1, 1, At, B1); PG8_BAR; PG8_SCHED;
;             }
	s_add_i32 s48, s63, s68
	v_lshl_add_u64 v[188:189], v[188:189], 0, s[18:19]
	s_mov_b32 m0, s48
	ds_read_b128 v[172:175], v202 offset:49152
	ds_read_b128 v[176:179], v202 offset:51200
	ds_read_b128 v[180:183], v203 offset:49152
	ds_read_b128 v[184:187], v203 offset:51200
	ds_read_b128 v[208:211], v202 offset:53248
	ds_read_b128 v[212:215], v202 offset:55296
	ds_read_b128 v[216:219], v203 offset:53248
	ds_read_b128 v[220:223], v203 offset:55296
	global_load_lds_dwordx4 v[188:189], off
	s_add_i32 m0, s48, 0x2000
	s_add_u32 s44, s44, 0x100080
	v_lshl_add_u64 v[188:189], v[224:225], 0, s[18:19]
	s_addc_u32 s45, s45, 0
	s_add_i32 s48, s64, s68
	global_load_lds_dwordx4 v[188:189], off
	v_lshl_add_u64 v[188:189], s[44:45], 0, v[158:159]
	s_mov_b32 m0, s48
	s_nop 0
	global_load_lds_dwordx4 v[188:189], off
	v_lshl_add_u64 v[188:189], s[44:45], 0, v[162:163]
	s_add_i32 m0, s48, 0x2000
	s_nop 0
	global_load_lds_dwordx4 v[188:189], off
	v_lshl_add_u64 v[188:189], v[226:227], 0, s[18:19]
	s_mov_b32 m0, s34
	s_nop 0
	global_load_lds_dwordx4 v[188:189], off
	v_lshl_add_u64 v[188:189], v[230:231], 0, s[18:19]
	s_mov_b32 m0, s35
	s_nop 0
	global_load_lds_dwordx4 v[188:189], off
	s_waitcnt vmcnt(8)
	s_waitcnt lgkmcnt(0)
	s_waitcnt lgkmcnt(0)
	v_mfma_f32_16x16x32_bf16 v[52:55], v[128:131], v[172:175], v[52:55]
	v_mfma_f32_16x16x32_bf16 v[52:55], v[132:135], v[180:183], v[52:55]
	v_mfma_f32_16x16x32_bf16 v[48:51], v[140:143], v[180:183], v[48:51]
	v_mfma_f32_16x16x32_bf16 v[48:51], v[136:139], v[172:175], v[48:51]
	v_mfma_f32_16x16x32_bf16 v[32:35], v[136:139], v[176:179], v[32:35]
	v_mfma_f32_16x16x32_bf16 v[32:35], v[140:143], v[184:187], v[32:35]
	v_mfma_f32_16x16x32_bf16 v[36:39], v[132:135], v[184:187], v[36:39]
	v_mfma_f32_16x16x32_bf16 v[36:39], v[128:131], v[176:179], v[36:39]
	s_barrier
	s_setprio 3
	v_mfma_f32_16x16x32_bf16 v[20:23], v[128:131], v[208:211], v[20:23]
	v_mfma_f32_16x16x32_bf16 v[20:23], v[132:135], v[216:219], v[20:23]
	v_mfma_f32_16x16x32_bf16 v[16:19], v[140:143], v[216:219], v[16:19]
	v_mfma_f32_16x16x32_bf16 v[16:19], v[136:139], v[208:211], v[16:19]
	v_mfma_f32_16x16x32_bf16 v[0:3], v[136:139], v[212:215], v[0:3]
	v_mfma_f32_16x16x32_bf16 v[0:3], v[140:143], v[220:223], v[0:3]
	v_mfma_f32_16x16x32_bf16 v[4:7], v[132:135], v[220:223], v[4:7]
	v_mfma_f32_16x16x32_bf16 v[4:7], v[128:131], v[212:215], v[4:7]
	s_setprio 0
	s_setprio 3
	v_mfma_f32_16x16x32_bf16 v[60:63], v[144:147], v[172:175], v[60:63]
	v_mfma_f32_16x16x32_bf16 v[60:63], v[148:151], v[180:183], v[60:63]
	v_mfma_f32_16x16x32_bf16 v[56:59], v[168:171], v[180:183], v[56:59]
	v_mfma_f32_16x16x32_bf16 v[56:59], v[152:155], v[172:175], v[56:59]
	v_mfma_f32_16x16x32_bf16 v[40:43], v[152:155], v[176:179], v[40:43]
	v_mfma_f32_16x16x32_bf16 v[40:43], v[168:171], v[184:187], v[40:43]
	v_mfma_f32_16x16x32_bf16 v[44:47], v[148:151], v[184:187], v[44:47]
	v_mfma_f32_16x16x32_bf16 v[44:47], v[144:147], v[176:179], v[44:47]
	v_mfma_f32_16x16x32_bf16 v[28:31], v[144:147], v[208:211], v[28:31]
	v_mfma_f32_16x16x32_bf16 v[28:31], v[148:151], v[216:219], v[28:31]
	v_mfma_f32_16x16x32_bf16 v[24:27], v[168:171], v[216:219], v[24:27]
	v_mfma_f32_16x16x32_bf16 v[24:27], v[152:155], v[208:211], v[24:27]
	v_mfma_f32_16x16x32_bf16 v[8:11], v[152:155], v[212:215], v[8:11]
	v_mfma_f32_16x16x32_bf16 v[8:11], v[168:171], v[220:223], v[8:11]
	v_mfma_f32_16x16x32_bf16 v[12:15], v[148:151], v[220:223], v[12:15]
	v_mfma_f32_16x16x32_bf16 v[12:15], v[144:147], v[212:215], v[12:15]
	s_setprio 0
	s_barrier
	s_add_i32 s62, s62, 2
	s_add_u32 s42, s42, 0x100
	s_addc_u32 s43, s43, 0
	s_add_u32 s60, s60, 0x100
	s_addc_u32 s61, s61, 0
	s_cmp_gt_u32 s62, 61
	s_cbranch_scc0 .LBB0_846
	s_and_b64 vcc, exec, s[20:21]
	s_cbranch_vccz .LBB0_849
	s_barrier

; #define PG8_STAGE(bufoff, gbase, voff) do { _Pragma("unroll") for (int _i = 0; _i < 2; ++_i) \
;         __builtin_amdgcn_global_load_lds((const unsigned*)((const char*)(gbase) + (voff)[_i]), (LAS unsigned*)(lds + (bufoff) + ldsw + _i * 8192), 16, 0, 0); } while (0)
; #define PG8_LDA(dst, b, h) do { _Pragma("unroll") for (int m = 0; m < 4; ++m) _Pragma("unroll") for (int k = 0; k < 2; ++k) dst[m][k] = *(const LAS bf16x8*)(lds + PG8_SA(b, h) + aoffk[k] + m * 2048); } while (0)
; #define PG8_LDB(dst, b, h) do { _Pragma("unroll") for (int n = 0; n < 2; ++n) _Pragma("unroll") for (int k = 0; k < 2; ++k) dst[n][k] = *(const LAS bf16x8*)(lds + PG8_SB(b, h) + boffk[k] + n * 2048); } while (0)
; #define PG8_WAIT_V(n) asm volatile("s_waitcnt vmcnt(" #n ")" ::: "memory")
; #define PG8_WAIT_L(n) asm volatile("s_waitcnt lgkmcnt(" #n ")" ::: "memory")
; #define PG8_BAR __builtin_amdgcn_s_barrier()
; #define PG8_SCHED __builtin_amdgcn_sched_barrier(0)
; template <class Epi, class Sched, class GemmT>
; __device__ __forceinline__ void gemm_phase(LAS unsigned char* lds, const GemmT& g, const Sched& S, const Epi& E, const int wid) {
;     ...
;                 PG8_LDB(B0, 0, 0); PG8_LDB(B1, 0, 1); PG8_SCHED; PG8_LDA(At, 0, 0); PG8_STAGE(PG8_SA(1, 1), a1 + hstepA, voffA);
;                 PG8_WAIT_V(8); PG8_WAIT_L(0); PG8_BAR; PG8_MMA(0, 0, At, B0); PG8_MMA(0, 1, At, B1); PG8_BAR; PG8_SCHED;
;                 PG8_LDA(At, 0, 1); PG8_STAGE(PG8_SB(0, 0), b2, vB2); PG8_STAGE(PG8_SB(0, 1), b2 + hB2, vB2); PG8_STAGE(PG8_SA(0, 0), a2, vA2);
;                 PG8_WAIT_V(8); PG8_WAIT_L(0); PG8_BAR; PG8_MMA(1, 0, At, B0); PG8_MMA(1, 1, At, B1); PG8_BAR; PG8_SCHED;
.LBB0_936:
	ds_read_b128 v[12:15], v223
	ds_read_b128 v[132:135], v224
	ds_read_b128 v[136:139], v225
	ds_read_b128 v[140:143], v226
	ds_read_b128 v[144:147], v227
	ds_read_b128 v[148:151], v229
	ds_read_b128 v[152:155], v230
	ds_read_b128 v[156:159], v231
	s_add_u32 s66, s64, 0xfff00080
	s_addc_u32 s67, s65, -1
	s_cmp_eq_u32 s81, 60
	s_cselect_b32 s71, s57, s67
	s_cselect_b32 s70, s56, s66
	s_cselect_b32 s67, s77, s79
	s_cselect_b32 s66, s63, s78
	v_lshl_add_u64 v[204:205], s[64:65], 0, v[176:177]
	s_add_i32 m0, s14, 0xc000
	ds_read_b128 v[160:163], v232
	ds_read_b128 v[164:167], v232 offset:2048
	ds_read_b128 v[168:171], v233
	ds_read_b128 v[172:175], v233 offset:2048
	ds_read_b128 v[188:191], v232 offset:4096
	ds_read_b128 v[192:195], v232 offset:6144
	ds_read_b128 v[196:199], v233 offset:4096
	ds_read_b128 v[200:203], v233 offset:6144
	global_load_lds_dwordx4 v[204:205], off
	v_lshl_add_u64 v[204:205], s[64:65], 0, v[180:181]
	s_add_i32 m0, s14, 0xe000
	s_nop 0
	global_load_lds_dwordx4 v[204:205], off
	s_waitcnt vmcnt(8)
	s_waitcnt lgkmcnt(0)
	s_waitcnt lgkmcnt(0)
	v_mfma_f32_16x16x32_bf16 v[124:127], v[12:15], v[160:163], v[124:127]
	v_mfma_f32_16x16x32_bf16 v[124:127], v[132:135], v[168:171], v[124:127]
	v_mfma_f32_16x16x32_bf16 v[120:123], v[140:143], v[168:171], v[120:123]
	v_mfma_f32_16x16x32_bf16 v[120:123], v[136:139], v[160:163], v[120:123]
	v_mfma_f32_16x16x32_bf16 v[104:107], v[136:139], v[164:167], v[104:107]
	v_mfma_f32_16x16x32_bf16 v[104:107], v[140:143], v[172:175], v[104:107]
	v_mfma_f32_16x16x32_bf16 v[40:43], v[132:135], v[172:175], v[40:43]
	v_mfma_f32_16x16x32_bf16 v[40:43], v[12:15], v[164:167], v[40:43]
	s_barrier
	s_setprio 3
	v_mfma_f32_16x16x32_bf16 v[32:35], v[12:15], v[188:191], v[32:35]
	v_mfma_f32_16x16x32_bf16 v[32:35], v[132:135], v[196:199], v[32:35]
	v_mfma_f32_16x16x32_bf16 v[96:99], v[140:143], v[196:199], v[96:99]
	v_mfma_f32_16x16x32_bf16 v[96:99], v[136:139], v[188:191], v[96:99]
	v_mfma_f32_16x16x32_bf16 v[92:95], v[136:139], v[192:195], v[92:95]
	v_mfma_f32_16x16x32_bf16 v[92:95], v[140:143], v[200:203], v[92:95]
	v_mfma_f32_16x16x32_bf16 v[112:115], v[132:135], v[200:203], v[112:115]
	v_mfma_f32_16x16x32_bf16 v[112:115], v[12:15], v[192:195], v[112:115]
	s_setprio 0
	s_setprio 3
	v_mfma_f32_16x16x32_bf16 v[68:71], v[144:147], v[160:163], v[68:71]
	v_mfma_f32_16x16x32_bf16 v[68:71], v[148:151], v[168:171], v[68:71]
	v_mfma_f32_16x16x32_bf16 v[60:63], v[156:159], v[168:171], v[60:63]
	v_mfma_f32_16x16x32_bf16 v[60:63], v[152:155], v[160:163], v[60:63]
	v_mfma_f32_16x16x32_bf16 v[20:23], v[152:155], v[164:167], v[20:23]
	v_mfma_f32_16x16x32_bf16 v[20:23], v[156:159], v[172:175], v[20:23]
	v_mfma_f32_16x16x32_bf16 v[76:79], v[148:151], v[172:175], v[76:79]
	v_mfma_f32_16x16x32_bf16 v[76:79], v[144:147], v[164:167], v[76:79]
	v_mfma_f32_16x16x32_bf16 v[72:75], v[144:147], v[188:191], v[72:75]
	v_mfma_f32_16x16x32_bf16 v[72:75], v[148:151], v[196:199], v[72:75]
	v_mfma_f32_16x16x32_bf16 v[16:19], v[156:159], v[196:199], v[16:19]
	v_mfma_f32_16x16x32_bf16 v[16:19], v[152:155], v[188:191], v[16:19]
	v_mfma_f32_16x16x32_bf16 v[80:83], v[152:155], v[192:195], v[80:83]
	v_mfma_f32_16x16x32_bf16 v[80:83], v[156:159], v[200:203], v[80:83]
	v_mfma_f32_16x16x32_bf16 v[84:87], v[148:151], v[200:203], v[84:87]
	v_mfma_f32_16x16x32_bf16 v[84:87], v[144:147], v[192:195], v[84:87]
	s_setprio 0
	s_barrier
	s_add_i32 s80, s69, s68
	v_lshl_add_u64 v[204:205], s[66:67], 0, v[178:179]
	s_mov_b32 m0, s80
	ds_read_b128 v[160:163], v232 offset:16384
	ds_read_b128 v[164:167], v232 offset:18432
	ds_read_b128 v[168:171], v233 offset:16384
	ds_read_b128 v[172:175], v233 offset:18432
	ds_read_b128 v[188:191], v232 offset:20480
	ds_read_b128 v[192:195], v232 offset:22528
	ds_read_b128 v[196:199], v233 offset:20480
	ds_read_b128 v[200:203], v233 offset:22528
	global_load_lds_dwordx4 v[204:205], off
	s_add_i32 m0, s80, 0x2000
	s_add_u32 s82, s66, 0x100000
	v_lshl_add_u64 v[206:207], s[66:67], 0, v[182:183]
	s_addc_u32 s83, s67, 0
	s_add_i32 s80, s72, s68
	global_load_lds_dwordx4 v[206:207], off
	v_lshl_add_u64 v[240:241], s[82:83], 0, v[178:179]
	s_mov_b32 m0, s80
	v_lshl_add_u64 v[242:243], s[70:71], 0, v[180:181]
	global_load_lds_dwordx4 v[240:241], off
	v_lshl_add_u64 v[240:241], s[82:83], 0, v[182:183]
	s_add_i32 m0, s80, 0x2000
	s_nop 0
	global_load_lds_dwordx4 v[240:241], off
	v_lshl_add_u64 v[240:241], s[70:71], 0, v[176:177]
	s_mov_b32 m0, s14
	s_nop 0
	global_load_lds_dwordx4 v[240:241], off
	s_mov_b32 m0, s15
	s_nop 0
	global_load_lds_dwordx4 v[242:243], off
	s_waitcnt vmcnt(8)
	s_waitcnt lgkmcnt(0)
	s_waitcnt lgkmcnt(0)
	v_mfma_f32_16x16x32_bf16 v[56:59], v[12:15], v[160:163], v[56:59]
	v_mfma_f32_16x16x32_bf16 v[56:59], v[132:135], v[168:171], v[56:59]
	v_mfma_f32_16x16x32_bf16 v[108:111], v[136:139], v[160:163], v[108:111]
	v_mfma_f32_16x16x32_bf16 v[108:111], v[140:143], v[168:171], v[108:111]
	v_mfma_f32_16x16x32_bf16 v[36:39], v[12:15], v[164:167], v[36:39]
	v_mfma_f32_16x16x32_bf16 v[36:39], v[132:135], v[172:175], v[36:39]
	v_mfma_f32_16x16x32_bf16 v[100:103], v[136:139], v[164:167], v[100:103]
	v_mfma_f32_16x16x32_bf16 v[100:103], v[140:143], v[172:175], v[100:103]
	s_barrier
; #define PG8_STAGE(bufoff, gbase, voff) do { _Pragma("unroll") for (int _i = 0; _i < 2; ++_i) \
;         __builtin_amdgcn_global_load_lds((const unsigned*)((const char*)(gbase) + (voff)[_i]), (LAS unsigned*)(lds + (bufoff) + ldsw + _i * 8192), 16, 0, 0); } while (0)
; #define PG8_LDA(dst, b, h) do { _Pragma("unroll") for (int m = 0; m < 4; ++m) _Pragma("unroll") for (int k = 0; k < 2; ++k) dst[m][k] = *(const LAS bf16x8*)(lds + PG8_SA(b, h) + aoffk[k] + m * 2048); } while (0)
; #define PG8_LDB(dst, b, h) do { _Pragma("unroll") for (int n = 0; n < 2; ++n) _Pragma("unroll") for (int k = 0; k < 2; ++k) dst[n][k] = *(const LAS bf16x8*)(lds + PG8_SB(b, h) + boffk[k] + n * 2048); } while (0)
; #define PG8_WAIT_V(n) asm volatile("s_waitcnt vmcnt(" #n ")" ::: "memory")
; #define PG8_WAIT_L(n) asm volatile("s_waitcnt lgkmcnt(" #n ")" ::: "memory")
; #define PG8_BAR __builtin_amdgcn_s_barrier()
; #define PG8_SCHED __builtin_amdgcn_sched_barrier(0)
; template <class Epi, class Sched, class GemmT>
; __device__ __forceinline__ void gemm_phase(LAS unsigned char* lds, const GemmT& g, const Sched& S, const Epi& E, const int wid) {
;     ...
;                 PG8_LDA(At, 0, 1); PG8_STAGE(PG8_SB(0, 0), b2, vB2); PG8_STAGE(PG8_SB(0, 1), b2 + hB2, vB2); PG8_STAGE(PG8_SA(0, 0), a2, vA2);
;                 PG8_WAIT_V(8); PG8_WAIT_L(0); PG8_BAR; PG8_MMA(1, 0, At, B0); PG8_MMA(1, 1, At, B1); PG8_BAR; PG8_SCHED;
;                 PG8_LDB(B0, 1, 0); PG8_LDB(B1, 1, 1); PG8_SCHED; PG8_LDA(At, 1, 0); PG8_STAGE(PG8_SA(0, 1), a2 + hA2, vA2);
;                 PG8_WAIT_V(8); PG8_WAIT_L(0); PG8_BAR; PG8_MMA(0, 0, At, B0); PG8_MMA(0, 1, At, B1); PG8_BAR; PG8_SCHED;
	s_setprio 3
	v_mfma_f32_16x16x32_bf16 v[28:31], v[12:15], v[188:191], v[28:31]
	v_mfma_f32_16x16x32_bf16 v[28:31], v[132:135], v[196:199], v[28:31]
	v_mfma_f32_16x16x32_bf16 v[88:91], v[136:139], v[188:191], v[88:91]
	v_mfma_f32_16x16x32_bf16 v[88:91], v[140:143], v[196:199], v[88:91]
	v_mfma_f32_16x16x32_bf16 v[24:27], v[136:139], v[192:195], v[24:27]
	v_mfma_f32_16x16x32_bf16 v[24:27], v[140:143], v[200:203], v[24:27]
	v_mfma_f32_16x16x32_bf16 v[12:15], v[12:15], v[192:195], v[64:67]
	v_mfma_f32_16x16x32_bf16 v[12:15], v[132:135], v[200:203], v[12:15]
	s_setprio 0
	s_setprio 3
	v_mfma_f32_16x16x32_bf16 v[64:67], v[144:147], v[192:195], v[116:119]
	v_mfma_f32_16x16x32_bf16 v[116:119], v[148:151], v[200:203], v[64:67]
	v_mfma_f32_16x16x32_bf16 v[44:47], v[144:147], v[160:163], v[44:47]
	v_mfma_f32_16x16x32_bf16 v[44:47], v[148:151], v[168:171], v[44:47]
	v_mfma_f32_16x16x32_bf16 v[0:3], v[152:155], v[160:163], v[0:3]
	v_mfma_f32_16x16x32_bf16 v[0:3], v[156:159], v[168:171], v[0:3]
	v_mfma_f32_16x16x32_bf16 v[48:51], v[144:147], v[164:167], v[48:51]
	v_mfma_f32_16x16x32_bf16 v[48:51], v[148:151], v[172:175], v[48:51]
	v_mfma_f32_16x16x32_bf16 v[4:7], v[152:155], v[164:167], v[4:7]
	v_mfma_f32_16x16x32_bf16 v[4:7], v[156:159], v[172:175], v[4:7]
	v_mfma_f32_16x16x32_bf16 v[64:67], v[152:155], v[192:195], v[128:131]
	v_mfma_f32_16x16x32_bf16 v[128:131], v[156:159], v[200:203], v[64:67]
	v_mfma_f32_16x16x32_bf16 v[52:55], v[144:147], v[188:191], v[52:55]
	v_mfma_f32_16x16x32_bf16 v[52:55], v[148:151], v[196:199], v[52:55]
	v_mfma_f32_16x16x32_bf16 v[8:11], v[152:155], v[188:191], v[8:11]
	v_mfma_f32_16x16x32_bf16 v[8:11], v[156:159], v[196:199], v[8:11]
	s_setprio 0
	s_barrier
	s_add_i32 s80, 0, 0x18000
	s_add_i32 s82, 0, 0x1c000
	v_add_u32_e32 v64, s80, v210
	v_add_u32_e32 v132, s80, v211
	v_add_u32_e32 v144, s82, v210
	v_add_u32_e32 v148, s82, v211
	ds_read_b128 v[64:67], v64
	ds_read_b128 v[132:135], v132
	ds_read_b128 v[136:139], v234
	ds_read_b128 v[140:143], v235
	ds_read_b128 v[144:147], v144
	ds_read_b128 v[148:151], v148
	ds_read_b128 v[152:155], v236
	ds_read_b128 v[156:159], v237
	s_add_u32 s70, s70, 0x100000
	s_addc_u32 s71, s71, 0
	s_mov_b32 m0, s23
	v_lshl_add_u64 v[244:245], s[70:71], 0, v[176:177]
	ds_read_b128 v[160:163], v232 offset:32768
	ds_read_b128 v[164:167], v232 offset:34816
	ds_read_b128 v[168:171], v233 offset:32768
	ds_read_b128 v[172:175], v233 offset:34816
	ds_read_b128 v[188:191], v232 offset:36864
	ds_read_b128 v[192:195], v232 offset:38912
	ds_read_b128 v[196:199], v233 offset:36864
	ds_read_b128 v[200:203], v233 offset:38912
	global_load_lds_dwordx4 v[244:245], off
	v_lshl_add_u64 v[244:245], s[70:71], 0, v[180:181]
	s_mov_b32 m0, s34
	s_nop 0
	global_load_lds_dwordx4 v[244:245], off
	s_waitcnt vmcnt(8)
	s_waitcnt lgkmcnt(0)
	s_waitcnt lgkmcnt(0)
	v_mfma_f32_16x16x32_bf16 v[124:127], v[64:67], v[160:163], v[124:127]
	v_mfma_f32_16x16x32_bf16 v[124:127], v[132:135], v[168:171], v[124:127]
	v_mfma_f32_16x16x32_bf16 v[120:123], v[140:143], v[168:171], v[120:123]
	v_mfma_f32_16x16x32_bf16 v[120:123], v[136:139], v[160:163], v[120:123]
	v_mfma_f32_16x16x32_bf16 v[104:107], v[136:139], v[164:167], v[104:107]
	v_mfma_f32_16x16x32_bf16 v[104:107], v[140:143], v[172:175], v[104:107]
	v_mfma_f32_16x16x32_bf16 v[40:43], v[132:135], v[172:175], v[40:43]
	v_mfma_f32_16x16x32_bf16 v[40:43], v[64:67], v[164:167], v[40:43]
	s_barrier
	s_setprio 3
	v_mfma_f32_16x16x32_bf16 v[32:35], v[64:67], v[188:191], v[32:35]
	v_mfma_f32_16x16x32_bf16 v[32:35], v[132:135], v[196:199], v[32:35]
	v_mfma_f32_16x16x32_bf16 v[96:99], v[140:143], v[196:199], v[96:99]
	v_mfma_f32_16x16x32_bf16 v[96:99], v[136:139], v[188:191], v[96:99]
	v_mfma_f32_16x16x32_bf16 v[92:95], v[136:139], v[192:195], v[92:95]
	v_mfma_f32_16x16x32_bf16 v[92:95], v[140:143], v[200:203], v[92:95]
	v_mfma_f32_16x16x32_bf16 v[112:115], v[132:135], v[200:203], v[112:115]
	v_mfma_f32_16x16x32_bf16 v[112:115], v[64:67], v[192:195], v[112:115]
	s_setprio 0
	s_setprio 3
	v_mfma_f32_16x16x32_bf16 v[68:71], v[144:147], v[160:163], v[68:71]
	v_mfma_f32_16x16x32_bf16 v[68:71], v[148:151], v[168:171], v[68:71]
	v_mfma_f32_16x16x32_bf16 v[60:63], v[156:159], v[168:171], v[60:63]
	v_mfma_f32_16x16x32_bf16 v[60:63], v[152:155], v[160:163], v[60:63]
	v_mfma_f32_16x16x32_bf16 v[20:23], v[152:155], v[164:167], v[20:23]
	v_mfma_f32_16x16x32_bf16 v[20:23], v[156:159], v[172:175], v[20:23]
	v_mfma_f32_16x16x32_bf16 v[76:79], v[148:151], v[172:175], v[76:79]
	v_mfma_f32_16x16x32_bf16 v[76:79], v[144:147], v[164:167], v[76:79]
	v_mfma_f32_16x16x32_bf16 v[72:75], v[144:147], v[188:191], v[72:75]
	v_mfma_f32_16x16x32_bf16 v[72:75], v[148:151], v[196:199], v[72:75]
	v_mfma_f32_16x16x32_bf16 v[16:19], v[156:159], v[196:199], v[16:19]
	v_mfma_f32_16x16x32_bf16 v[16:19], v[152:155], v[188:191], v[16:19]
	v_mfma_f32_16x16x32_bf16 v[80:83], v[152:155], v[192:195], v[80:83]
	v_mfma_f32_16x16x32_bf16 v[80:83], v[156:159], v[200:203], v[80:83]
	v_mfma_f32_16x16x32_bf16 v[84:87], v[148:151], v[200:203], v[84:87]
	v_mfma_f32_16x16x32_bf16 v[84:87], v[144:147], v[192:195], v[84:87]
	s_setprio 0
	s_barrier
; #define PG8_STAGE(bufoff, gbase, voff) do { _Pragma("unroll") for (int _i = 0; _i < 2; ++_i) \
;         __builtin_amdgcn_global_load_lds((const unsigned*)((const char*)(gbase) + (voff)[_i]), (LAS unsigned*)(lds + (bufoff) + ldsw + _i * 8192), 16, 0, 0); } while (0)
; #define PG8_LDA(dst, b, h) do { _Pragma("unroll") for (int m = 0; m < 4; ++m) _Pragma("unroll") for (int k = 0; k < 2; ++k) dst[m][k] = *(const LAS bf16x8*)(lds + PG8_SA(b, h) + aoffk[k] + m * 2048); } while (0)
; #define PG8_LDB(dst, b, h) do { _Pragma("unroll") for (int n = 0; n < 2; ++n) _Pragma("unroll") for (int k = 0; k < 2; ++k) dst[n][k] = *(const LAS bf16x8*)(lds + PG8_SB(b, h) + boffk[k] + n * 2048); } while (0)
; #define PG8_WAIT_V(n) asm volatile("s_waitcnt vmcnt(" #n ")" ::: "memory")
; #define PG8_WAIT_L(n) asm volatile("s_waitcnt lgkmcnt(" #n ")" ::: "memory")
; #define PG8_BAR __builtin_amdgcn_s_barrier()
; #define PG8_SCHED __builtin_amdgcn_sched_barrier(0)
; template <class Epi, class Sched, class GemmT>
; __device__ __forceinline__ void gemm_phase(LAS unsigned char* lds, const GemmT& g, const Sched& S, const Epi& E, const int wid) {
;     ...
;                 PG8_LDB(B0, 1, 0); PG8_LDB(B1, 1, 1); PG8_SCHED; PG8_LDA(At, 1, 0); PG8_STAGE(PG8_SA(0, 1), a2 + hA2, vA2);
;                 PG8_WAIT_V(8); PG8_WAIT_L(0); PG8_BAR; PG8_MMA(0, 0, At, B0); PG8_MMA(0, 1, At, B1); PG8_BAR; PG8_SCHED;
;                 PG8_LDA(At, 1, 1); PG8_STAGE(PG8_SB(1, 0), b3, vB2); PG8_STAGE(PG8_SB(1, 1), b3 + hB2, vB2); PG8_STAGE(PG8_SA(1, 0), a3, vA2);
;                 PG8_WAIT_V(8); PG8_WAIT_L(0); PG8_BAR; PG8_MMA(1, 0, At, B0); PG8_MMA(1, 1, At, B1); PG8_BAR; PG8_SCHED;
;             }
	s_add_i32 s70, s80, s68
	v_lshl_add_u64 v[204:205], v[204:205], 0, s[38:39]
	s_mov_b32 m0, s70
	ds_read_b128 v[160:163], v232 offset:49152
	ds_read_b128 v[164:167], v232 offset:51200
	ds_read_b128 v[168:171], v233 offset:49152
	ds_read_b128 v[172:175], v233 offset:51200
	ds_read_b128 v[188:191], v232 offset:53248
	ds_read_b128 v[192:195], v232 offset:55296
	ds_read_b128 v[196:199], v233 offset:53248
	ds_read_b128 v[200:203], v233 offset:55296
	global_load_lds_dwordx4 v[204:205], off
	s_add_i32 m0, s70, 0x2000
	s_add_u32 s66, s66, 0x100080
	v_lshl_add_u64 v[204:205], v[206:207], 0, s[38:39]
	s_addc_u32 s67, s67, 0
	s_add_i32 s70, s82, s68
	global_load_lds_dwordx4 v[204:205], off
	v_lshl_add_u64 v[204:205], s[66:67], 0, v[178:179]
	s_mov_b32 m0, s70
	s_nop 0
	global_load_lds_dwordx4 v[204:205], off
	v_lshl_add_u64 v[204:205], s[66:67], 0, v[182:183]
	s_add_i32 m0, s70, 0x2000
	s_nop 0
	global_load_lds_dwordx4 v[204:205], off
	v_lshl_add_u64 v[204:205], v[240:241], 0, s[38:39]
	s_mov_b32 m0, s54
	s_nop 0
	global_load_lds_dwordx4 v[204:205], off
	v_lshl_add_u64 v[204:205], v[242:243], 0, s[38:39]
	s_mov_b32 m0, s55
	s_nop 0
	global_load_lds_dwordx4 v[204:205], off
	s_waitcnt vmcnt(8)
	s_waitcnt lgkmcnt(0)
	s_waitcnt lgkmcnt(0)
	v_mfma_f32_16x16x32_bf16 v[12:15], v[64:67], v[192:195], v[12:15]
	v_mfma_f32_16x16x32_bf16 v[56:59], v[64:67], v[160:163], v[56:59]
	v_mfma_f32_16x16x32_bf16 v[56:59], v[132:135], v[168:171], v[56:59]
	v_mfma_f32_16x16x32_bf16 v[108:111], v[136:139], v[160:163], v[108:111]
	v_mfma_f32_16x16x32_bf16 v[108:111], v[140:143], v[168:171], v[108:111]
	v_mfma_f32_16x16x32_bf16 v[36:39], v[64:67], v[164:167], v[36:39]
	v_mfma_f32_16x16x32_bf16 v[36:39], v[132:135], v[172:175], v[36:39]
	v_mfma_f32_16x16x32_bf16 v[100:103], v[136:139], v[164:167], v[100:103]
	s_barrier
	s_setprio 3
	v_mfma_f32_16x16x32_bf16 v[100:103], v[140:143], v[172:175], v[100:103]
	v_mfma_f32_16x16x32_bf16 v[28:31], v[64:67], v[188:191], v[28:31]
	v_mfma_f32_16x16x32_bf16 v[28:31], v[132:135], v[196:199], v[28:31]
	v_mfma_f32_16x16x32_bf16 v[88:91], v[136:139], v[188:191], v[88:91]
	v_mfma_f32_16x16x32_bf16 v[88:91], v[140:143], v[196:199], v[88:91]
	v_mfma_f32_16x16x32_bf16 v[64:67], v[132:135], v[200:203], v[12:15]
	v_mfma_f32_16x16x32_bf16 v[12:15], v[136:139], v[192:195], v[24:27]
	v_mfma_f32_16x16x32_bf16 v[24:27], v[140:143], v[200:203], v[12:15]
	s_setprio 0
	s_setprio 3
	v_mfma_f32_16x16x32_bf16 v[12:15], v[144:147], v[160:163], v[44:47]
	v_mfma_f32_16x16x32_bf16 v[44:47], v[148:151], v[168:171], v[12:15]
	v_mfma_f32_16x16x32_bf16 v[0:3], v[152:155], v[160:163], v[0:3]
	v_mfma_f32_16x16x32_bf16 v[0:3], v[156:159], v[168:171], v[0:3]
	v_mfma_f32_16x16x32_bf16 v[4:7], v[152:155], v[164:167], v[4:7]
	v_mfma_f32_16x16x32_bf16 v[4:7], v[156:159], v[172:175], v[4:7]
	v_mfma_f32_16x16x32_bf16 v[12:15], v[144:147], v[164:167], v[48:51]
	v_mfma_f32_16x16x32_bf16 v[48:51], v[148:151], v[172:175], v[12:15]
	v_mfma_f32_16x16x32_bf16 v[8:11], v[152:155], v[188:191], v[8:11]
	v_mfma_f32_16x16x32_bf16 v[8:11], v[156:159], v[196:199], v[8:11]
	v_mfma_f32_16x16x32_bf16 v[12:15], v[144:147], v[188:191], v[52:55]
	v_mfma_f32_16x16x32_bf16 v[52:55], v[148:151], v[196:199], v[12:15]
	v_mfma_f32_16x16x32_bf16 v[12:15], v[144:147], v[192:195], v[116:119]
	v_mfma_f32_16x16x32_bf16 v[116:119], v[148:151], v[200:203], v[12:15]
	v_mfma_f32_16x16x32_bf16 v[12:15], v[152:155], v[192:195], v[128:131]
	v_mfma_f32_16x16x32_bf16 v[128:131], v[156:159], v[200:203], v[12:15]
	s_setprio 0
	s_barrier
	s_add_i32 s81, s81, 2
	s_add_u32 s64, s64, 0x100
	s_addc_u32 s65, s65, 0
	s_add_u32 s78, s78, 0x100
	s_addc_u32 s79, s79, 0
	s_cmp_gt_u32 s81, 61
	s_cbranch_scc0 .LBB0_936
	s_and_b64 vcc, exec, s[40:41]
	s_cbranch_vccz .LBB0_939
	s_barrier

; #define PG8_STAGE(bufoff, gbase, voff) do { _Pragma("unroll") for (int _i = 0; _i < 2; ++_i) \
;         __builtin_amdgcn_global_load_lds((const unsigned*)((const char*)(gbase) + (voff)[_i]), (LAS unsigned*)(lds + (bufoff) + ldsw + _i * 8192), 16, 0, 0); } while (0)
; #define PG8_LDA(dst, b, h) do { _Pragma("unroll") for (int m = 0; m < 4; ++m) _Pragma("unroll") for (int k = 0; k < 2; ++k) dst[m][k] = *(const LAS bf16x8*)(lds + PG8_SA(b, h) + aoffk[k] + m * 2048); } while (0)
; #define PG8_LDB(dst, b, h) do { _Pragma("unroll") for (int n = 0; n < 2; ++n) _Pragma("unroll") for (int k = 0; k < 2; ++k) dst[n][k] = *(const LAS bf16x8*)(lds + PG8_SB(b, h) + boffk[k] + n * 2048); } while (0)
; #define PG8_WAIT_V(n) asm volatile("s_waitcnt vmcnt(" #n ")" ::: "memory")
; #define PG8_WAIT_L(n) asm volatile("s_waitcnt lgkmcnt(" #n ")" ::: "memory")
; #define PG8_BAR __builtin_amdgcn_s_barrier()
; #define PG8_SCHED __builtin_amdgcn_sched_barrier(0)
; template <class Epi, class Sched, class GemmT>
; __device__ __forceinline__ void gemm_phase(LAS unsigned char* lds, const GemmT& g, const Sched& S, const Epi& E, const int wid) {
;     ...
;                 PG8_LDB(B0, 0, 0); PG8_LDB(B1, 0, 1); PG8_SCHED; PG8_LDA(At, 0, 0); PG8_STAGE(PG8_SA(1, 1), a1 + hstepA, voffA);
;                 PG8_WAIT_V(8); PG8_WAIT_L(0); PG8_BAR; PG8_MMA(0, 0, At, B0); PG8_MMA(0, 1, At, B1); PG8_BAR; PG8_SCHED;
;                 PG8_LDA(At, 0, 1); PG8_STAGE(PG8_SB(0, 0), b2, vB2); PG8_STAGE(PG8_SB(0, 1), b2 + hB2, vB2); PG8_STAGE(PG8_SA(0, 0), a2, vA2);
;                 PG8_WAIT_V(8); PG8_WAIT_L(0); PG8_BAR; PG8_MMA(1, 0, At, B0); PG8_MMA(1, 1, At, B1); PG8_BAR; PG8_SCHED;
.LBB0_1096:
	ds_read_b128 v[128:131], v188
	ds_read_b128 v[132:135], v189
	ds_read_b128 v[136:139], v190
	ds_read_b128 v[140:143], v191
	ds_read_b128 v[144:147], v192
	ds_read_b128 v[148:151], v193
	ds_read_b128 v[152:155], v194
	ds_read_b128 v[156:159], v195
	s_add_u32 s24, s22, 0xffd50080
	s_addc_u32 s25, s23, -1
	s_cmpk_eq_i32 s56, 0xa8
	s_cselect_b32 s27, s19, s25
	s_cselect_b32 s26, s18, s24
	s_cselect_b32 s25, s53, s55
	s_cselect_b32 s24, s52, s54
	v_lshl_add_u64 v[222:223], s[22:23], 0, v[168:169]
	s_add_i32 m0, s34, 0xc000
	ds_read_b128 v[160:163], v196
	ds_read_b128 v[164:167], v196 offset:2048
	ds_read_b128 v[180:183], v197
	ds_read_b128 v[202:205], v197 offset:2048
	ds_read_b128 v[206:209], v196 offset:4096
	ds_read_b128 v[210:213], v196 offset:6144
	ds_read_b128 v[214:217], v197 offset:4096
	ds_read_b128 v[218:221], v197 offset:6144
	global_load_lds_dwordx4 v[222:223], off
	v_lshl_add_u64 v[222:223], s[22:23], 0, v[172:173]
	s_add_i32 m0, s34, 0xe000
	s_nop 0
	global_load_lds_dwordx4 v[222:223], off
	s_waitcnt vmcnt(8)
	s_waitcnt lgkmcnt(0)
	s_waitcnt lgkmcnt(0)
	v_mfma_f32_16x16x32_bf16 v[124:127], v[128:131], v[160:163], v[124:127]
	v_mfma_f32_16x16x32_bf16 v[124:127], v[132:135], v[180:183], v[124:127]
	v_mfma_f32_16x16x32_bf16 v[120:123], v[140:143], v[180:183], v[120:123]
	v_mfma_f32_16x16x32_bf16 v[120:123], v[136:139], v[160:163], v[120:123]
	v_mfma_f32_16x16x32_bf16 v[104:107], v[136:139], v[164:167], v[104:107]
	v_mfma_f32_16x16x32_bf16 v[104:107], v[140:143], v[202:205], v[104:107]
	v_mfma_f32_16x16x32_bf16 v[112:115], v[132:135], v[202:205], v[112:115]
	v_mfma_f32_16x16x32_bf16 v[112:115], v[128:131], v[164:167], v[112:115]
	s_barrier
	s_setprio 3
	v_mfma_f32_16x16x32_bf16 v[96:99], v[128:131], v[206:209], v[96:99]
	v_mfma_f32_16x16x32_bf16 v[96:99], v[132:135], v[214:217], v[96:99]
	v_mfma_f32_16x16x32_bf16 v[88:91], v[140:143], v[214:217], v[88:91]
	v_mfma_f32_16x16x32_bf16 v[88:91], v[136:139], v[206:209], v[88:91]
	v_mfma_f32_16x16x32_bf16 v[72:75], v[136:139], v[210:213], v[72:75]
	v_mfma_f32_16x16x32_bf16 v[72:75], v[140:143], v[218:221], v[72:75]
	v_mfma_f32_16x16x32_bf16 v[80:83], v[132:135], v[218:221], v[80:83]
	v_mfma_f32_16x16x32_bf16 v[80:83], v[128:131], v[210:213], v[80:83]
	s_setprio 0
	s_setprio 3
	v_mfma_f32_16x16x32_bf16 v[116:119], v[144:147], v[160:163], v[116:119]
	v_mfma_f32_16x16x32_bf16 v[116:119], v[148:151], v[180:183], v[116:119]
	v_mfma_f32_16x16x32_bf16 v[108:111], v[156:159], v[180:183], v[108:111]
	v_mfma_f32_16x16x32_bf16 v[108:111], v[152:155], v[160:163], v[108:111]
	v_mfma_f32_16x16x32_bf16 v[92:95], v[152:155], v[164:167], v[92:95]
	v_mfma_f32_16x16x32_bf16 v[92:95], v[156:159], v[202:205], v[92:95]
	v_mfma_f32_16x16x32_bf16 v[100:103], v[148:151], v[202:205], v[100:103]
	v_mfma_f32_16x16x32_bf16 v[100:103], v[144:147], v[164:167], v[100:103]
	v_mfma_f32_16x16x32_bf16 v[84:87], v[144:147], v[206:209], v[84:87]
	v_mfma_f32_16x16x32_bf16 v[84:87], v[148:151], v[214:217], v[84:87]
	v_mfma_f32_16x16x32_bf16 v[76:79], v[156:159], v[214:217], v[76:79]
	v_mfma_f32_16x16x32_bf16 v[76:79], v[152:155], v[206:209], v[76:79]
	v_mfma_f32_16x16x32_bf16 v[60:63], v[152:155], v[210:213], v[60:63]
	v_mfma_f32_16x16x32_bf16 v[60:63], v[156:159], v[218:221], v[60:63]
	v_mfma_f32_16x16x32_bf16 v[68:71], v[148:151], v[218:221], v[68:71]
	v_mfma_f32_16x16x32_bf16 v[68:71], v[144:147], v[210:213], v[68:71]
	s_setprio 0
	s_barrier
	s_add_i32 s57, s41, s68
	v_lshl_add_u64 v[222:223], s[24:25], 0, v[170:171]
	s_mov_b32 m0, s57
	ds_read_b128 v[160:163], v196 offset:16384
	ds_read_b128 v[164:167], v196 offset:18432
	ds_read_b128 v[180:183], v197 offset:16384
	ds_read_b128 v[202:205], v197 offset:18432
	ds_read_b128 v[206:209], v196 offset:20480
	ds_read_b128 v[210:213], v196 offset:22528
	ds_read_b128 v[214:217], v197 offset:20480
	ds_read_b128 v[218:221], v197 offset:22528
	global_load_lds_dwordx4 v[222:223], off
	s_add_i32 m0, s57, 0x2000
	s_add_u32 s58, s24, 0x2b0000
	v_lshl_add_u64 v[224:225], s[24:25], 0, v[174:175]
	s_addc_u32 s59, s25, 0
	s_add_i32 s57, s42, s68
	global_load_lds_dwordx4 v[224:225], off
	v_lshl_add_u64 v[226:227], s[58:59], 0, v[170:171]
	s_mov_b32 m0, s57
	v_lshl_add_u64 v[228:229], s[26:27], 0, v[172:173]
	global_load_lds_dwordx4 v[226:227], off
	v_lshl_add_u64 v[226:227], s[58:59], 0, v[174:175]
	s_add_i32 m0, s57, 0x2000
	s_nop 0
	global_load_lds_dwordx4 v[226:227], off
	v_lshl_add_u64 v[226:227], s[26:27], 0, v[168:169]
	s_mov_b32 m0, s34
	s_nop 0
	global_load_lds_dwordx4 v[226:227], off
	s_mov_b32 m0, s35
	s_nop 0
	global_load_lds_dwordx4 v[228:229], off
	s_waitcnt vmcnt(8)
	s_waitcnt lgkmcnt(0)
	s_waitcnt lgkmcnt(0)
	v_mfma_f32_16x16x32_bf16 v[52:55], v[128:131], v[160:163], v[52:55]
	v_mfma_f32_16x16x32_bf16 v[52:55], v[132:135], v[180:183], v[52:55]
	v_mfma_f32_16x16x32_bf16 v[48:51], v[140:143], v[180:183], v[48:51]
	v_mfma_f32_16x16x32_bf16 v[48:51], v[136:139], v[160:163], v[48:51]
	v_mfma_f32_16x16x32_bf16 v[32:35], v[136:139], v[164:167], v[32:35]
	v_mfma_f32_16x16x32_bf16 v[32:35], v[140:143], v[202:205], v[32:35]
	v_mfma_f32_16x16x32_bf16 v[36:39], v[132:135], v[202:205], v[36:39]
	v_mfma_f32_16x16x32_bf16 v[36:39], v[128:131], v[164:167], v[36:39]
	s_barrier
; #define PG8_STAGE(bufoff, gbase, voff) do { _Pragma("unroll") for (int _i = 0; _i < 2; ++_i) \
;         __builtin_amdgcn_global_load_lds((const unsigned*)((const char*)(gbase) + (voff)[_i]), (LAS unsigned*)(lds + (bufoff) + ldsw + _i * 8192), 16, 0, 0); } while (0)
; #define PG8_LDA(dst, b, h) do { _Pragma("unroll") for (int m = 0; m < 4; ++m) _Pragma("unroll") for (int k = 0; k < 2; ++k) dst[m][k] = *(const LAS bf16x8*)(lds + PG8_SA(b, h) + aoffk[k] + m * 2048); } while (0)
; #define PG8_LDB(dst, b, h) do { _Pragma("unroll") for (int n = 0; n < 2; ++n) _Pragma("unroll") for (int k = 0; k < 2; ++k) dst[n][k] = *(const LAS bf16x8*)(lds + PG8_SB(b, h) + boffk[k] + n * 2048); } while (0)
; #define PG8_WAIT_V(n) asm volatile("s_waitcnt vmcnt(" #n ")" ::: "memory")
; #define PG8_WAIT_L(n) asm volatile("s_waitcnt lgkmcnt(" #n ")" ::: "memory")
; #define PG8_BAR __builtin_amdgcn_s_barrier()
; #define PG8_SCHED __builtin_amdgcn_sched_barrier(0)
; template <class Epi, class Sched, class GemmT>
; __device__ __forceinline__ void gemm_phase(LAS unsigned char* lds, const GemmT& g, const Sched& S, const Epi& E, const int wid) {
;     ...
;                 PG8_LDA(At, 0, 1); PG8_STAGE(PG8_SB(0, 0), b2, vB2); PG8_STAGE(PG8_SB(0, 1), b2 + hB2, vB2); PG8_STAGE(PG8_SA(0, 0), a2, vA2);
;                 PG8_WAIT_V(8); PG8_WAIT_L(0); PG8_BAR; PG8_MMA(1, 0, At, B0); PG8_MMA(1, 1, At, B1); PG8_BAR; PG8_SCHED;
;                 PG8_LDB(B0, 1, 0); PG8_LDB(B1, 1, 1); PG8_SCHED; PG8_LDA(At, 1, 0); PG8_STAGE(PG8_SA(0, 1), a2 + hA2, vA2);
;                 PG8_WAIT_V(8); PG8_WAIT_L(0); PG8_BAR; PG8_MMA(0, 0, At, B0); PG8_MMA(0, 1, At, B1); PG8_BAR; PG8_SCHED;
;                 PG8_LDA(At, 1, 1); PG8_STAGE(PG8_SB(1, 0), b3, vB2); PG8_STAGE(PG8_SB(1, 1), b3 + hB2, vB2); PG8_STAGE(PG8_SA(1, 0), a3, vA2);
	s_setprio 3
	v_mfma_f32_16x16x32_bf16 v[20:23], v[128:131], v[206:209], v[20:23]
	v_mfma_f32_16x16x32_bf16 v[20:23], v[132:135], v[214:217], v[20:23]
	v_mfma_f32_16x16x32_bf16 v[8:11], v[140:143], v[214:217], v[8:11]
	v_mfma_f32_16x16x32_bf16 v[8:11], v[136:139], v[206:209], v[8:11]
	v_mfma_f32_16x16x32_bf16 v[0:3], v[136:139], v[210:213], v[0:3]
	v_mfma_f32_16x16x32_bf16 v[0:3], v[140:143], v[218:221], v[0:3]
	v_mfma_f32_16x16x32_bf16 v[4:7], v[132:135], v[218:221], v[4:7]
	v_mfma_f32_16x16x32_bf16 v[4:7], v[128:131], v[210:213], v[4:7]
	s_setprio 0
	s_setprio 3
	v_mfma_f32_16x16x32_bf16 v[64:67], v[144:147], v[160:163], v[64:67]
	v_mfma_f32_16x16x32_bf16 v[64:67], v[148:151], v[180:183], v[64:67]
	v_mfma_f32_16x16x32_bf16 v[56:59], v[156:159], v[180:183], v[56:59]
	v_mfma_f32_16x16x32_bf16 v[56:59], v[152:155], v[160:163], v[56:59]
	v_mfma_f32_16x16x32_bf16 v[40:43], v[152:155], v[164:167], v[40:43]
	v_mfma_f32_16x16x32_bf16 v[40:43], v[156:159], v[202:205], v[40:43]
	v_mfma_f32_16x16x32_bf16 v[44:47], v[148:151], v[202:205], v[44:47]
	v_mfma_f32_16x16x32_bf16 v[44:47], v[144:147], v[164:167], v[44:47]
	v_mfma_f32_16x16x32_bf16 v[28:31], v[144:147], v[206:209], v[28:31]
	v_mfma_f32_16x16x32_bf16 v[28:31], v[148:151], v[214:217], v[28:31]
	v_mfma_f32_16x16x32_bf16 v[24:27], v[156:159], v[214:217], v[24:27]
	v_mfma_f32_16x16x32_bf16 v[24:27], v[152:155], v[206:209], v[24:27]
	v_mfma_f32_16x16x32_bf16 v[12:15], v[152:155], v[210:213], v[12:15]
	v_mfma_f32_16x16x32_bf16 v[12:15], v[156:159], v[218:221], v[12:15]
	v_mfma_f32_16x16x32_bf16 v[16:19], v[148:151], v[218:221], v[16:19]
	v_mfma_f32_16x16x32_bf16 v[16:19], v[144:147], v[210:213], v[16:19]
	s_setprio 0
	s_barrier
	s_add_i32 s57, 0, 0x18000
	s_add_i32 s58, 0, 0x1c000
	v_add_u32_e32 v128, s57, v185
	v_add_u32_e32 v132, s57, v186
	v_add_u32_e32 v144, s58, v185
	v_add_u32_e32 v148, s58, v186
	ds_read_b128 v[128:131], v128
	ds_read_b128 v[132:135], v132
	ds_read_b128 v[136:139], v198
	ds_read_b128 v[140:143], v199
	ds_read_b128 v[144:147], v144
	ds_read_b128 v[148:151], v148
	ds_read_b128 v[152:155], v200
	ds_read_b128 v[156:159], v201
	s_add_u32 s26, s26, 0x2b0000
	s_addc_u32 s27, s27, 0
	s_mov_b32 m0, s36
	v_lshl_add_u64 v[230:231], s[26:27], 0, v[168:169]
	ds_read_b128 v[160:163], v196 offset:32768
	ds_read_b128 v[164:167], v196 offset:34816
	ds_read_b128 v[180:183], v197 offset:32768
	ds_read_b128 v[202:205], v197 offset:34816
	ds_read_b128 v[206:209], v196 offset:36864
	ds_read_b128 v[210:213], v196 offset:38912
	ds_read_b128 v[214:217], v197 offset:36864
	ds_read_b128 v[218:221], v197 offset:38912
	global_load_lds_dwordx4 v[230:231], off
	v_lshl_add_u64 v[230:231], s[26:27], 0, v[172:173]
	s_mov_b32 m0, s37
	s_nop 0
	global_load_lds_dwordx4 v[230:231], off
	s_waitcnt vmcnt(8)
	s_waitcnt lgkmcnt(0)
	s_waitcnt lgkmcnt(0)
	v_mfma_f32_16x16x32_bf16 v[124:127], v[128:131], v[160:163], v[124:127]
	v_mfma_f32_16x16x32_bf16 v[124:127], v[132:135], v[180:183], v[124:127]
	v_mfma_f32_16x16x32_bf16 v[120:123], v[140:143], v[180:183], v[120:123]
	v_mfma_f32_16x16x32_bf16 v[120:123], v[136:139], v[160:163], v[120:123]
	v_mfma_f32_16x16x32_bf16 v[104:107], v[136:139], v[164:167], v[104:107]
	v_mfma_f32_16x16x32_bf16 v[104:107], v[140:143], v[202:205], v[104:107]
	v_mfma_f32_16x16x32_bf16 v[112:115], v[132:135], v[202:205], v[112:115]
	v_mfma_f32_16x16x32_bf16 v[112:115], v[128:131], v[164:167], v[112:115]
	s_barrier
	s_setprio 3
	v_mfma_f32_16x16x32_bf16 v[96:99], v[128:131], v[206:209], v[96:99]
	v_mfma_f32_16x16x32_bf16 v[96:99], v[132:135], v[214:217], v[96:99]
	v_mfma_f32_16x16x32_bf16 v[88:91], v[140:143], v[214:217], v[88:91]
	v_mfma_f32_16x16x32_bf16 v[88:91], v[136:139], v[206:209], v[88:91]
	v_mfma_f32_16x16x32_bf16 v[72:75], v[136:139], v[210:213], v[72:75]
	v_mfma_f32_16x16x32_bf16 v[72:75], v[140:143], v[218:221], v[72:75]
	v_mfma_f32_16x16x32_bf16 v[80:83], v[132:135], v[218:221], v[80:83]
	v_mfma_f32_16x16x32_bf16 v[80:83], v[128:131], v[210:213], v[80:83]
	s_setprio 0
	s_setprio 3
	v_mfma_f32_16x16x32_bf16 v[116:119], v[144:147], v[160:163], v[116:119]
	v_mfma_f32_16x16x32_bf16 v[116:119], v[148:151], v[180:183], v[116:119]
	v_mfma_f32_16x16x32_bf16 v[108:111], v[156:159], v[180:183], v[108:111]
	v_mfma_f32_16x16x32_bf16 v[108:111], v[152:155], v[160:163], v[108:111]
	v_mfma_f32_16x16x32_bf16 v[92:95], v[152:155], v[164:167], v[92:95]
	v_mfma_f32_16x16x32_bf16 v[92:95], v[156:159], v[202:205], v[92:95]
	v_mfma_f32_16x16x32_bf16 v[100:103], v[148:151], v[202:205], v[100:103]
	v_mfma_f32_16x16x32_bf16 v[100:103], v[144:147], v[164:167], v[100:103]
	v_mfma_f32_16x16x32_bf16 v[84:87], v[144:147], v[206:209], v[84:87]
	v_mfma_f32_16x16x32_bf16 v[84:87], v[148:151], v[214:217], v[84:87]
	v_mfma_f32_16x16x32_bf16 v[76:79], v[156:159], v[214:217], v[76:79]
	v_mfma_f32_16x16x32_bf16 v[76:79], v[152:155], v[206:209], v[76:79]
	v_mfma_f32_16x16x32_bf16 v[60:63], v[152:155], v[210:213], v[60:63]
	v_mfma_f32_16x16x32_bf16 v[60:63], v[156:159], v[218:221], v[60:63]
	v_mfma_f32_16x16x32_bf16 v[68:71], v[148:151], v[218:221], v[68:71]
	v_mfma_f32_16x16x32_bf16 v[68:71], v[144:147], v[210:213], v[68:71]
	s_setprio 0
	s_barrier
; #define PG8_STAGE(bufoff, gbase, voff) do { _Pragma("unroll") for (int _i = 0; _i < 2; ++_i) \
;         __builtin_amdgcn_global_load_lds((const unsigned*)((const char*)(gbase) + (voff)[_i]), (LAS unsigned*)(lds + (bufoff) + ldsw + _i * 8192), 16, 0, 0); } while (0)
; #define PG8_LDA(dst, b, h) do { _Pragma("unroll") for (int m = 0; m < 4; ++m) _Pragma("unroll") for (int k = 0; k < 2; ++k) dst[m][k] = *(const LAS bf16x8*)(lds + PG8_SA(b, h) + aoffk[k] + m * 2048); } while (0)
; #define PG8_LDB(dst, b, h) do { _Pragma("unroll") for (int n = 0; n < 2; ++n) _Pragma("unroll") for (int k = 0; k < 2; ++k) dst[n][k] = *(const LAS bf16x8*)(lds + PG8_SB(b, h) + boffk[k] + n * 2048); } while (0)
; #define PG8_WAIT_V(n) asm volatile("s_waitcnt vmcnt(" #n ")" ::: "memory")
; #define PG8_WAIT_L(n) asm volatile("s_waitcnt lgkmcnt(" #n ")" ::: "memory")
; #define PG8_BAR __builtin_amdgcn_s_barrier()
; #define PG8_SCHED __builtin_amdgcn_sched_barrier(0)
; template <class Epi, class Sched, class GemmT>
; __device__ __forceinline__ void gemm_phase(LAS unsigned char* lds, const GemmT& g, const Sched& S, const Epi& E, const int wid) {
;     ...
;                 PG8_LDB(B0, 1, 0); PG8_LDB(B1, 1, 1); PG8_SCHED; PG8_LDA(At, 1, 0); PG8_STAGE(PG8_SA(0, 1), a2 + hA2, vA2);
;                 PG8_WAIT_V(8); PG8_WAIT_L(0); PG8_BAR; PG8_MMA(0, 0, At, B0); PG8_MMA(0, 1, At, B1); PG8_BAR; PG8_SCHED;
;                 PG8_LDA(At, 1, 1); PG8_STAGE(PG8_SB(1, 0), b3, vB2); PG8_STAGE(PG8_SB(1, 1), b3 + hB2, vB2); PG8_STAGE(PG8_SA(1, 0), a3, vA2);
;                 PG8_WAIT_V(8); PG8_WAIT_L(0); PG8_BAR; PG8_MMA(1, 0, At, B0); PG8_MMA(1, 1, At, B1); PG8_BAR; PG8_SCHED;
;             }
	s_add_i32 s26, s57, s68
	v_lshl_add_u64 v[222:223], v[222:223], 0, s[6:7]
	s_mov_b32 m0, s26
	ds_read_b128 v[160:163], v196 offset:49152
	ds_read_b128 v[164:167], v196 offset:51200
	ds_read_b128 v[180:183], v197 offset:49152
	ds_read_b128 v[202:205], v197 offset:51200
	ds_read_b128 v[206:209], v196 offset:53248
	ds_read_b128 v[210:213], v196 offset:55296
	ds_read_b128 v[214:217], v197 offset:53248
	ds_read_b128 v[218:221], v197 offset:55296
	global_load_lds_dwordx4 v[222:223], off
	s_add_i32 m0, s26, 0x2000
	s_add_u32 s24, s24, 0x2b0080
	v_lshl_add_u64 v[222:223], v[224:225], 0, s[6:7]
	s_addc_u32 s25, s25, 0
	s_add_i32 s26, s58, s68
	global_load_lds_dwordx4 v[222:223], off
	v_lshl_add_u64 v[222:223], s[24:25], 0, v[170:171]
	s_mov_b32 m0, s26
	s_nop 0
	global_load_lds_dwordx4 v[222:223], off
	v_lshl_add_u64 v[222:223], s[24:25], 0, v[174:175]
	s_add_i32 m0, s26, 0x2000
	s_nop 0
	global_load_lds_dwordx4 v[222:223], off
	v_lshl_add_u64 v[222:223], v[226:227], 0, s[6:7]
	s_mov_b32 m0, s39
	s_nop 0
	global_load_lds_dwordx4 v[222:223], off
	v_lshl_add_u64 v[222:223], v[228:229], 0, s[6:7]
	s_mov_b32 m0, s40
	s_nop 0
	global_load_lds_dwordx4 v[222:223], off
	s_waitcnt vmcnt(8)
	s_waitcnt lgkmcnt(0)
	s_waitcnt lgkmcnt(0)
	v_mfma_f32_16x16x32_bf16 v[52:55], v[128:131], v[160:163], v[52:55]
	v_mfma_f32_16x16x32_bf16 v[52:55], v[132:135], v[180:183], v[52:55]
	v_mfma_f32_16x16x32_bf16 v[48:51], v[140:143], v[180:183], v[48:51]
	v_mfma_f32_16x16x32_bf16 v[48:51], v[136:139], v[160:163], v[48:51]
	v_mfma_f32_16x16x32_bf16 v[32:35], v[136:139], v[164:167], v[32:35]
	v_mfma_f32_16x16x32_bf16 v[32:35], v[140:143], v[202:205], v[32:35]
	v_mfma_f32_16x16x32_bf16 v[36:39], v[132:135], v[202:205], v[36:39]
	v_mfma_f32_16x16x32_bf16 v[36:39], v[128:131], v[164:167], v[36:39]
	s_barrier
	s_setprio 3
	v_mfma_f32_16x16x32_bf16 v[20:23], v[128:131], v[206:209], v[20:23]
	v_mfma_f32_16x16x32_bf16 v[20:23], v[132:135], v[214:217], v[20:23]
	v_mfma_f32_16x16x32_bf16 v[8:11], v[140:143], v[214:217], v[8:11]
	v_mfma_f32_16x16x32_bf16 v[8:11], v[136:139], v[206:209], v[8:11]
	v_mfma_f32_16x16x32_bf16 v[0:3], v[136:139], v[210:213], v[0:3]
	v_mfma_f32_16x16x32_bf16 v[0:3], v[140:143], v[218:221], v[0:3]
	v_mfma_f32_16x16x32_bf16 v[4:7], v[132:135], v[218:221], v[4:7]
	v_mfma_f32_16x16x32_bf16 v[4:7], v[128:131], v[210:213], v[4:7]
	s_setprio 0
	s_setprio 3
	v_mfma_f32_16x16x32_bf16 v[64:67], v[144:147], v[160:163], v[64:67]
	v_mfma_f32_16x16x32_bf16 v[64:67], v[148:151], v[180:183], v[64:67]
	v_mfma_f32_16x16x32_bf16 v[56:59], v[156:159], v[180:183], v[56:59]
	v_mfma_f32_16x16x32_bf16 v[56:59], v[152:155], v[160:163], v[56:59]
	v_mfma_f32_16x16x32_bf16 v[40:43], v[152:155], v[164:167], v[40:43]
	v_mfma_f32_16x16x32_bf16 v[40:43], v[156:159], v[202:205], v[40:43]
	v_mfma_f32_16x16x32_bf16 v[44:47], v[148:151], v[202:205], v[44:47]
	v_mfma_f32_16x16x32_bf16 v[44:47], v[144:147], v[164:167], v[44:47]
	v_mfma_f32_16x16x32_bf16 v[28:31], v[144:147], v[206:209], v[28:31]
	v_mfma_f32_16x16x32_bf16 v[28:31], v[148:151], v[214:217], v[28:31]
	v_mfma_f32_16x16x32_bf16 v[24:27], v[156:159], v[214:217], v[24:27]
	v_mfma_f32_16x16x32_bf16 v[24:27], v[152:155], v[206:209], v[24:27]
	v_mfma_f32_16x16x32_bf16 v[12:15], v[152:155], v[210:213], v[12:15]
	v_mfma_f32_16x16x32_bf16 v[12:15], v[156:159], v[218:221], v[12:15]
	v_mfma_f32_16x16x32_bf16 v[16:19], v[148:151], v[218:221], v[16:19]
	v_mfma_f32_16x16x32_bf16 v[16:19], v[144:147], v[210:213], v[16:19]
	s_setprio 0
	s_barrier
	s_add_i32 s56, s56, 2
	s_add_u32 s22, s22, 0x100
	s_addc_u32 s23, s23, 0
	s_add_u32 s54, s54, 0x100
	s_addc_u32 s55, s55, 0
	s_cmpk_gt_u32 s56, 0xa9
	s_cbranch_scc0 .LBB0_1096
	s_and_b64 vcc, exec, s[8:9]
	s_cbranch_vccz .LBB0_1099
	s_barrier
